# nt cache policy also on the once-read f32 weight loads of the conversion tiles and the norm's residual loads
# speedup vs baseline: 1.0256x; 1.0152x over previous
.LBB0_28:
	v_mov_b32_e32 v0, v198
	s_ashr_i32 s10, s1, 11
	v_and_b32_e32 v21, 63, v0
	v_bfe_u32 v0, v0, 6, 2
	v_add_u32_e32 v10, s16, v0
	v_ashrrev_i32_e32 v11, 31, v10
	v_lshlrev_b64 v[0:1], 12, v[10:11]
	s_waitcnt lgkmcnt(0)
	v_lshl_add_u64 v[0:1], s[2:3], 0, v[0:1]
	v_lshlrev_b32_e32 v8, 4, v21
	v_lshl_add_u64 v[32:33], v[0:1], 0, v[8:9]
	global_load_dwordx4 v[24:27], v[32:33], off nt
	global_load_dwordx4 v[28:31], v[32:33], off offset:1024 nt
	global_load_dwordx4 v[4:7], v[32:33], off offset:2048 nt
	global_load_dwordx4 v[0:3], v[32:33], off offset:3072 nt
	s_mulk_i32 s10, 0xc00
	s_ashr_i32 s11, s10, 31
	s_lshl_b64 s[10:11], s[10:11], 2
	s_add_u32 s10, s14, s10
	s_addc_u32 s11, s15, s11
	s_add_u32 s12, s10, 0x1000
	s_addc_u32 s13, s11, 0
	global_load_dwordx4 v[32:35], v8, s[12:13]
	global_load_dwordx4 v[36:39], v8, s[4:5]
	global_load_dwordx4 v[40:43], v8, s[10:11]
	v_or_b32_e32 v100, 0x400, v8
	v_or_b32_e32 v101, 0x800, v8
	v_or_b32_e32 v102, 0xc00, v8
	global_load_dwordx4 v[64:67], v8, s[4:5] offset:1024
	global_load_dwordx4 v[68:71], v100, s[12:13]
	global_load_dwordx4 v[72:75], v8, s[10:11] offset:1024
	global_load_dwordx4 v[76:79], v8, s[4:5] offset:2048
	global_load_dwordx4 v[80:83], v101, s[12:13]
	global_load_dwordx4 v[84:87], v8, s[10:11] offset:2048
	global_load_dwordx4 v[88:91], v8, s[4:5] offset:3072
	global_load_dwordx4 v[92:95], v102, s[12:13]
	global_load_dwordx4 v[96:99], v8, s[10:11] offset:3072
	v_cmp_lt_i32_e32 vcc, v14, v13
	s_waitcnt vmcnt(15)
	v_mov_b32_e32 v46, v25
	v_cndmask_b32_e32 v44, v12, v14, vcc
	s_waitcnt vmcnt(14)
	v_mov_b32_e32 v47, v29
	v_lshlrev_b32_e32 v60, 2, v44
	v_mov_b32_e32 v44, v24
	v_mov_b32_e32 v45, v28
	s_waitcnt vmcnt(13)
	v_mov_b32_e32 v54, v5
	s_waitcnt vmcnt(12)
	v_mov_b32_e32 v55, v1
	v_pk_mul_f32 v[46:47], v[46:47], v[46:47]
	v_mov_b32_e32 v48, v26
	v_mov_b32_e32 v49, v30
	v_mov_b32_e32 v52, v4
	v_mov_b32_e32 v53, v0
	v_pk_mul_f32 v[54:55], v[54:55], v[54:55]
	v_pk_fma_f32 v[44:45], v[44:45], v[44:45], v[46:47]
	v_mov_b32_e32 v50, v27
	v_mov_b32_e32 v51, v31
	v_mov_b32_e32 v56, v6
	v_mov_b32_e32 v57, v2
	v_pk_fma_f32 v[46:47], v[52:53], v[52:53], v[54:55]
	v_pk_fma_f32 v[44:45], v[48:49], v[48:49], v[44:45]
	v_mov_b32_e32 v58, v7
	v_mov_b32_e32 v59, v3
	v_pk_fma_f32 v[46:47], v[56:57], v[56:57], v[46:47]
	v_pk_fma_f32 v[44:45], v[50:51], v[50:51], v[44:45]
	v_pk_fma_f32 v[46:47], v[58:59], v[58:59], v[46:47]
	v_add_f32_e32 v44, v44, v45
	v_add_f32_e32 v44, v44, v46
	v_add_f32_e32 v44, v44, v47
	ds_bpermute_b32 v45, v60, v44
	v_cmp_lt_i32_e32 vcc, v15, v13
	s_waitcnt vmcnt(11)
	v_pk_add_f32 v[32:33], v[32:33], 1.0 op_sel_hi:[1,0]
	v_pk_add_f32 v[34:35], v[34:35], 1.0 op_sel_hi:[1,0]
	v_cndmask_b32_e32 v46, v12, v15, vcc
	v_lshlrev_b32_e32 v46, 2, v46
	s_waitcnt lgkmcnt(0)
	v_add_f32_e32 v44, v44, v45
	ds_bpermute_b32 v45, v46, v44
	v_cmp_lt_i32_e32 vcc, v16, v13
	v_or_b32_e32 v50, 0x400, v8
	s_waitcnt lgkmcnt(0)
	v_add_f32_e32 v44, v44, v45
	v_cndmask_b32_e32 v46, v12, v16, vcc
	v_lshlrev_b32_e32 v46, 2, v46
	ds_bpermute_b32 v45, v46, v44
	v_cmp_lt_i32_e32 vcc, v17, v13
	s_waitcnt lgkmcnt(0)
	v_add_f32_e32 v44, v44, v45
	v_cndmask_b32_e32 v46, v12, v17, vcc
	v_lshlrev_b32_e32 v46, 2, v46
	ds_bpermute_b32 v45, v46, v44
	v_cmp_lt_i32_e32 vcc, v18, v13
	s_waitcnt lgkmcnt(0)
	v_add_f32_e32 v44, v44, v45
	v_cndmask_b32_e32 v46, v12, v18, vcc
	v_lshlrev_b32_e32 v46, 2, v46
	ds_bpermute_b32 v46, v46, v44
	v_cmp_lt_i32_e32 vcc, v19, v13
	v_mov_b32_e32 v45, v9
	s_waitcnt lgkmcnt(0)
	v_add_f32_e32 v48, v44, v46
	v_cndmask_b32_e32 v47, v12, v19, vcc
	v_lshlrev_b32_e32 v47, 2, v47
	ds_bpermute_b32 v49, v47, v48
	v_lshlrev_b64 v[46:47], 11, v[10:11]
	v_lshlrev_b32_e32 v44, 3, v21
	v_lshl_add_u64 v[46:47], s[6:7], 0, v[46:47]
	v_lshl_add_u64 v[44:45], v[46:47], 0, v[44:45]
	s_waitcnt lgkmcnt(0)
	v_add_f32_e32 v11, v48, v49
	v_fmamk_f32 v11, v11, 0x3a800000, v20
	v_mul_f32_e32 v48, 0x4b800000, v11
	v_cmp_gt_f32_e32 vcc, s18, v11
	s_nop 1
	v_cndmask_b32_e32 v11, v11, v48, vcc
	v_rsq_f32_e32 v11, v11
	s_nop 0
	v_mul_f32_e32 v46, 0x45800000, v11
	v_cndmask_b32_e32 v46, v11, v46, vcc
	v_pk_mul_f32 v[24:25], v[24:25], v[46:47] op_sel_hi:[1,0]
	v_pk_mul_f32 v[26:27], v[26:27], v[46:47] op_sel_hi:[1,0]
	s_waitcnt vmcnt(10)
	v_pk_mul_f32 v[24:25], v[36:37], v[24:25]
	v_pk_mul_f32 v[26:27], v[38:39], v[26:27]
	s_waitcnt vmcnt(9)
	v_pk_fma_f32 v[24:25], v[32:33], v[24:25], v[40:41]
	v_pk_fma_f32 v[26:27], v[34:35], v[26:27], v[42:43]
	v_cvt_pk_bf16_f32 v24, v24, v25
	v_cvt_pk_bf16_f32 v25, v26, v27
	global_store_dwordx2 v[44:45], v[24:25], off
	v_pk_mul_f32 v[28:29], v[28:29], v[46:47] op_sel_hi:[1, 0]
	v_pk_mul_f32 v[30:31], v[30:31], v[46:47] op_sel_hi:[1, 0]
	v_or_b32_e32 v11, 0x800, v8
	v_pk_mul_f32 v[4:5], v[4:5], v[46:47] op_sel_hi:[1, 0]
	v_pk_mul_f32 v[6:7], v[6:7], v[46:47] op_sel_hi:[1, 0]
	v_pk_mul_f32 v[0:1], v[0:1], v[46:47] op_sel_hi:[1, 0]
	v_pk_mul_f32 v[2:3], v[2:3], v[46:47] op_sel_hi:[1, 0]
	v_cmp_eq_u32_e32 vcc, 0, v21
	s_waitcnt vmcnt(9)
	v_pk_mul_f32 v[24:25], v[64:65], v[28:29]
	s_waitcnt vmcnt(8)
	v_pk_add_f32 v[28:29], v[68:69], 1.0 op_sel_hi:[1, 0]
	v_pk_mul_f32 v[26:27], v[66:67], v[30:31]
	v_pk_add_f32 v[30:31], v[70:71], 1.0 op_sel_hi:[1, 0]
	s_waitcnt vmcnt(7)
	v_pk_fma_f32 v[24:25], v[28:29], v[24:25], v[72:73]
	v_pk_fma_f32 v[26:27], v[30:31], v[26:27], v[74:75]
	v_cvt_pk_bf16_f32 v24, v24, v25
	v_cvt_pk_bf16_f32 v25, v26, v27
	global_store_dwordx2 v[44:45], v[24:25], off offset:512
	v_or_b32_e32 v11, 0xc00, v8
	s_waitcnt vmcnt(7)
	v_pk_mul_f32 v[4:5], v[4:5], v[76:77]
	s_waitcnt vmcnt(6)
	v_pk_add_f32 v[24:25], v[80:81], 1.0 op_sel_hi:[1, 0]
	v_pk_mul_f32 v[6:7], v[6:7], v[78:79]
	v_pk_add_f32 v[26:27], v[82:83], 1.0 op_sel_hi:[1, 0]
	s_waitcnt vmcnt(5)
	v_pk_fma_f32 v[4:5], v[4:5], v[24:25], v[84:85]
	v_pk_fma_f32 v[6:7], v[6:7], v[26:27], v[86:87]
	v_cvt_pk_bf16_f32 v4, v4, v5
	v_cvt_pk_bf16_f32 v5, v6, v7
	global_store_dwordx2 v[44:45], v[4:5], off offset:1024
	s_waitcnt vmcnt(5)
	v_pk_mul_f32 v[0:1], v[0:1], v[88:89]
	s_waitcnt vmcnt(4)
	v_pk_add_f32 v[4:5], v[92:93], 1.0 op_sel_hi:[1, 0]
	v_pk_mul_f32 v[2:3], v[2:3], v[90:91]
	v_pk_add_f32 v[6:7], v[94:95], 1.0 op_sel_hi:[1, 0]
	s_waitcnt vmcnt(3)
	v_pk_fma_f32 v[0:1], v[0:1], v[4:5], v[96:97]
	v_pk_fma_f32 v[2:3], v[2:3], v[6:7], v[98:99]
	v_cvt_pk_bf16_f32 v0, v0, v1
	v_cvt_pk_bf16_f32 v1, v2, v3
	global_store_dwordx2 v[44:45], v[0:1], off offset:1536
	s_and_saveexec_b64 s[10:11], vcc
	s_cbranch_execz .LBB0_27
	v_lshlrev_b32_e32 v0, 1, v10
	v_ashrrev_i32_e32 v1, 31, v0
	v_lshl_add_u64 v[0:1], v[0:1], 2, s[8:9]
	global_store_dwordx2 v[0:1], v[22:23], off
	s_branch .LBB0_27

.LBB0_39:
	s_lshl_b32 s59, s31, 3
	s_lshl_b32 s35, s30, 3
	v_mov_b32_e32 v65, v25
	v_or_b32_e32 v64, s59, v6
	s_add_i32 s64, s59, 16
	v_or_b32_e32 v66, s35, v5
	s_add_i32 s61, s35, 16
	s_add_i32 s66, s59, 32
	v_mov_b32_e32 v69, v1
	v_add_lshl_u32 v68, v64, s2, 10
	v_mov_b32_e32 v71, v27
	v_or_b32_e32 v70, s64, v6
	v_mov_b32_e32 v72, v8
	v_mov_b32_e32 v73, v69
	s_add_i32 s65, s35, 32
	s_add_i32 s35, s35, 48
	s_add_i32 s59, s59, 48
	v_mov_b32_e32 v75, v73
	v_add_lshl_u32 v74, v66, s3, 10
	v_mov_b32_e32 v72, v64
	v_or_b32_e32 v73, s61, v5
	v_or_b32_e32 v64, s66, v6
	v_lshl_add_u64 v[76:77], v[68:69], 2, v[2:3]
	v_mov_b32_e32 v79, v69
	v_add_lshl_u32 v78, v70, s2, 10
	v_mov_b32_e32 v68, v10
	v_mov_b32_e32 v69, v79
	v_mov_b32_e32 v80, v70
	v_or_b32_e32 v81, s65, v5
	v_or_b32_e32 v65, s35, v5
	v_or_b32_e32 v67, s59, v6
	v_lshl_add_u64 v[70:71], v[74:75], 2, v[2:3]
	v_mov_b32_e32 v75, v69
	v_add_lshl_u32 v74, v73, s3, 10
	v_lshl_add_u64 v[68:69], v[78:79], 2, v[2:3]
	v_mov_b32_e32 v83, v79
	v_add_lshl_u32 v82, v64, s2, 10
	v_mov_b32_e32 v78, v12
	v_mov_b32_e32 v79, v83
	v_mov_b32_e32 v84, v18
	v_mov_b32_e32 v85, v83
	v_mov_b32_e32 v87, v79
	v_add_lshl_u32 v86, v81, s3, 10
	v_mov_b32_e32 v79, v85
	v_add_lshl_u32 v78, v65, s3, 10
	v_lshl_add_u64 v[84:85], v[74:75], 2, v[2:3]
	global_load_dword v74, v[76:77], off nt
	global_load_dword v75, v[70:71], off nt
	global_load_dword v88, v[68:69], off nt
	global_load_dword v89, v[84:85], off nt
	v_lshl_add_u64 v[90:91], v[82:83], 2, v[2:3]
	v_mov_b32_e32 v71, v83
	v_add_lshl_u32 v70, v67, s2, 10
	v_lshl_add_u64 v[82:83], v[86:87], 2, v[2:3]
	v_lshl_add_u64 v[86:87], v[78:79], 2, v[2:3]
	v_lshl_add_u64 v[78:79], v[70:71], 2, v[2:3]
	v_mov_b32_e32 v85, v71
	global_load_dword v84, v[90:91], off nt
	global_load_dword v70, v[82:83], off nt
	global_load_dword v71, v[78:79], off nt
	global_load_dword v92, v[86:87], off nt
	s_add_i32 s31, s31, 8
	s_add_i32 s30, s30, 8
	s_add_i32 s34, s34, -8
	v_mad_u64_u32 v[94:95], s[64:65], v72, s41, v[4:5]
	s_cmp_lg_u32 s34, 0
	v_mad_u64_u32 v[90:91], s[64:65], v66, s41, v[4:5]
	v_mad_u64_u32 v[78:79], s[64:65], v80, s41, v[4:5]
	v_mad_u64_u32 v[82:83], s[64:65], v73, s41, v[4:5]
	v_mad_u64_u32 v[86:87], s[64:65], v64, s41, v[4:5]
	v_mad_u64_u32 v[76:77], s[64:65], v81, s41, v[4:5]
	v_mad_u64_u32 v[68:69], s[64:65], v67, s41, v[4:5]
	v_mad_u64_u32 v[72:73], s[64:65], v65, s41, v[4:5]
	s_lshl_b32 s59, s31, 3
	s_lshl_b32 s35, s30, 3
	v_mov_b32_e32 v81, v69
	v_or_b32_e32 v80, s59, v6
	s_add_i32 s64, s59, 16
	v_or_b32_e32 v69, s35, v5
	s_add_i32 s61, s35, 16
	s_add_i32 s66, s59, 32
	v_mov_b32_e32 v97, v85
	v_add_lshl_u32 v96, v80, s2, 10
	v_mov_b32_e32 v99, v73
	v_or_b32_e32 v98, s64, v6
	v_mov_b32_e32 v100, v94
	v_mov_b32_e32 v101, v97
	s_add_i32 s65, s35, 32
	s_add_i32 s35, s35, 48
	s_add_i32 s59, s59, 48
	v_mov_b32_e32 v103, v101
	v_add_lshl_u32 v102, v69, s3, 10
	v_mov_b32_e32 v100, v80
	v_or_b32_e32 v101, s61, v5
	v_or_b32_e32 v66, s66, v6
	v_lshl_add_u64 v[80:81], v[96:97], 2, v[2:3]
	v_mov_b32_e32 v105, v97
	v_add_lshl_u32 v104, v98, s2, 10
	v_mov_b32_e32 v96, v90
	v_mov_b32_e32 v97, v105
	v_mov_b32_e32 v106, v98
	v_or_b32_e32 v107, s65, v5
	v_or_b32_e32 v64, s35, v5
	v_or_b32_e32 v65, s59, v6
	v_lshl_add_u64 v[98:99], v[102:103], 2, v[2:3]
	v_mov_b32_e32 v103, v97
	v_add_lshl_u32 v102, v101, s3, 10
	v_lshl_add_u64 v[96:97], v[104:105], 2, v[2:3]
	v_mov_b32_e32 v109, v105
	v_add_lshl_u32 v108, v66, s2, 10
	v_mov_b32_e32 v104, v78
	v_mov_b32_e32 v105, v109
	v_mov_b32_e32 v110, v82
	v_mov_b32_e32 v111, v109
	v_mov_b32_e32 v113, v105
	v_add_lshl_u32 v112, v107, s3, 10
	v_mov_b32_e32 v105, v111
	v_add_lshl_u32 v104, v64, s3, 10
	v_lshl_add_u64 v[110:111], v[102:103], 2, v[2:3]
	global_load_dword v67, v[80:81], off nt
	global_load_dword v73, v[98:99], off nt
	global_load_dword v77, v[96:97], off nt
	global_load_dword v79, v[110:111], off nt
	v_lshl_add_u64 v[102:103], v[108:109], 2, v[2:3]
	v_mov_b32_e32 v99, v109
	v_add_lshl_u32 v98, v65, s2, 10
	v_lshl_add_u64 v[108:109], v[112:113], 2, v[2:3]
	v_lshl_add_u64 v[112:113], v[104:105], 2, v[2:3]
	v_lshl_add_u64 v[104:105], v[98:99], 2, v[2:3]
	v_mov_b32_e32 v111, v99
	global_load_dword v110, v[102:103], off nt
	global_load_dword v83, v[108:109], off nt
	global_load_dword v85, v[104:105], off nt
	global_load_dword v87, v[112:113], off nt
	s_add_i32 s31, s31, 8
	s_add_i32 s30, s30, 8
	s_add_i32 s34, s34, -8
	v_mad_u64_u32 v[98:99], s[64:65], v100, s41, v[4:5]
	s_cmp_lg_u32 s34, 0
	v_mad_u64_u32 v[102:103], s[64:65], v69, s41, v[4:5]
	v_mad_u64_u32 v[104:105], s[64:65], v106, s41, v[4:5]
	v_mad_u64_u32 v[108:109], s[64:65], v101, s41, v[4:5]
	v_mad_u64_u32 v[112:113], s[64:65], v66, s41, v[4:5]
	v_mad_u64_u32 v[80:81], s[64:65], v107, s41, v[4:5]
	v_mad_u64_u32 v[96:97], s[64:65], v65, s41, v[4:5]
	v_mad_u64_u32 v[100:101], s[64:65], v64, s41, v[4:5]
	s_waitcnt vmcnt(15)
	ds_write_b32 v94, v74
	s_waitcnt vmcnt(14)
	ds_write_b32 v90, v75
	s_waitcnt vmcnt(13)
	ds_write_b32 v78, v88
	s_waitcnt vmcnt(12)
	ds_write_b32 v82, v89
	s_waitcnt vmcnt(11)
	ds_write_b32 v86, v84
	s_waitcnt vmcnt(10)
	ds_write_b32 v76, v70
	s_waitcnt vmcnt(9)
	ds_write_b32 v68, v71
	s_waitcnt vmcnt(8)
	ds_write_b32 v72, v92
	s_waitcnt vmcnt(7)
	ds_write_b32 v98, v67
	s_waitcnt vmcnt(6)
	ds_write_b32 v102, v73
	s_waitcnt vmcnt(5)
	ds_write_b32 v104, v77
	s_waitcnt vmcnt(4)
	ds_write_b32 v108, v79
	s_waitcnt vmcnt(3)
	ds_write_b32 v112, v110
	s_waitcnt vmcnt(2)
	ds_write_b32 v80, v83
	s_waitcnt vmcnt(1)
	ds_write_b32 v96, v85
	s_waitcnt vmcnt(0)
	ds_write_b32 v100, v87
	v_mov_b32_e32 v0, v110
	v_mov_b32_e32 v1, v111
	v_mov_b32_e32 v8, v98
	v_mov_b32_e32 v9, v99
	v_mov_b32_e32 v10, v102
	v_mov_b32_e32 v11, v103
	v_mov_b32_e32 v12, v104
	v_mov_b32_e32 v13, v105
	v_mov_b32_e32 v17, v69
	v_mov_b32_e32 v18, v108
	v_mov_b32_e32 v19, v109
	v_mov_b32_e32 v20, v112
	v_mov_b32_e32 v21, v113
	v_mov_b32_e32 v22, v80
	v_mov_b32_e32 v23, v81
	v_mov_b32_e32 v24, v96
	v_mov_b32_e32 v25, v97
	v_mov_b32_e32 v26, v100
	v_mov_b32_e32 v27, v101
	v_mov_b32_e32 v28, v66
	v_mov_b32_e32 v29, v64
	v_mov_b32_e32 v30, v65
	v_mov_b32_e32 v31, v67
	v_mov_b32_e32 v32, v73
	v_mov_b32_e32 v33, v77
	v_mov_b32_e32 v34, v79
	v_mov_b32_e32 v35, v83
	v_mov_b32_e32 v36, v85
	v_mov_b32_e32 v37, v87
	v_lshlrev_b32_sdwa v0, v14, v7 dst_sel:DWORD dst_unused:UNUSED_PAD src0_sel:DWORD src1_sel:BYTE_0
	v_and_b32_e32 v0, 0x7e, v0
	v_lshrrev_b32_sdwa v8, v15, v7 dst_sel:DWORD dst_unused:UNUSED_PAD src0_sel:DWORD src1_sel:BYTE_0
	v_or_b32_e32 v6, s2, v0
	v_mul_u32_u24_e32 v0, 0x84, v0
	v_lshlrev_b32_e32 v2, 2, v8
	v_add3_u32 v12, s36, v0, v2
	s_waitcnt lgkmcnt(0)
	s_barrier
	ds_read2_b32 v[2:3], v12 offset0:33 offset1:37
	ds_read2_b32 v[4:5], v12 offset1:4
	v_lshlrev_b32_e32 v0, 1, v6
	v_lshl_add_u64 v[6:7], s[4:5], 0, v[0:1]
	v_or_b32_e32 v0, s20, v8
	v_lshlrev_b64 v[10:11], 11, v[0:1]
	s_waitcnt lgkmcnt(0)
	v_cvt_pk_bf16_f32 v2, v4, v2
	v_lshl_add_u64 v[10:11], v[6:7], 0, v[10:11]
	ds_read2_b32 v[8:9], v12 offset0:8 offset1:12
	global_store_dword v[10:11], v2, off
	v_or_b32_e32 v10, 4, v0
	v_mov_b32_e32 v11, v1
	v_cvt_pk_bf16_f32 v13, v5, v3
	ds_read2_b32 v[4:5], v12 offset0:41 offset1:45
	v_lshlrev_b64 v[2:3], 11, v[10:11]
	v_lshl_add_u64 v[2:3], v[6:7], 0, v[2:3]
	global_store_dword v[2:3], v13, off
	v_or_b32_e32 v2, 8, v0
	v_mov_b32_e32 v3, v1
	v_lshlrev_b64 v[2:3], 11, v[2:3]
	s_waitcnt lgkmcnt(0)
	v_cvt_pk_bf16_f32 v4, v8, v4
	v_lshl_add_u64 v[2:3], v[6:7], 0, v[2:3]
	global_store_dword v[2:3], v4, off
	v_or_b32_e32 v2, 12, v0
	v_mov_b32_e32 v3, v1
	v_cvt_pk_bf16_f32 v10, v9, v5
	ds_read2_b32 v[4:5], v12 offset0:16 offset1:20
	ds_read2_b32 v[8:9], v12 offset0:49 offset1:53
	v_lshlrev_b64 v[2:3], 11, v[2:3]
	v_lshl_add_u64 v[2:3], v[6:7], 0, v[2:3]
	global_store_dword v[2:3], v10, off
	v_or_b32_e32 v2, 16, v0
	v_mov_b32_e32 v3, v1
	v_lshlrev_b64 v[2:3], 11, v[2:3]
	s_waitcnt lgkmcnt(0)
	v_cvt_pk_bf16_f32 v4, v4, v8
	v_lshl_add_u64 v[2:3], v[6:7], 0, v[2:3]
	global_store_dword v[2:3], v4, off
	v_or_b32_e32 v2, 20, v0
	v_mov_b32_e32 v3, v1
	v_cvt_pk_bf16_f32 v10, v5, v9
	ds_read2_b32 v[4:5], v12 offset0:57 offset1:61
	ds_read2_b32 v[8:9], v12 offset0:24 offset1:28
	v_lshlrev_b64 v[2:3], 11, v[2:3]
	v_lshl_add_u64 v[2:3], v[6:7], 0, v[2:3]
	global_store_dword v[2:3], v10, off
	v_or_b32_e32 v2, 24, v0
	v_mov_b32_e32 v3, v1
	v_lshlrev_b64 v[2:3], 11, v[2:3]
	s_waitcnt lgkmcnt(0)
	v_cvt_pk_bf16_f32 v4, v8, v4
	v_lshl_add_u64 v[2:3], v[6:7], 0, v[2:3]
	v_or_b32_e32 v0, 28, v0
	global_store_dword v[2:3], v4, off
	v_lshlrev_b64 v[2:3], 11, v[0:1]
	v_cvt_pk_bf16_f32 v4, v9, v5
	v_lshl_add_u64 v[2:3], v[6:7], 0, v[2:3]
	global_store_dword v[2:3], v4, off
	s_barrier
	s_mov_b64 s[2:3], 0

.LBB0_43:
	s_lshl_b32 s61, s31, 3
	s_lshl_b32 s59, s30, 3
	v_mov_b32_e32 v65, v25
	v_or_b32_e32 v64, s61, v6
	s_add_i32 s65, s61, 16
	v_or_b32_e32 v66, s59, v5
	s_add_i32 s64, s59, 16
	s_add_i32 s67, s61, 32
	v_mov_b32_e32 v69, v1
	v_add_lshl_u32 v68, v64, s3, 10
	v_mov_b32_e32 v71, v27
	v_or_b32_e32 v70, s65, v6
	v_mov_b32_e32 v72, v8
	v_mov_b32_e32 v73, v69
	s_add_i32 s66, s59, 32
	s_add_i32 s59, s59, 48
	s_add_i32 s61, s61, 48
	v_mov_b32_e32 v75, v73
	v_add_lshl_u32 v74, v66, s34, 10
	v_mov_b32_e32 v72, v64
	v_or_b32_e32 v73, s64, v5
	v_or_b32_e32 v64, s67, v6
	v_lshl_add_u64 v[76:77], v[68:69], 2, v[2:3]
	v_mov_b32_e32 v79, v69
	v_add_lshl_u32 v78, v70, s3, 10
	v_mov_b32_e32 v68, v10
	v_mov_b32_e32 v69, v79
	v_mov_b32_e32 v80, v70
	v_or_b32_e32 v81, s66, v5
	v_or_b32_e32 v65, s59, v5
	v_or_b32_e32 v67, s61, v6
	v_lshl_add_u64 v[70:71], v[74:75], 2, v[2:3]
	v_mov_b32_e32 v75, v69
	v_add_lshl_u32 v74, v73, s34, 10
	v_lshl_add_u64 v[68:69], v[78:79], 2, v[2:3]
	v_mov_b32_e32 v83, v79
	v_add_lshl_u32 v82, v64, s3, 10
	v_mov_b32_e32 v78, v12
	v_mov_b32_e32 v79, v83
	v_mov_b32_e32 v84, v18
	v_mov_b32_e32 v85, v83
	v_mov_b32_e32 v87, v79
	v_add_lshl_u32 v86, v81, s34, 10
	v_mov_b32_e32 v79, v85
	v_add_lshl_u32 v78, v65, s34, 10
	v_lshl_add_u64 v[84:85], v[74:75], 2, v[2:3]
	global_load_dword v74, v[76:77], off nt
	global_load_dword v75, v[70:71], off nt
	global_load_dword v88, v[68:69], off nt
	global_load_dword v89, v[84:85], off nt
	v_lshl_add_u64 v[90:91], v[82:83], 2, v[2:3]
	v_mov_b32_e32 v71, v83
	v_add_lshl_u32 v70, v67, s3, 10
	v_lshl_add_u64 v[82:83], v[86:87], 2, v[2:3]
	v_lshl_add_u64 v[86:87], v[78:79], 2, v[2:3]
	v_lshl_add_u64 v[78:79], v[70:71], 2, v[2:3]
	v_mov_b32_e32 v85, v71
	global_load_dword v84, v[90:91], off nt
	global_load_dword v70, v[82:83], off nt
	global_load_dword v71, v[78:79], off nt
	global_load_dword v92, v[86:87], off nt
	s_add_i32 s31, s31, 8
	s_add_i32 s30, s30, 8
	s_add_i32 s35, s35, -8
	v_mad_u64_u32 v[94:95], s[64:65], v72, s41, v[4:5]
	s_cmp_lg_u32 s35, 0
	v_mad_u64_u32 v[90:91], s[64:65], v66, s41, v[4:5]
	v_mad_u64_u32 v[78:79], s[64:65], v80, s41, v[4:5]
	v_mad_u64_u32 v[82:83], s[64:65], v73, s41, v[4:5]
	v_mad_u64_u32 v[86:87], s[64:65], v64, s41, v[4:5]
	v_mad_u64_u32 v[76:77], s[64:65], v81, s41, v[4:5]
	v_mad_u64_u32 v[68:69], s[64:65], v67, s41, v[4:5]
	v_mad_u64_u32 v[72:73], s[64:65], v65, s41, v[4:5]
	s_lshl_b32 s61, s31, 3
	s_lshl_b32 s59, s30, 3
	v_mov_b32_e32 v81, v69
	v_or_b32_e32 v80, s61, v6
	s_add_i32 s65, s61, 16
	v_or_b32_e32 v69, s59, v5
	s_add_i32 s64, s59, 16
	s_add_i32 s67, s61, 32
	v_mov_b32_e32 v97, v85
	v_add_lshl_u32 v96, v80, s3, 10
	v_mov_b32_e32 v99, v73
	v_or_b32_e32 v98, s65, v6
	v_mov_b32_e32 v100, v94
	v_mov_b32_e32 v101, v97
	s_add_i32 s66, s59, 32
	s_add_i32 s59, s59, 48
	s_add_i32 s61, s61, 48
	v_mov_b32_e32 v103, v101
	v_add_lshl_u32 v102, v69, s34, 10
	v_mov_b32_e32 v100, v80
	v_or_b32_e32 v101, s64, v5
	v_or_b32_e32 v66, s67, v6
	v_lshl_add_u64 v[80:81], v[96:97], 2, v[2:3]
	v_mov_b32_e32 v105, v97
	v_add_lshl_u32 v104, v98, s3, 10
	v_mov_b32_e32 v96, v90
	v_mov_b32_e32 v97, v105
	v_mov_b32_e32 v106, v98
	v_or_b32_e32 v107, s66, v5
	v_or_b32_e32 v64, s59, v5
	v_or_b32_e32 v65, s61, v6
	v_lshl_add_u64 v[98:99], v[102:103], 2, v[2:3]
	v_mov_b32_e32 v103, v97
	v_add_lshl_u32 v102, v101, s34, 10
	v_lshl_add_u64 v[96:97], v[104:105], 2, v[2:3]
	v_mov_b32_e32 v109, v105
	v_add_lshl_u32 v108, v66, s3, 10
	v_mov_b32_e32 v104, v78
	v_mov_b32_e32 v105, v109
	v_mov_b32_e32 v110, v82
	v_mov_b32_e32 v111, v109
	v_mov_b32_e32 v113, v105
	v_add_lshl_u32 v112, v107, s34, 10
	v_mov_b32_e32 v105, v111
	v_add_lshl_u32 v104, v64, s34, 10
	v_lshl_add_u64 v[110:111], v[102:103], 2, v[2:3]
	global_load_dword v67, v[80:81], off nt
	global_load_dword v73, v[98:99], off nt
	global_load_dword v77, v[96:97], off nt
	global_load_dword v79, v[110:111], off nt
	v_lshl_add_u64 v[102:103], v[108:109], 2, v[2:3]
	v_mov_b32_e32 v99, v109
	v_add_lshl_u32 v98, v65, s3, 10
	v_lshl_add_u64 v[108:109], v[112:113], 2, v[2:3]
	v_lshl_add_u64 v[112:113], v[104:105], 2, v[2:3]
	v_lshl_add_u64 v[104:105], v[98:99], 2, v[2:3]
	v_mov_b32_e32 v111, v99
	global_load_dword v110, v[102:103], off nt
	global_load_dword v83, v[108:109], off nt
	global_load_dword v85, v[104:105], off nt
	global_load_dword v87, v[112:113], off nt
	s_add_i32 s31, s31, 8
	s_add_i32 s30, s30, 8
	s_add_i32 s35, s35, -8
	v_mad_u64_u32 v[98:99], s[64:65], v100, s41, v[4:5]
	s_cmp_lg_u32 s35, 0
	v_mad_u64_u32 v[102:103], s[64:65], v69, s41, v[4:5]
	v_mad_u64_u32 v[104:105], s[64:65], v106, s41, v[4:5]
	v_mad_u64_u32 v[108:109], s[64:65], v101, s41, v[4:5]
	v_mad_u64_u32 v[112:113], s[64:65], v66, s41, v[4:5]
	v_mad_u64_u32 v[80:81], s[64:65], v107, s41, v[4:5]
	v_mad_u64_u32 v[96:97], s[64:65], v65, s41, v[4:5]
	v_mad_u64_u32 v[100:101], s[64:65], v64, s41, v[4:5]
	s_waitcnt vmcnt(15)
	ds_write_b32 v94, v74
	s_waitcnt vmcnt(14)
	ds_write_b32 v90, v75
	s_waitcnt vmcnt(13)
	ds_write_b32 v78, v88
	s_waitcnt vmcnt(12)
	ds_write_b32 v82, v89
	s_waitcnt vmcnt(11)
	ds_write_b32 v86, v84
	s_waitcnt vmcnt(10)
	ds_write_b32 v76, v70
	s_waitcnt vmcnt(9)
	ds_write_b32 v68, v71
	s_waitcnt vmcnt(8)
	ds_write_b32 v72, v92
	s_waitcnt vmcnt(7)
	ds_write_b32 v98, v67
	s_waitcnt vmcnt(6)
	ds_write_b32 v102, v73
	s_waitcnt vmcnt(5)
	ds_write_b32 v104, v77
	s_waitcnt vmcnt(4)
	ds_write_b32 v108, v79
	s_waitcnt vmcnt(3)
	ds_write_b32 v112, v110
	s_waitcnt vmcnt(2)
	ds_write_b32 v80, v83
	s_waitcnt vmcnt(1)
	ds_write_b32 v96, v85
	s_waitcnt vmcnt(0)
	ds_write_b32 v100, v87
	v_mov_b32_e32 v0, v110
	v_mov_b32_e32 v1, v111
	v_mov_b32_e32 v8, v98
	v_mov_b32_e32 v9, v99
	v_mov_b32_e32 v10, v102
	v_mov_b32_e32 v11, v103
	v_mov_b32_e32 v12, v104
	v_mov_b32_e32 v13, v105
	v_mov_b32_e32 v17, v69
	v_mov_b32_e32 v18, v108
	v_mov_b32_e32 v19, v109
	v_mov_b32_e32 v20, v112
	v_mov_b32_e32 v21, v113
	v_mov_b32_e32 v22, v80
	v_mov_b32_e32 v23, v81
	v_mov_b32_e32 v24, v96
	v_mov_b32_e32 v25, v97
	v_mov_b32_e32 v26, v100
	v_mov_b32_e32 v27, v101
	v_mov_b32_e32 v28, v66
	v_mov_b32_e32 v29, v64
	v_mov_b32_e32 v30, v65
	v_mov_b32_e32 v31, v67
	v_mov_b32_e32 v32, v73
	v_mov_b32_e32 v33, v77
	v_mov_b32_e32 v34, v79
	v_mov_b32_e32 v35, v83
	v_mov_b32_e32 v36, v85
	v_mov_b32_e32 v37, v87
	v_lshlrev_b32_sdwa v0, v14, v7 dst_sel:DWORD dst_unused:UNUSED_PAD src0_sel:DWORD src1_sel:BYTE_0
	v_and_b32_e32 v0, 0x7e, v0
	v_lshrrev_b32_sdwa v2, v15, v7 dst_sel:DWORD dst_unused:UNUSED_PAD src0_sel:DWORD src1_sel:BYTE_0
	v_or_b32_e32 v12, s2, v2
	v_or_b32_e32 v6, s3, v0
	v_mul_u32_u24_e32 v0, 0x84, v0
	v_lshlrev_b32_e32 v2, 2, v2
	v_add3_u32 v17, s36, v0, v2
	s_waitcnt lgkmcnt(0)
	s_barrier
	ds_read2_b32 v[2:3], v17 offset0:33 offset1:37
	ds_read2_b32 v[4:5], v17 offset1:4
	s_lshl_b64 s[30:31], s[20:21], 20
	s_add_u32 s30, s1, s30
	s_addc_u32 s31, s33, s31
	v_lshlrev_b32_e32 v0, 1, v6
	v_lshl_add_u64 v[6:7], s[30:31], 0, v[0:1]
	ds_read2_b32 v[8:9], v17 offset0:8 offset1:12
	ds_read2_b32 v[10:11], v17 offset0:41 offset1:45
	v_lshlrev_b32_e32 v0, 10, v12
	s_waitcnt lgkmcnt(2)
	v_cvt_pk_bf16_f32 v2, v4, v2
	v_lshl_add_u64 v[6:7], v[6:7], 0, v[0:1]
	global_store_dword v[6:7], v2, off
	ds_read2_b32 v[12:13], v17 offset0:16 offset1:20
	ds_read2_b32 v[18:19], v17 offset0:49 offset1:53
	ds_read2_b32 v[20:21], v17 offset0:24 offset1:28
	ds_read2_b32 v[22:23], v17 offset0:57 offset1:61
	v_add_co_u32_e32 v24, vcc, s43, v6
	s_waitcnt lgkmcnt(4)
	v_cvt_pk_bf16_f32 v0, v8, v10
	v_addc_co_u32_e32 v25, vcc, 0, v7, vcc
	global_store_dword v[24:25], v0, off offset:-4096
	s_waitcnt lgkmcnt(2)
	v_cvt_pk_bf16_f32 v0, v12, v18
	global_store_dword v[24:25], v0, off
	v_add_co_u32_e32 v24, vcc, s52, v6
	s_waitcnt lgkmcnt(0)
	v_cvt_pk_bf16_f32 v0, v20, v22
	v_addc_co_u32_e32 v25, vcc, 0, v7, vcc
	global_store_dword v[24:25], v0, off offset:-4096
	v_cvt_pk_bf16_f32 v0, v5, v3
	v_add_co_u32_e32 v2, vcc, s53, v6
	global_store_dword v[24:25], v0, off
	v_cvt_pk_bf16_f32 v0, v9, v11
	v_addc_co_u32_e32 v3, vcc, 0, v7, vcc
	global_store_dword v[2:3], v0, off
	v_add_co_u32_e32 v2, vcc, 0x6000, v6
	v_cvt_pk_bf16_f32 v0, v13, v19
	s_nop 0
	v_addc_co_u32_e32 v3, vcc, 0, v7, vcc
	global_store_dword v[2:3], v0, off
	v_add_co_u32_e32 v2, vcc, 0x7000, v6
	v_cvt_pk_bf16_f32 v0, v21, v23
	s_nop 0
	v_addc_co_u32_e32 v3, vcc, 0, v7, vcc
	global_store_dword v[2:3], v0, off
	s_barrier

.LBB0_46:
	s_andn2_b64 vcc, exec, s[2:3]
	s_cbranch_vccnz .LBB0_58
	s_bfe_u32 s20, s38, 0x1a0005
	v_mov_b32_e32 v17, v198
	s_lshl_b64 s[2:3], s[20:21], 7
	s_bfe_u32 s20, s39, 0x10007
	v_mov_b32_e32 v5, v1
	v_bfe_u32 v10, v17, 5, 3
	v_lshlrev_b32_e32 v2, 2, v17
	v_lshl_or_b32 v8, s20, 7, v10
	v_mul_u32_u24_e32 v0, 0x84, v10
	v_and_b32_e32 v12, 0x7c, v2
	v_lshlrev_b32_e32 v6, 12, v8
	v_add3_u32 v18, v0, v12, s36
	v_or_b32_e32 v0, 0x18000, v6
	v_lshl_add_u64 v[2:3], s[2:3], 0, v[0:1]
	v_lshlrev_b32_e32 v0, 2, v10
	v_lshlrev_b32_e32 v10, 12, v10
	v_or_b32_e32 v4, 0x10000, v6
	v_or_b32_e32 v6, 0x8000, v6
	v_mov_b32_e32 v7, v1
	v_lshl_or_b32 v10, s20, 19, v10
	v_mov_b32_e32 v11, v1
	v_readlane_b32 s44, v240, 2
	v_lshl_add_u64 v[4:5], s[2:3], 0, v[4:5]
	v_lshl_add_u64 v[6:7], s[2:3], 0, v[6:7]
	v_lshl_add_u64 v[10:11], s[2:3], 0, v[10:11]
	v_or_b32_e32 v2, v2, v12
	v_readlane_b32 s48, v240, 6
	v_readlane_b32 s49, v240, 7
	v_readlane_b32 s50, v240, 8
	v_readlane_b32 s51, v240, 9
	v_or_b32_e32 v4, v4, v12
	v_or_b32_e32 v6, v6, v12
	v_or_b32_e32 v10, v10, v12
	v_lshl_add_u64 v[2:3], s[50:51], 0, v[2:3]
	v_lshl_or_b32 v0, s20, 9, v0
	v_lshl_add_u64 v[4:5], s[50:51], 0, v[4:5]
	v_lshl_add_u64 v[6:7], s[50:51], 0, v[6:7]
	v_lshlrev_b32_e32 v8, 2, v8
	v_mov_b32_e32 v9, v1
	v_lshl_add_u64 v[10:11], s[50:51], 0, v[10:11]
	s_mov_b64 s[30:31], 0
	s_mov_b64 s[34:35], s[48:49]
	v_readlane_b32 s45, v240, 3
	v_readlane_b32 s46, v240, 4
	v_readlane_b32 s47, v240, 5
	s_andn2_b64 vcc, exec, s[6:7]
	s_cbranch_vccnz .LBB0_49
	v_lshl_add_u64 v[64:65], v[10:11], 0, s[30:31]
	v_mov_b32_e32 v67, v65
	global_load_dword v66, v[64:65], off nt
	v_cndmask_b32_e64 v64, 0, 1, s[6:7]
	v_cmp_ne_u32_e64 s[2:3], 1, v64
	s_andn2_b64 vcc, exec, s[6:7]
	v_lshl_add_u64 v[68:69], s[34:35], 0, v[8:9]
	global_load_dword v65, v[68:69], off nt
	v_lshl_add_u64 v[70:71], v[6:7], 0, s[30:31]
	global_load_dword v64, v[70:71], off nt
	s_and_b64 vcc, exec, s[2:3]
	v_lshl_add_u64 v[68:69], s[34:35], 0, v[0:1]
	v_mov_b32_e32 v73, v71
	global_load_dword v72, v[68:69], off offset:32 nt
	v_lshl_add_u64 v[70:71], v[4:5], 0, s[30:31]
	v_mov_b32_e32 v75, v71
	global_load_dword v74, v[70:71], off nt
	s_and_b64 vcc, exec, s[2:3]
	global_load_dword v67, v[68:69], off offset:64 nt
	v_lshl_add_u64 v[70:71], v[2:3], 0, s[30:31]
	global_load_dword v73, v[70:71], off nt
	s_and_b64 vcc, exec, s[2:3]
	v_mov_b32_e32 v77, v69
	global_load_dword v76, v[68:69], off offset:96 nt
	s_add_u32 s30, s30, 0x20000
	s_addc_u32 s31, s31, 0
	s_add_u32 s34, s34, 0x80
	s_addc_u32 s35, s35, 0
	s_cmp_lg_u32 s30, 0x80000
	v_add_u32_e32 v68, 0x1080, v18
	v_lshl_add_u64 v[78:79], v[10:11], 0, s[30:31]
	v_mov_b32_e32 v81, v79
	global_load_dword v80, v[78:79], off nt
	v_cndmask_b32_e64 v69, 0, 1, s[6:7]
	v_cmp_ne_u32_e64 s[2:3], 1, v69
	s_andn2_b64 vcc, exec, s[6:7]
	v_lshl_add_u64 v[78:79], s[34:35], 0, v[8:9]
	global_load_dword v75, v[78:79], off nt
	v_lshl_add_u64 v[82:83], v[6:7], 0, s[30:31]
	global_load_dword v69, v[82:83], off nt
	s_and_b64 vcc, exec, s[2:3]
	v_lshl_add_u64 v[78:79], s[34:35], 0, v[0:1]
	v_mov_b32_e32 v85, v83
	global_load_dword v84, v[78:79], off offset:32 nt
	v_lshl_add_u64 v[82:83], v[4:5], 0, s[30:31]
	v_mov_b32_e32 v87, v83
	global_load_dword v86, v[82:83], off nt
	s_and_b64 vcc, exec, s[2:3]
	global_load_dword v77, v[78:79], off offset:64 nt
	v_lshl_add_u64 v[82:83], v[2:3], 0, s[30:31]
	global_load_dword v70, v[82:83], off nt
	s_and_b64 vcc, exec, s[2:3]
	v_mov_b32_e32 v89, v79
	global_load_dword v88, v[78:79], off offset:96 nt
	s_add_u32 s30, s30, 0x20000
	s_addc_u32 s31, s31, 0
	s_add_u32 s34, s34, 0x80
	s_addc_u32 s35, s35, 0
	s_cmp_lg_u32 s30, 0x80000
	v_add_u32_e32 v71, 0x1080, v68
	v_lshl_add_u64 v[78:79], v[10:11], 0, s[30:31]
	v_mov_b32_e32 v91, v79
	global_load_dword v90, v[78:79], off nt
	v_cndmask_b32_e64 v78, 0, 1, s[6:7]
	v_cmp_ne_u32_e64 s[2:3], 1, v78
	s_andn2_b64 vcc, exec, s[6:7]
	v_lshl_add_u64 v[92:93], s[34:35], 0, v[8:9]
	global_load_dword v79, v[92:93], off nt
	v_lshl_add_u64 v[94:95], v[6:7], 0, s[30:31]
	global_load_dword v78, v[94:95], off nt
	s_and_b64 vcc, exec, s[2:3]
	v_lshl_add_u64 v[92:93], s[34:35], 0, v[0:1]
	v_mov_b32_e32 v97, v95
	global_load_dword v96, v[92:93], off offset:32 nt
	v_lshl_add_u64 v[94:95], v[4:5], 0, s[30:31]
	v_mov_b32_e32 v99, v95
	global_load_dword v98, v[94:95], off nt
	s_and_b64 vcc, exec, s[2:3]
	global_load_dword v81, v[92:93], off offset:64 nt
	v_lshl_add_u64 v[94:95], v[2:3], 0, s[30:31]
	global_load_dword v82, v[94:95], off nt
	s_and_b64 vcc, exec, s[2:3]
	v_mov_b32_e32 v101, v93
	global_load_dword v100, v[92:93], off offset:96 nt
	s_add_u32 s30, s30, 0x20000
	s_addc_u32 s31, s31, 0
	s_add_u32 s34, s34, 0x80
	s_addc_u32 s35, s35, 0
	s_cmp_lg_u32 s30, 0x80000
	v_add_u32_e32 v83, 0x1080, v71
	v_lshl_add_u64 v[92:93], v[10:11], 0, s[30:31]
	v_mov_b32_e32 v103, v93
	global_load_dword v102, v[92:93], off nt
	v_cndmask_b32_e64 v85, 0, 1, s[6:7]
	v_cmp_ne_u32_e64 s[2:3], 1, v85
	s_andn2_b64 vcc, exec, s[6:7]
	v_lshl_add_u64 v[92:93], s[34:35], 0, v[8:9]
	global_load_dword v87, v[92:93], off nt
	v_lshl_add_u64 v[104:105], v[6:7], 0, s[30:31]
	global_load_dword v85, v[104:105], off nt
	s_and_b64 vcc, exec, s[2:3]
	v_lshl_add_u64 v[92:93], s[34:35], 0, v[0:1]
	v_mov_b32_e32 v107, v105
	global_load_dword v106, v[92:93], off offset:32 nt
	v_lshl_add_u64 v[104:105], v[4:5], 0, s[30:31]
	v_mov_b32_e32 v109, v105
	global_load_dword v108, v[104:105], off nt
	s_and_b64 vcc, exec, s[2:3]
	global_load_dword v89, v[92:93], off offset:64 nt
	v_lshl_add_u64 v[104:105], v[2:3], 0, s[30:31]
	global_load_dword v91, v[104:105], off nt
	s_and_b64 vcc, exec, s[2:3]
	v_mov_b32_e32 v95, v93
	global_load_dword v94, v[92:93], off offset:96 nt
	s_add_u32 s30, s30, 0x20000
	s_addc_u32 s31, s31, 0
	s_add_u32 s34, s34, 0x80
	s_addc_u32 s35, s35, 0
	s_cmp_lg_u32 s30, 0x80000
	v_add_u32_e32 v92, 0x1080, v83
	s_waitcnt vmcnt(30)
	v_mul_f32_e32 v66, v66, v65
	ds_write_b32 v18, v66
	s_waitcnt vmcnt(28)
	v_mul_f32_e32 v64, v64, v72
	ds_write_b32 v18, v64 offset:1056
	s_waitcnt vmcnt(26)
	v_mul_f32_e32 v74, v74, v67
	ds_write_b32 v18, v74 offset:2112
	s_waitcnt vmcnt(24)
	v_mul_f32_e32 v73, v73, v76
	ds_write_b32 v18, v73 offset:3168
	s_waitcnt vmcnt(22)
	v_mul_f32_e32 v80, v80, v75
	ds_write_b32 v68, v80
	s_waitcnt vmcnt(20)
	v_mul_f32_e32 v69, v69, v84
	ds_write_b32 v68, v69 offset:1056
	s_waitcnt vmcnt(18)
	v_mul_f32_e32 v86, v86, v77
	ds_write_b32 v68, v86 offset:2112
	s_waitcnt vmcnt(16)
	v_mul_f32_e32 v70, v70, v88
	ds_write_b32 v68, v70 offset:3168
	s_waitcnt vmcnt(14)
	v_mul_f32_e32 v90, v90, v79
	ds_write_b32 v71, v90
	s_waitcnt vmcnt(12)
	v_mul_f32_e32 v78, v78, v96
	ds_write_b32 v71, v78 offset:1056
	s_waitcnt vmcnt(10)
	v_mul_f32_e32 v98, v98, v81
	ds_write_b32 v71, v98 offset:2112
	s_waitcnt vmcnt(8)
	v_mul_f32_e32 v82, v82, v100
	ds_write_b32 v71, v82 offset:3168
	s_waitcnt vmcnt(6)
	v_mul_f32_e32 v102, v102, v87
	ds_write_b32 v83, v102
	s_waitcnt vmcnt(4)
	v_mul_f32_e32 v85, v85, v106
	ds_write_b32 v83, v85 offset:1056
	s_waitcnt vmcnt(2)
	v_mul_f32_e32 v108, v108, v89
	ds_write_b32 v83, v108 offset:2112
	s_waitcnt vmcnt(0)
	v_mul_f32_e32 v91, v91, v94
	ds_write_b32 v83, v91 offset:3168
	v_mov_b32_e32 v12, v94
	v_mov_b32_e32 v13, v95
	v_mov_b32_e32 v18, v92
	v_mov_b32_e32 v19, v91
	v_mov_b32_e32 v20, v108
	v_mov_b32_e32 v21, v109
	v_mov_b32_e32 v22, v104
	v_mov_b32_e32 v23, v105
	s_branch .LBB0_57

.LBB0_64:
	s_mul_i32 s2, s59, 6
	s_sub_i32 s2, s30, s2
	s_and_b32 s2, s2, 0xff
	v_readlane_b32 s44, v240, 2
	s_lshl_b32 s34, s2, 7
	s_lshl_b64 s[2:3], s[20:21], 2
	v_readlane_b32 s46, v240, 4
	v_readlane_b32 s47, v240, 5
	s_add_u32 s30, s46, s2
	s_addc_u32 s31, s47, s3
	s_cmpk_gt_u32 s35, 0x59
	s_mov_b64 s[2:3], -1
	s_mul_i32 s20, s59, 48
	v_readlane_b32 s45, v240, 3
	v_readlane_b32 s48, v240, 6
	v_readlane_b32 s49, v240, 7
	v_readlane_b32 s50, v240, 8
	v_readlane_b32 s51, v240, 9
	s_cbranch_scc0 .LBB0_76
	v_mov_b32_e32 v6, v198
	s_mul_hi_u32 s2, s35, 0x2aaaaaab
	v_bfe_u32 v4, v6, 5, 3
	v_lshlrev_b32_e32 v0, 2, v6
	v_and_b32_e32 v0, 0x7c, v0
	v_mul_u32_u24_e32 v5, 0x84, v4
	v_lshl_add_u64 v[2:3], s[30:31], 0, v[0:1]
	v_add3_u32 v7, v5, v0, s36
	v_lshl_or_b32 v0, s35, 7, v4
	s_mulk_i32 s2, 0x300
	v_subrev_u32_e32 v8, s2, v0
	v_add_lshl_u32 v0, v4, s34, 2
	v_lshl_add_u64 v[4:5], s[22:23], 0, v[0:1]
	s_mov_b32 s59, 0
	s_andn2_b64 vcc, exec, s[10:11]
	s_cbranch_vccnz .LBB0_67
	v_mov_b32_e32 v65, v1
	v_add_u32_e32 v64, s59, v8
	v_mad_u64_u32 v[66:67], s[2:3], v64, s55, v[2:3]
	global_load_dword v68, v[66:67], off nt
	v_mov_b32_e32 v71, v67
	v_cndmask_b32_e64 v70, 0, 1, s[10:11]
	v_cmp_ne_u32_e64 s[2:3], 1, v70
	s_andn2_b64 vcc, exec, s[10:11]
	v_readlane_b32 s44, v240, 2
	v_readlane_b32 s45, v240, 3
	v_readlane_b32 s46, v240, 4
	v_readlane_b32 s47, v240, 5
	v_lshl_add_u64 v[66:67], v[64:65], 2, s[44:45]
	v_mov_b32_e32 v71, v67
	global_load_dword v70, v[66:67], off nt
	v_readlane_b32 s48, v240, 6
	v_readlane_b32 s49, v240, 7
	v_readlane_b32 s50, v240, 8
	v_readlane_b32 s51, v240, 9
	v_mov_b32_e32 v67, v71
	v_add_u32_e32 v66, 8, v64
	v_mad_u64_u32 v[72:73], s[64:65], v66, s55, v[2:3]
	v_mov_b32_e32 v67, v73
	global_load_dword v66, v[72:73], off nt
	s_and_b64 vcc, exec, s[2:3]
	global_load_dword v69, v[4:5], off offset:-32 nt
	v_add_u32_e32 v71, 16, v64
	v_mad_u64_u32 v[72:73], s[64:65], v71, s55, v[2:3]
	global_load_dword v74, v[72:73], off nt
	s_and_b64 vcc, exec, s[2:3]
	v_mov_b32_e32 v77, v67
	global_load_dword v76, v[4:5], off nt
	v_mov_b32_e32 v79, v65
	v_add_u32_e32 v78, 24, v64
	v_mad_u64_u32 v[64:65], s[64:65], v78, s55, v[2:3]
	v_mov_b32_e32 v81, v79
	global_load_dword v80, v[64:65], off nt
	s_and_b64 vcc, exec, s[2:3]
	global_load_dword v67, v[4:5], off offset:32 nt
	s_add_i32 s59, s59, 32
	v_add_u32_e32 v71, 0x1080, v7
	s_cmpk_lg_i32 s59, 0x80
	v_lshl_add_u64 v[78:79], v[4:5], 0, s[24:25]
	v_mov_b32_e32 v83, v81
	v_add_u32_e32 v82, s59, v8
	v_mad_u64_u32 v[84:85], s[2:3], v82, s55, v[2:3]
	global_load_dword v64, v[84:85], off nt
	v_mov_b32_e32 v87, v85
	v_cndmask_b32_e64 v86, 0, 1, s[10:11]
	v_cmp_ne_u32_e64 s[2:3], 1, v86
	s_andn2_b64 vcc, exec, s[10:11]
	v_readlane_b32 s44, v240, 2
	v_readlane_b32 s45, v240, 3
	v_readlane_b32 s46, v240, 4
	v_readlane_b32 s47, v240, 5
	v_lshl_add_u64 v[84:85], v[82:83], 2, s[44:45]
	v_mov_b32_e32 v87, v85
	global_load_dword v86, v[84:85], off nt
	v_readlane_b32 s48, v240, 6
	v_readlane_b32 s49, v240, 7
	v_readlane_b32 s50, v240, 8
	v_readlane_b32 s51, v240, 9
	v_mov_b32_e32 v85, v87
	v_add_u32_e32 v84, 8, v82
	v_mad_u64_u32 v[88:89], s[64:65], v84, s55, v[2:3]
	v_mov_b32_e32 v85, v89
	global_load_dword v84, v[88:89], off nt
	s_and_b64 vcc, exec, s[2:3]
	global_load_dword v65, v[78:79], off offset:-32 nt
	v_add_u32_e32 v75, 16, v82
	v_mad_u64_u32 v[88:89], s[64:65], v75, s55, v[2:3]
	global_load_dword v72, v[88:89], off nt
	s_and_b64 vcc, exec, s[2:3]
	v_mov_b32_e32 v91, v85
	global_load_dword v90, v[78:79], off nt
	v_mov_b32_e32 v93, v83
	v_add_u32_e32 v92, 24, v82
	v_mad_u64_u32 v[82:83], s[64:65], v92, s55, v[2:3]
	v_mov_b32_e32 v95, v93
	global_load_dword v94, v[82:83], off nt
	s_and_b64 vcc, exec, s[2:3]
	global_load_dword v73, v[78:79], off offset:32 nt
	s_add_i32 s59, s59, 32
	v_add_u32_e32 v75, 0x1080, v71
	s_cmpk_lg_i32 s59, 0x80
	v_lshl_add_u64 v[92:93], v[78:79], 0, s[24:25]
	v_mov_b32_e32 v79, v95
	v_add_u32_e32 v78, s59, v8
	v_mad_u64_u32 v[96:97], s[2:3], v78, s55, v[2:3]
	global_load_dword v77, v[96:97], off nt
	v_mov_b32_e32 v83, v97
	v_cndmask_b32_e64 v82, 0, 1, s[10:11]
	v_cmp_ne_u32_e64 s[2:3], 1, v82
	s_andn2_b64 vcc, exec, s[10:11]
	v_readlane_b32 s44, v240, 2
	v_readlane_b32 s45, v240, 3
	v_readlane_b32 s46, v240, 4
	v_readlane_b32 s47, v240, 5
	v_lshl_add_u64 v[96:97], v[78:79], 2, s[44:45]
	v_mov_b32_e32 v83, v97
	global_load_dword v82, v[96:97], off nt
	v_readlane_b32 s48, v240, 6
	v_readlane_b32 s49, v240, 7
	v_readlane_b32 s50, v240, 8
	v_readlane_b32 s51, v240, 9
	v_mov_b32_e32 v97, v83
	v_add_u32_e32 v96, 8, v78
	v_mad_u64_u32 v[98:99], s[64:65], v96, s55, v[2:3]
	v_mov_b32_e32 v97, v99
	global_load_dword v96, v[98:99], off nt
	s_and_b64 vcc, exec, s[2:3]
	global_load_dword v81, v[92:93], off offset:-32 nt
	v_add_u32_e32 v83, 16, v78
	v_mad_u64_u32 v[98:99], s[64:65], v83, s55, v[2:3]
	global_load_dword v85, v[98:99], off nt
	s_and_b64 vcc, exec, s[2:3]
	v_mov_b32_e32 v89, v97
	global_load_dword v88, v[92:93], off nt
	v_mov_b32_e32 v101, v79
	v_add_u32_e32 v100, 24, v78
	v_mad_u64_u32 v[78:79], s[64:65], v100, s55, v[2:3]
	v_mov_b32_e32 v103, v101
	global_load_dword v102, v[78:79], off nt
	s_and_b64 vcc, exec, s[2:3]
	global_load_dword v83, v[92:93], off offset:32 nt
	s_add_i32 s59, s59, 32
	v_add_u32_e32 v87, 0x1080, v75
	s_cmpk_lg_i32 s59, 0x80
	v_lshl_add_u64 v[100:101], v[92:93], 0, s[24:25]
	v_mov_b32_e32 v93, v103
	v_add_u32_e32 v92, s59, v8
	v_mad_u64_u32 v[104:105], s[2:3], v92, s55, v[2:3]
	global_load_dword v78, v[104:105], off nt
	v_mov_b32_e32 v107, v105
	v_cndmask_b32_e64 v106, 0, 1, s[10:11]
	v_cmp_ne_u32_e64 s[2:3], 1, v106
	s_andn2_b64 vcc, exec, s[10:11]
	v_readlane_b32 s44, v240, 2
	v_readlane_b32 s45, v240, 3
	v_readlane_b32 s46, v240, 4
	v_readlane_b32 s47, v240, 5
	v_lshl_add_u64 v[104:105], v[92:93], 2, s[44:45]
	v_mov_b32_e32 v107, v105
	global_load_dword v106, v[104:105], off nt
	v_readlane_b32 s48, v240, 6
	v_readlane_b32 s49, v240, 7
	v_readlane_b32 s50, v240, 8
	v_readlane_b32 s51, v240, 9
	v_mov_b32_e32 v105, v107
	v_add_u32_e32 v104, 8, v92
	v_mad_u64_u32 v[108:109], s[64:65], v104, s55, v[2:3]
	v_mov_b32_e32 v105, v109
	global_load_dword v104, v[108:109], off nt
	s_and_b64 vcc, exec, s[2:3]
	global_load_dword v79, v[100:101], off offset:-32 nt
	v_add_u32_e32 v89, 16, v92
	v_mad_u64_u32 v[108:109], s[64:65], v89, s55, v[2:3]
	global_load_dword v91, v[108:109], off nt
	s_and_b64 vcc, exec, s[2:3]
	v_mov_b32_e32 v99, v105
	global_load_dword v98, v[100:101], off nt
	v_mov_b32_e32 v111, v93
	v_add_u32_e32 v110, 24, v92
	v_mad_u64_u32 v[92:93], s[64:65], v110, s55, v[2:3]
	v_mov_b32_e32 v113, v111
	global_load_dword v112, v[92:93], off nt
	s_and_b64 vcc, exec, s[2:3]
	global_load_dword v89, v[100:101], off offset:32 nt
	s_add_i32 s59, s59, 32
	v_add_u32_e32 v95, 0x1080, v87
	s_cmpk_lg_i32 s59, 0x80
	v_lshl_add_u64 v[110:111], v[100:101], 0, s[24:25]
	s_waitcnt vmcnt(30)
	v_mul_f32_e32 v68, v68, v70
	v_mul_f32_e32 v68, 0x3e16c740, v68
	ds_write_b32 v7, v68
	s_waitcnt vmcnt(28)
	v_mul_f32_e32 v66, v66, v69
	v_mul_f32_e32 v66, 0x3e16c740, v66
	ds_write_b32 v7, v66 offset:1056
	s_waitcnt vmcnt(26)
	v_mul_f32_e32 v74, v74, v76
	v_mul_f32_e32 v74, 0x3e16c740, v74
	ds_write_b32 v7, v74 offset:2112
	s_waitcnt vmcnt(24)
	v_mul_f32_e32 v80, v80, v67
	v_mul_f32_e32 v80, 0x3e16c740, v80
	ds_write_b32 v7, v80 offset:3168
	s_waitcnt vmcnt(22)
	v_mul_f32_e32 v64, v64, v86
	v_mul_f32_e32 v64, 0x3e16c740, v64
	ds_write_b32 v71, v64
	s_waitcnt vmcnt(20)
	v_mul_f32_e32 v84, v84, v65
	v_mul_f32_e32 v84, 0x3e16c740, v84
	ds_write_b32 v71, v84 offset:1056
	s_waitcnt vmcnt(18)
	v_mul_f32_e32 v72, v72, v90
	v_mul_f32_e32 v72, 0x3e16c740, v72
	ds_write_b32 v71, v72 offset:2112
	s_waitcnt vmcnt(16)
	v_mul_f32_e32 v94, v94, v73
	v_mul_f32_e32 v94, 0x3e16c740, v94
	ds_write_b32 v71, v94 offset:3168
	s_waitcnt vmcnt(14)
	v_mul_f32_e32 v77, v77, v82
	v_mul_f32_e32 v77, 0x3e16c740, v77
	ds_write_b32 v75, v77
	s_waitcnt vmcnt(12)
	v_mul_f32_e32 v96, v96, v81
	v_mul_f32_e32 v96, 0x3e16c740, v96
	ds_write_b32 v75, v96 offset:1056
	s_waitcnt vmcnt(10)
	v_mul_f32_e32 v85, v85, v88
	v_mul_f32_e32 v85, 0x3e16c740, v85
	ds_write_b32 v75, v85 offset:2112
	s_waitcnt vmcnt(8)
	v_mul_f32_e32 v102, v102, v83
	v_mul_f32_e32 v102, 0x3e16c740, v102
	ds_write_b32 v75, v102 offset:3168
	s_waitcnt vmcnt(6)
	v_mul_f32_e32 v78, v78, v106
	v_mul_f32_e32 v78, 0x3e16c740, v78
	ds_write_b32 v87, v78
	s_waitcnt vmcnt(4)
	v_mul_f32_e32 v104, v104, v79
	v_mul_f32_e32 v104, 0x3e16c740, v104
	ds_write_b32 v87, v104 offset:1056
	s_waitcnt vmcnt(2)
	v_mul_f32_e32 v91, v91, v98
	v_mul_f32_e32 v91, 0x3e16c740, v91
	ds_write_b32 v87, v91 offset:2112
	s_waitcnt vmcnt(0)
	v_mul_f32_e32 v112, v112, v89
	v_mul_f32_e32 v112, 0x3e16c740, v112
	ds_write_b32 v87, v112 offset:3168
	v_mov_b32_e32 v0, v112
	v_mov_b32_e32 v1, v113
	v_mov_b32_e32 v4, v110
	v_mov_b32_e32 v5, v111
	v_mov_b32_e32 v7, v95
	v_mov_b32_e32 v9, v89
	v_mov_b32_e32 v10, v92
	v_mov_b32_e32 v11, v93
	v_mov_b32_e32 v12, v108
	v_mov_b32_e32 v13, v109
	s_branch .LBB0_75

.LBB0_76:
	s_and_b64 vcc, exec, s[2:3]
	s_cbranch_vccz .LBB0_88
	v_mov_b32_e32 v6, v198
	s_mul_hi_u32 s2, s35, 0x2aaaaaab
	v_bfe_u32 v4, v6, 5, 3
	v_lshlrev_b32_e32 v0, 2, v6
	v_and_b32_e32 v0, 0x7c, v0
	v_mul_u32_u24_e32 v5, 0x84, v4
	v_lshl_add_u64 v[2:3], s[30:31], 0, v[0:1]
	v_add3_u32 v7, v5, v0, s36
	v_lshl_or_b32 v0, s35, 7, v4
	s_mulk_i32 s2, 0x300
	v_subrev_u32_e32 v8, s2, v0
	v_add_lshl_u32 v0, v4, s34, 2
	v_lshl_add_u64 v[4:5], s[22:23], 0, v[0:1]
	s_mov_b32 s30, 0
	s_andn2_b64 vcc, exec, s[10:11]
	s_cbranch_vccnz .LBB0_79
	v_mov_b32_e32 v65, v1
	v_add_u32_e32 v64, s30, v8
	v_mad_u64_u32 v[66:67], s[2:3], v64, s55, v[2:3]
	global_load_dword v68, v[66:67], off nt
	v_mov_b32_e32 v71, v67
	v_cndmask_b32_e64 v70, 0, 1, s[10:11]
	v_cmp_ne_u32_e64 s[2:3], 1, v70
	s_andn2_b64 vcc, exec, s[10:11]
	v_readlane_b32 s44, v240, 2
	v_readlane_b32 s45, v240, 3
	v_readlane_b32 s46, v240, 4
	v_readlane_b32 s47, v240, 5
	v_lshl_add_u64 v[66:67], v[64:65], 2, s[44:45]
	v_mov_b32_e32 v71, v67
	global_load_dword v70, v[66:67], off nt
	v_readlane_b32 s48, v240, 6
	v_readlane_b32 s49, v240, 7
	v_readlane_b32 s50, v240, 8
	v_readlane_b32 s51, v240, 9
	v_mov_b32_e32 v67, v71
	v_add_u32_e32 v66, 8, v64
	v_mad_u64_u32 v[72:73], s[64:65], v66, s55, v[2:3]
	v_mov_b32_e32 v67, v73
	global_load_dword v66, v[72:73], off nt
	s_and_b64 vcc, exec, s[2:3]
	global_load_dword v69, v[4:5], off offset:-32 nt
	v_add_u32_e32 v71, 16, v64
	v_mad_u64_u32 v[72:73], s[64:65], v71, s55, v[2:3]
	global_load_dword v74, v[72:73], off nt
	s_and_b64 vcc, exec, s[2:3]
	v_mov_b32_e32 v77, v67
	global_load_dword v76, v[4:5], off nt
	v_mov_b32_e32 v79, v65
	v_add_u32_e32 v78, 24, v64
	v_mad_u64_u32 v[64:65], s[64:65], v78, s55, v[2:3]
	v_mov_b32_e32 v81, v79
	global_load_dword v80, v[64:65], off nt
	s_and_b64 vcc, exec, s[2:3]
	global_load_dword v67, v[4:5], off offset:32 nt
	s_add_i32 s30, s30, 32
	v_add_u32_e32 v71, 0x1080, v7
	s_cmpk_lg_i32 s30, 0x80
	v_lshl_add_u64 v[78:79], v[4:5], 0, s[24:25]
	v_mov_b32_e32 v83, v81
	v_add_u32_e32 v82, s30, v8
	v_mad_u64_u32 v[84:85], s[2:3], v82, s55, v[2:3]
	global_load_dword v64, v[84:85], off nt
	v_mov_b32_e32 v87, v85
	v_cndmask_b32_e64 v86, 0, 1, s[10:11]
	v_cmp_ne_u32_e64 s[2:3], 1, v86
	s_andn2_b64 vcc, exec, s[10:11]
	v_readlane_b32 s44, v240, 2
	v_readlane_b32 s45, v240, 3
	v_readlane_b32 s46, v240, 4
	v_readlane_b32 s47, v240, 5
	v_lshl_add_u64 v[84:85], v[82:83], 2, s[44:45]
	v_mov_b32_e32 v87, v85
	global_load_dword v86, v[84:85], off nt
	v_readlane_b32 s48, v240, 6
	v_readlane_b32 s49, v240, 7
	v_readlane_b32 s50, v240, 8
	v_readlane_b32 s51, v240, 9
	v_mov_b32_e32 v85, v87
	v_add_u32_e32 v84, 8, v82
	v_mad_u64_u32 v[88:89], s[64:65], v84, s55, v[2:3]
	v_mov_b32_e32 v85, v89
	global_load_dword v84, v[88:89], off nt
	s_and_b64 vcc, exec, s[2:3]
	global_load_dword v65, v[78:79], off offset:-32 nt
	v_add_u32_e32 v75, 16, v82
	v_mad_u64_u32 v[88:89], s[64:65], v75, s55, v[2:3]
	global_load_dword v72, v[88:89], off nt
	s_and_b64 vcc, exec, s[2:3]
	v_mov_b32_e32 v91, v85
	global_load_dword v90, v[78:79], off nt
	v_mov_b32_e32 v93, v83
	v_add_u32_e32 v92, 24, v82
	v_mad_u64_u32 v[82:83], s[64:65], v92, s55, v[2:3]
	v_mov_b32_e32 v95, v93
	global_load_dword v94, v[82:83], off nt
	s_and_b64 vcc, exec, s[2:3]
	global_load_dword v73, v[78:79], off offset:32 nt
	s_add_i32 s30, s30, 32
	v_add_u32_e32 v75, 0x1080, v71
	s_cmpk_lg_i32 s30, 0x80
	v_lshl_add_u64 v[92:93], v[78:79], 0, s[24:25]
	v_mov_b32_e32 v79, v95
	v_add_u32_e32 v78, s30, v8
	v_mad_u64_u32 v[96:97], s[2:3], v78, s55, v[2:3]
	global_load_dword v77, v[96:97], off nt
	v_mov_b32_e32 v83, v97
	v_cndmask_b32_e64 v82, 0, 1, s[10:11]
	v_cmp_ne_u32_e64 s[2:3], 1, v82
	s_andn2_b64 vcc, exec, s[10:11]
	v_readlane_b32 s44, v240, 2
	v_readlane_b32 s45, v240, 3
	v_readlane_b32 s46, v240, 4
	v_readlane_b32 s47, v240, 5
	v_lshl_add_u64 v[96:97], v[78:79], 2, s[44:45]
	v_mov_b32_e32 v83, v97
	global_load_dword v82, v[96:97], off nt
	v_readlane_b32 s48, v240, 6
	v_readlane_b32 s49, v240, 7
	v_readlane_b32 s50, v240, 8
	v_readlane_b32 s51, v240, 9
	v_mov_b32_e32 v97, v83
	v_add_u32_e32 v96, 8, v78
	v_mad_u64_u32 v[98:99], s[64:65], v96, s55, v[2:3]
	v_mov_b32_e32 v97, v99
	global_load_dword v96, v[98:99], off nt
	s_and_b64 vcc, exec, s[2:3]
	global_load_dword v81, v[92:93], off offset:-32 nt
	v_add_u32_e32 v83, 16, v78
	v_mad_u64_u32 v[98:99], s[64:65], v83, s55, v[2:3]
	global_load_dword v85, v[98:99], off nt
	s_and_b64 vcc, exec, s[2:3]
	v_mov_b32_e32 v89, v97
	global_load_dword v88, v[92:93], off nt
	v_mov_b32_e32 v101, v79
	v_add_u32_e32 v100, 24, v78
	v_mad_u64_u32 v[78:79], s[64:65], v100, s55, v[2:3]
	v_mov_b32_e32 v103, v101
	global_load_dword v102, v[78:79], off nt
	s_and_b64 vcc, exec, s[2:3]
	global_load_dword v83, v[92:93], off offset:32 nt
	s_add_i32 s30, s30, 32
	v_add_u32_e32 v87, 0x1080, v75
	s_cmpk_lg_i32 s30, 0x80
	v_lshl_add_u64 v[100:101], v[92:93], 0, s[24:25]
	v_mov_b32_e32 v93, v103
	v_add_u32_e32 v92, s30, v8
	v_mad_u64_u32 v[104:105], s[2:3], v92, s55, v[2:3]
	global_load_dword v78, v[104:105], off nt
	v_mov_b32_e32 v107, v105
	v_cndmask_b32_e64 v106, 0, 1, s[10:11]
	v_cmp_ne_u32_e64 s[2:3], 1, v106
	s_andn2_b64 vcc, exec, s[10:11]
	v_readlane_b32 s44, v240, 2
	v_readlane_b32 s45, v240, 3
	v_readlane_b32 s46, v240, 4
	v_readlane_b32 s47, v240, 5
	v_lshl_add_u64 v[104:105], v[92:93], 2, s[44:45]
	v_mov_b32_e32 v107, v105
	global_load_dword v106, v[104:105], off nt
	v_readlane_b32 s48, v240, 6
	v_readlane_b32 s49, v240, 7
	v_readlane_b32 s50, v240, 8
	v_readlane_b32 s51, v240, 9
	v_mov_b32_e32 v105, v107
	v_add_u32_e32 v104, 8, v92
	v_mad_u64_u32 v[108:109], s[64:65], v104, s55, v[2:3]
	v_mov_b32_e32 v105, v109
	global_load_dword v104, v[108:109], off nt
	s_and_b64 vcc, exec, s[2:3]
	global_load_dword v79, v[100:101], off offset:-32 nt
	v_add_u32_e32 v89, 16, v92
	v_mad_u64_u32 v[108:109], s[64:65], v89, s55, v[2:3]
	global_load_dword v91, v[108:109], off nt
	s_and_b64 vcc, exec, s[2:3]
	v_mov_b32_e32 v99, v105
	global_load_dword v98, v[100:101], off nt
	v_mov_b32_e32 v111, v93
	v_add_u32_e32 v110, 24, v92
	v_mad_u64_u32 v[92:93], s[64:65], v110, s55, v[2:3]
	v_mov_b32_e32 v113, v111
	global_load_dword v112, v[92:93], off nt
	s_and_b64 vcc, exec, s[2:3]
	global_load_dword v89, v[100:101], off offset:32 nt
	s_add_i32 s30, s30, 32
	v_add_u32_e32 v95, 0x1080, v87
	s_cmpk_lg_i32 s30, 0x80
	v_lshl_add_u64 v[110:111], v[100:101], 0, s[24:25]
	s_waitcnt vmcnt(30)
	v_mul_f32_e32 v68, v68, v70
	v_mul_f32_e32 v68, 0x3e16c740, v68
	ds_write_b32 v7, v68
	s_waitcnt vmcnt(28)
	v_mul_f32_e32 v66, v66, v69
	v_mul_f32_e32 v66, 0x3e16c740, v66
	ds_write_b32 v7, v66 offset:1056
	s_waitcnt vmcnt(26)
	v_mul_f32_e32 v74, v74, v76
	v_mul_f32_e32 v74, 0x3e16c740, v74
	ds_write_b32 v7, v74 offset:2112
	s_waitcnt vmcnt(24)
	v_mul_f32_e32 v80, v80, v67
	v_mul_f32_e32 v80, 0x3e16c740, v80
	ds_write_b32 v7, v80 offset:3168
	s_waitcnt vmcnt(22)
	v_mul_f32_e32 v64, v64, v86
	v_mul_f32_e32 v64, 0x3e16c740, v64
	ds_write_b32 v71, v64
	s_waitcnt vmcnt(20)
	v_mul_f32_e32 v84, v84, v65
	v_mul_f32_e32 v84, 0x3e16c740, v84
	ds_write_b32 v71, v84 offset:1056
	s_waitcnt vmcnt(18)
	v_mul_f32_e32 v72, v72, v90
	v_mul_f32_e32 v72, 0x3e16c740, v72
	ds_write_b32 v71, v72 offset:2112
	s_waitcnt vmcnt(16)
	v_mul_f32_e32 v94, v94, v73
	v_mul_f32_e32 v94, 0x3e16c740, v94
	ds_write_b32 v71, v94 offset:3168
	s_waitcnt vmcnt(14)
	v_mul_f32_e32 v77, v77, v82
	v_mul_f32_e32 v77, 0x3e16c740, v77
	ds_write_b32 v75, v77
	s_waitcnt vmcnt(12)
	v_mul_f32_e32 v96, v96, v81
	v_mul_f32_e32 v96, 0x3e16c740, v96
	ds_write_b32 v75, v96 offset:1056
	s_waitcnt vmcnt(10)
	v_mul_f32_e32 v85, v85, v88
	v_mul_f32_e32 v85, 0x3e16c740, v85
	ds_write_b32 v75, v85 offset:2112
	s_waitcnt vmcnt(8)
	v_mul_f32_e32 v102, v102, v83
	v_mul_f32_e32 v102, 0x3e16c740, v102
	ds_write_b32 v75, v102 offset:3168
	s_waitcnt vmcnt(6)
	v_mul_f32_e32 v78, v78, v106
	v_mul_f32_e32 v78, 0x3e16c740, v78
	ds_write_b32 v87, v78
	s_waitcnt vmcnt(4)
	v_mul_f32_e32 v104, v104, v79
	v_mul_f32_e32 v104, 0x3e16c740, v104
	ds_write_b32 v87, v104 offset:1056
	s_waitcnt vmcnt(2)
	v_mul_f32_e32 v91, v91, v98
	v_mul_f32_e32 v91, 0x3e16c740, v91
	ds_write_b32 v87, v91 offset:2112
	s_waitcnt vmcnt(0)
	v_mul_f32_e32 v112, v112, v89
	v_mul_f32_e32 v112, 0x3e16c740, v112
	ds_write_b32 v87, v112 offset:3168
	v_mov_b32_e32 v0, v112
	v_mov_b32_e32 v1, v113
	v_mov_b32_e32 v4, v110
	v_mov_b32_e32 v5, v111
	v_mov_b32_e32 v7, v95
	v_mov_b32_e32 v9, v89
	v_mov_b32_e32 v10, v92
	v_mov_b32_e32 v11, v93
	v_mov_b32_e32 v12, v108
	v_mov_b32_e32 v13, v109
	s_branch .LBB0_87

.LBB0_91:
	s_lshl_b32 s59, s31, 3
	s_lshl_b32 s35, s30, 3
	v_mov_b32_e32 v65, v25
	v_or_b32_e32 v64, s59, v6
	s_add_i32 s64, s59, 16
	v_or_b32_e32 v66, s35, v5
	s_add_i32 s61, s35, 16
	s_add_i32 s65, s35, 32
	s_add_i32 s66, s59, 32
	s_add_i32 s35, s35, 48
	v_mov_b32_e32 v69, v1
	v_add_u32_e32 v68, s2, v64
	v_mov_b32_e32 v71, v27
	v_or_b32_e32 v70, s64, v6
	s_add_i32 s59, s59, 48
	v_mov_b32_e32 v73, v9
	v_add_u32_e32 v72, s3, v66
	v_mov_b32_e32 v74, v64
	v_or_b32_e32 v75, s61, v5
	v_mov_b32_e32 v64, v70
	v_or_b32_e32 v65, s65, v5
	v_or_b32_e32 v67, s66, v6
	v_or_b32_e32 v70, s35, v5
	v_mov_b32_e32 v77, v69
	v_mul_lo_u32 v76, v68, s56
	v_mov_b32_e32 v69, v13
	v_add_u32_e32 v68, s2, v64
	v_mov_b32_e32 v78, v72
	v_mov_b32_e32 v79, v77
	v_or_b32_e32 v71, s59, v6
	v_mov_b32_e32 v73, v79
	v_mul_lo_u32 v72, v78, s56
	v_mov_b32_e32 v79, v11
	v_add_u32_e32 v78, s3, v75
	v_add_u32_e32 v80, s2, v67
	v_mov_b32_e32 v83, v19
	v_add_u32_e32 v82, s3, v65
	v_mov_b32_e32 v85, v23
	v_add_u32_e32 v84, s3, v70
	v_lshl_add_u64 v[86:87], v[76:77], 2, v[2:3]
	v_mov_b32_e32 v89, v77
	v_mul_lo_u32 v88, v68, s56
	v_mov_b32_e32 v76, v78
	v_mov_b32_e32 v77, v89
	v_add_u32_e32 v78, s2, v71
	v_lshl_add_u64 v[90:91], v[72:73], 2, v[2:3]
	v_mov_b32_e32 v73, v77
	v_mul_lo_u32 v72, v76, s56
	v_mov_b32_e32 v77, v69
	v_mul_lo_u32 v76, v82, s56
	v_mov_b32_e32 v69, v83
	v_mul_lo_u32 v68, v84, s56
	v_lshl_add_u64 v[82:83], v[88:89], 2, v[2:3]
	v_mov_b32_e32 v85, v89
	v_mul_lo_u32 v84, v80, s56
	v_mov_b32_e32 v88, v76
	v_mov_b32_e32 v89, v85
	v_mov_b32_e32 v76, v68
	v_mov_b32_e32 v77, v85
	v_lshl_add_u64 v[68:69], v[72:73], 2, v[2:3]
	global_load_dword v72, v[86:87], off nt
	global_load_dword v73, v[90:91], off nt
	global_load_dword v79, v[82:83], off nt
	global_load_dword v80, v[68:69], off nt
	v_lshl_add_u64 v[92:93], v[84:85], 2, v[2:3]
	v_mov_b32_e32 v91, v85
	v_mul_lo_u32 v90, v78, s56
	v_lshl_add_u64 v[84:85], v[88:89], 2, v[2:3]
	v_lshl_add_u64 v[88:89], v[76:77], 2, v[2:3]
	v_lshl_add_u64 v[76:77], v[90:91], 2, v[2:3]
	v_mov_b32_e32 v69, v91
	global_load_dword v68, v[92:93], off nt
	global_load_dword v81, v[84:85], off nt
	global_load_dword v78, v[76:77], off nt
	global_load_dword v90, v[88:89], off nt
	s_add_i32 s31, s31, 8
	s_add_i32 s30, s30, 8
	s_add_i32 s34, s34, -8
	v_mad_u64_u32 v[94:95], s[64:65], v74, s41, v[4:5]
	s_cmp_lg_u32 s34, 0
	v_mad_u64_u32 v[92:93], s[64:65], v66, s41, v[4:5]
	v_mad_u64_u32 v[76:77], s[64:65], v64, s41, v[4:5]
	v_mad_u64_u32 v[84:85], s[64:65], v75, s41, v[4:5]
	v_mad_u64_u32 v[88:89], s[64:65], v67, s41, v[4:5]
	v_mad_u64_u32 v[86:87], s[64:65], v65, s41, v[4:5]
	v_mad_u64_u32 v[82:83], s[64:65], v71, s41, v[4:5]
	v_mad_u64_u32 v[74:75], s[64:65], v70, s41, v[4:5]
	s_lshl_b32 s59, s31, 3
	s_lshl_b32 s35, s30, 3
	v_mov_b32_e32 v65, v83
	v_or_b32_e32 v64, s59, v6
	s_add_i32 s64, s59, 16
	v_or_b32_e32 v83, s35, v5
	s_add_i32 s61, s35, 16
	s_add_i32 s65, s35, 32
	s_add_i32 s66, s59, 32
	s_add_i32 s35, s35, 48
	v_mov_b32_e32 v97, v69
	v_add_u32_e32 v96, s2, v64
	v_mov_b32_e32 v99, v75
	v_or_b32_e32 v98, s64, v6
	s_add_i32 s59, s59, 48
	v_mov_b32_e32 v101, v95
	v_add_u32_e32 v100, s3, v83
	v_mov_b32_e32 v102, v64
	v_or_b32_e32 v103, s61, v5
	v_mov_b32_e32 v64, v98
	v_or_b32_e32 v65, s65, v5
	v_or_b32_e32 v66, s66, v6
	v_or_b32_e32 v67, s35, v5
	v_mov_b32_e32 v99, v97
	v_mul_lo_u32 v98, v96, s56
	v_mov_b32_e32 v97, v77
	v_add_u32_e32 v96, s2, v64
	v_mov_b32_e32 v104, v100
	v_mov_b32_e32 v105, v99
	v_or_b32_e32 v69, s59, v6
	v_mov_b32_e32 v71, v105
	v_mul_lo_u32 v70, v104, s56
	v_mov_b32_e32 v101, v93
	v_add_u32_e32 v100, s3, v103
	v_add_u32_e32 v75, s2, v66
	v_mov_b32_e32 v105, v85
	v_add_u32_e32 v104, s3, v65
	v_mov_b32_e32 v107, v87
	v_add_u32_e32 v106, s3, v67
	v_lshl_add_u64 v[108:109], v[98:99], 2, v[2:3]
	v_mov_b32_e32 v111, v99
	v_mul_lo_u32 v110, v96, s56
	v_mov_b32_e32 v98, v100
	v_mov_b32_e32 v99, v111
	v_add_u32_e32 v77, s2, v69
	v_lshl_add_u64 v[100:101], v[70:71], 2, v[2:3]
	v_mov_b32_e32 v71, v99
	v_mul_lo_u32 v70, v98, s56
	v_mov_b32_e32 v99, v97
	v_mul_lo_u32 v98, v104, s56
	v_mov_b32_e32 v97, v105
	v_mul_lo_u32 v96, v106, s56
	v_lshl_add_u64 v[104:105], v[110:111], 2, v[2:3]
	v_mov_b32_e32 v107, v111
	v_mul_lo_u32 v106, v75, s56
	v_mov_b32_e32 v110, v98
	v_mov_b32_e32 v111, v107
	v_mov_b32_e32 v98, v96
	v_mov_b32_e32 v99, v107
	v_lshl_add_u64 v[96:97], v[70:71], 2, v[2:3]
	global_load_dword v70, v[108:109], off nt
	global_load_dword v71, v[100:101], off nt
	global_load_dword v75, v[104:105], off nt
	global_load_dword v85, v[96:97], off nt
	v_lshl_add_u64 v[112:113], v[106:107], 2, v[2:3]
	v_mov_b32_e32 v101, v107
	v_mul_lo_u32 v100, v77, s56
	v_lshl_add_u64 v[106:107], v[110:111], 2, v[2:3]
	v_lshl_add_u64 v[110:111], v[98:99], 2, v[2:3]
	v_lshl_add_u64 v[98:99], v[100:101], 2, v[2:3]
	v_mov_b32_e32 v97, v101
	global_load_dword v96, v[112:113], off nt
	global_load_dword v87, v[106:107], off nt
	global_load_dword v77, v[98:99], off nt
	global_load_dword v89, v[110:111], off nt
	s_add_i32 s31, s31, 8
	s_add_i32 s30, s30, 8
	s_add_i32 s34, s34, -8
	v_mad_u64_u32 v[100:101], s[64:65], v102, s41, v[4:5]
	s_cmp_lg_u32 s34, 0
	v_mad_u64_u32 v[112:113], s[64:65], v83, s41, v[4:5]
	v_mad_u64_u32 v[98:99], s[64:65], v64, s41, v[4:5]
	v_mad_u64_u32 v[106:107], s[64:65], v103, s41, v[4:5]
	v_mad_u64_u32 v[110:111], s[64:65], v66, s41, v[4:5]
	v_mad_u64_u32 v[108:109], s[64:65], v65, s41, v[4:5]
	v_mad_u64_u32 v[104:105], s[64:65], v69, s41, v[4:5]
	v_mad_u64_u32 v[102:103], s[64:65], v67, s41, v[4:5]
	s_waitcnt vmcnt(15)
	ds_write_b32 v94, v72
	s_waitcnt vmcnt(14)
	ds_write_b32 v92, v73
	s_waitcnt vmcnt(13)
	ds_write_b32 v76, v79
	s_waitcnt vmcnt(12)
	ds_write_b32 v84, v80
	s_waitcnt vmcnt(11)
	ds_write_b32 v88, v68
	s_waitcnt vmcnt(10)
	ds_write_b32 v86, v81
	s_waitcnt vmcnt(9)
	ds_write_b32 v82, v78
	s_waitcnt vmcnt(8)
	ds_write_b32 v74, v90
	s_waitcnt vmcnt(7)
	ds_write_b32 v100, v70
	s_waitcnt vmcnt(6)
	ds_write_b32 v112, v71
	s_waitcnt vmcnt(5)
	ds_write_b32 v98, v75
	s_waitcnt vmcnt(4)
	ds_write_b32 v106, v85
	s_waitcnt vmcnt(3)
	ds_write_b32 v110, v96
	s_waitcnt vmcnt(2)
	ds_write_b32 v108, v87
	s_waitcnt vmcnt(1)
	ds_write_b32 v104, v77
	s_waitcnt vmcnt(0)
	ds_write_b32 v102, v89
	v_mov_b32_e32 v0, v96
	v_mov_b32_e32 v1, v97
	v_mov_b32_e32 v8, v100
	v_mov_b32_e32 v9, v101
	v_mov_b32_e32 v10, v112
	v_mov_b32_e32 v11, v113
	v_mov_b32_e32 v12, v98
	v_mov_b32_e32 v13, v99
	v_mov_b32_e32 v17, v83
	v_mov_b32_e32 v18, v106
	v_mov_b32_e32 v19, v107
	v_mov_b32_e32 v20, v110
	v_mov_b32_e32 v21, v111
	v_mov_b32_e32 v22, v108
	v_mov_b32_e32 v23, v109
	v_mov_b32_e32 v24, v104
	v_mov_b32_e32 v25, v105
	v_mov_b32_e32 v26, v102
	v_mov_b32_e32 v27, v103
	v_mov_b32_e32 v28, v66
	v_mov_b32_e32 v29, v67
	v_mov_b32_e32 v30, v69
	v_mov_b32_e32 v31, v70
	v_mov_b32_e32 v32, v87
	v_mov_b32_e32 v33, v71
	v_mov_b32_e32 v34, v75
	v_mov_b32_e32 v35, v85
	v_mov_b32_e32 v36, v77
	v_mov_b32_e32 v37, v89
	v_lshlrev_b32_sdwa v0, v14, v7 dst_sel:DWORD dst_unused:UNUSED_PAD src0_sel:DWORD src1_sel:BYTE_0
	v_and_b32_e32 v0, 0x7e, v0
	v_lshrrev_b32_sdwa v3, v15, v7 dst_sel:DWORD dst_unused:UNUSED_PAD src0_sel:DWORD src1_sel:BYTE_0
	v_or_b32_e32 v2, s20, v3
	v_or_b32_e32 v8, s2, v0
	v_mul_u32_u24_e32 v0, 0x84, v0
	v_lshlrev_b32_e32 v3, 2, v3
	v_add3_u32 v17, s36, v0, v3
	s_waitcnt lgkmcnt(0)
	s_barrier
	ds_read2_b32 v[4:5], v17 offset0:33 offset1:37
	ds_read2_b32 v[6:7], v17 offset1:4
	v_lshlrev_b32_e32 v0, 1, v8
	v_mov_b32_e32 v3, v1
	ds_read2_b32 v[10:11], v17 offset0:8 offset1:12
	ds_read2_b32 v[12:13], v17 offset0:41 offset1:45
	v_lshl_add_u64 v[8:9], s[14:15], 0, v[0:1]
	v_lshlrev_b64 v[18:19], 11, v[2:3]
	s_waitcnt lgkmcnt(2)
	v_cvt_pk_bf16_f32 v0, v6, v4
	v_lshl_add_u64 v[18:19], v[8:9], 0, v[18:19]
	global_store_dword v[18:19], v0, off
	v_or_b32_e32 v0, 4, v2
	v_lshlrev_b64 v[22:23], 11, v[0:1]
	s_waitcnt lgkmcnt(0)
	v_cvt_pk_bf16_f32 v3, v10, v12
	ds_read2_b32 v[18:19], v17 offset0:16 offset1:20
	ds_read2_b32 v[20:21], v17 offset0:49 offset1:53
	v_lshl_add_u64 v[22:23], v[8:9], 0, v[22:23]
	global_store_dword v[22:23], v3, off
	ds_read2_b32 v[22:23], v17 offset0:24 offset1:28
	ds_read2_b32 v[24:25], v17 offset0:57 offset1:61
	v_or_b32_e32 v0, 8, v2
	v_lshlrev_b64 v[26:27], 11, v[0:1]
	s_waitcnt lgkmcnt(2)
	v_cvt_pk_bf16_f32 v3, v18, v20
	v_lshl_add_u64 v[26:27], v[8:9], 0, v[26:27]
	v_or_b32_e32 v0, 12, v2
	global_store_dword v[26:27], v3, off
	v_lshlrev_b64 v[26:27], 11, v[0:1]
	s_waitcnt lgkmcnt(0)
	v_cvt_pk_bf16_f32 v3, v22, v24
	v_lshl_add_u64 v[26:27], v[8:9], 0, v[26:27]
	v_or_b32_e32 v0, 16, v2
	global_store_dword v[26:27], v3, off
	v_cvt_pk_bf16_f32 v3, v7, v5
	v_lshlrev_b64 v[4:5], 11, v[0:1]
	v_lshl_add_u64 v[4:5], v[8:9], 0, v[4:5]
	v_or_b32_e32 v0, 20, v2
	global_store_dword v[4:5], v3, off
	v_lshlrev_b64 v[4:5], 11, v[0:1]
	v_cvt_pk_bf16_f32 v3, v11, v13
	v_lshl_add_u64 v[4:5], v[8:9], 0, v[4:5]
	v_or_b32_e32 v0, 24, v2
	global_store_dword v[4:5], v3, off
	v_lshlrev_b64 v[4:5], 11, v[0:1]
	v_cvt_pk_bf16_f32 v3, v19, v21
	v_lshl_add_u64 v[4:5], v[8:9], 0, v[4:5]
	v_or_b32_e32 v0, 28, v2
	global_store_dword v[4:5], v3, off
	v_lshlrev_b64 v[2:3], 11, v[0:1]
	v_cvt_pk_bf16_f32 v4, v23, v25
	v_lshl_add_u64 v[2:3], v[8:9], 0, v[2:3]
	global_store_dword v[2:3], v4, off
	s_barrier

.LBB0_97:
	s_lshl_b32 s61, s35, 3
	s_lshl_b32 s59, s34, 3
	v_mov_b32_e32 v65, v25
	v_or_b32_e32 v64, s61, v6
	s_add_i32 s65, s61, 16
	v_or_b32_e32 v66, s59, v5
	s_add_i32 s64, s59, 16
	s_add_i32 s66, s59, 32
	s_add_i32 s67, s61, 32
	s_add_i32 s59, s59, 48
	v_mov_b32_e32 v69, v1
	v_add_u32_e32 v68, s2, v64
	v_mov_b32_e32 v71, v27
	v_or_b32_e32 v70, s65, v6
	s_add_i32 s61, s61, 48
	v_mov_b32_e32 v73, v9
	v_add_u32_e32 v72, s3, v66
	v_mov_b32_e32 v74, v64
	v_or_b32_e32 v75, s64, v5
	v_mov_b32_e32 v64, v70
	v_or_b32_e32 v65, s66, v5
	v_or_b32_e32 v67, s67, v6
	v_or_b32_e32 v70, s59, v5
	v_mov_b32_e32 v77, v69
	v_mul_lo_u32 v76, v68, s56
	v_mov_b32_e32 v69, v13
	v_add_u32_e32 v68, s2, v64
	v_mov_b32_e32 v78, v72
	v_mov_b32_e32 v79, v77
	v_or_b32_e32 v71, s61, v6
	v_mov_b32_e32 v73, v79
	v_mul_lo_u32 v72, v78, s56
	v_mov_b32_e32 v79, v11
	v_add_u32_e32 v78, s3, v75
	v_add_u32_e32 v80, s2, v67
	v_mov_b32_e32 v83, v19
	v_add_u32_e32 v82, s3, v65
	v_mov_b32_e32 v85, v23
	v_add_u32_e32 v84, s3, v70
	v_lshl_add_u64 v[86:87], v[76:77], 2, v[2:3]
	v_mov_b32_e32 v89, v77
	v_mul_lo_u32 v88, v68, s56
	v_mov_b32_e32 v76, v78
	v_mov_b32_e32 v77, v89
	v_add_u32_e32 v78, s2, v71
	v_lshl_add_u64 v[90:91], v[72:73], 2, v[2:3]
	v_mov_b32_e32 v73, v77
	v_mul_lo_u32 v72, v76, s56
	v_mov_b32_e32 v77, v69
	v_mul_lo_u32 v76, v82, s56
	v_mov_b32_e32 v69, v83
	v_mul_lo_u32 v68, v84, s56
	v_lshl_add_u64 v[82:83], v[88:89], 2, v[2:3]
	v_mov_b32_e32 v85, v89
	v_mul_lo_u32 v84, v80, s56
	v_mov_b32_e32 v88, v76
	v_mov_b32_e32 v89, v85
	v_mov_b32_e32 v76, v68
	v_mov_b32_e32 v77, v85
	v_lshl_add_u64 v[68:69], v[72:73], 2, v[2:3]
	global_load_dword v72, v[86:87], off nt
	global_load_dword v73, v[90:91], off nt
	global_load_dword v79, v[82:83], off nt
	global_load_dword v80, v[68:69], off nt
	v_lshl_add_u64 v[92:93], v[84:85], 2, v[2:3]
	v_mov_b32_e32 v91, v85
	v_mul_lo_u32 v90, v78, s56
	v_lshl_add_u64 v[84:85], v[88:89], 2, v[2:3]
	v_lshl_add_u64 v[88:89], v[76:77], 2, v[2:3]
	v_lshl_add_u64 v[76:77], v[90:91], 2, v[2:3]
	v_mov_b32_e32 v69, v91
	global_load_dword v68, v[92:93], off nt
	global_load_dword v81, v[84:85], off nt
	global_load_dword v78, v[76:77], off nt
	global_load_dword v90, v[88:89], off nt
	s_add_i32 s35, s35, 8
	s_add_i32 s34, s34, 8
	s_add_i32 s58, s58, -8
	v_mad_u64_u32 v[94:95], s[64:65], v74, s41, v[4:5]
	s_cmp_lg_u32 s58, 0
	v_mad_u64_u32 v[92:93], s[64:65], v66, s41, v[4:5]
	v_mad_u64_u32 v[76:77], s[64:65], v64, s41, v[4:5]
	v_mad_u64_u32 v[84:85], s[64:65], v75, s41, v[4:5]
	v_mad_u64_u32 v[88:89], s[64:65], v67, s41, v[4:5]
	v_mad_u64_u32 v[86:87], s[64:65], v65, s41, v[4:5]
	v_mad_u64_u32 v[82:83], s[64:65], v71, s41, v[4:5]
	v_mad_u64_u32 v[74:75], s[64:65], v70, s41, v[4:5]
	s_lshl_b32 s61, s35, 3
	s_lshl_b32 s59, s34, 3
	v_mov_b32_e32 v65, v83
	v_or_b32_e32 v64, s61, v6
	s_add_i32 s65, s61, 16
	v_or_b32_e32 v83, s59, v5
	s_add_i32 s64, s59, 16
	s_add_i32 s66, s59, 32
	s_add_i32 s67, s61, 32
	s_add_i32 s59, s59, 48
	v_mov_b32_e32 v97, v69
	v_add_u32_e32 v96, s2, v64
	v_mov_b32_e32 v99, v75
	v_or_b32_e32 v98, s65, v6
	s_add_i32 s61, s61, 48
	v_mov_b32_e32 v101, v95
	v_add_u32_e32 v100, s3, v83
	v_mov_b32_e32 v102, v64
	v_or_b32_e32 v103, s64, v5
	v_mov_b32_e32 v64, v98
	v_or_b32_e32 v65, s66, v5
	v_or_b32_e32 v66, s67, v6
	v_or_b32_e32 v67, s59, v5
	v_mov_b32_e32 v99, v97
	v_mul_lo_u32 v98, v96, s56
	v_mov_b32_e32 v97, v77
	v_add_u32_e32 v96, s2, v64
	v_mov_b32_e32 v104, v100
	v_mov_b32_e32 v105, v99
	v_or_b32_e32 v69, s61, v6
	v_mov_b32_e32 v71, v105
	v_mul_lo_u32 v70, v104, s56
	v_mov_b32_e32 v101, v93
	v_add_u32_e32 v100, s3, v103
	v_add_u32_e32 v75, s2, v66
	v_mov_b32_e32 v105, v85
	v_add_u32_e32 v104, s3, v65
	v_mov_b32_e32 v107, v87
	v_add_u32_e32 v106, s3, v67
	v_lshl_add_u64 v[108:109], v[98:99], 2, v[2:3]
	v_mov_b32_e32 v111, v99
	v_mul_lo_u32 v110, v96, s56
	v_mov_b32_e32 v98, v100
	v_mov_b32_e32 v99, v111
	v_add_u32_e32 v77, s2, v69
	v_lshl_add_u64 v[100:101], v[70:71], 2, v[2:3]
	v_mov_b32_e32 v71, v99
	v_mul_lo_u32 v70, v98, s56
	v_mov_b32_e32 v99, v97
	v_mul_lo_u32 v98, v104, s56
	v_mov_b32_e32 v97, v105
	v_mul_lo_u32 v96, v106, s56
	v_lshl_add_u64 v[104:105], v[110:111], 2, v[2:3]
	v_mov_b32_e32 v107, v111
	v_mul_lo_u32 v106, v75, s56
	v_mov_b32_e32 v110, v98
	v_mov_b32_e32 v111, v107
	v_mov_b32_e32 v98, v96
	v_mov_b32_e32 v99, v107
	v_lshl_add_u64 v[96:97], v[70:71], 2, v[2:3]
	global_load_dword v70, v[108:109], off nt
	global_load_dword v71, v[100:101], off nt
	global_load_dword v75, v[104:105], off nt
	global_load_dword v85, v[96:97], off nt
	v_lshl_add_u64 v[112:113], v[106:107], 2, v[2:3]
	v_mov_b32_e32 v101, v107
	v_mul_lo_u32 v100, v77, s56
	v_lshl_add_u64 v[106:107], v[110:111], 2, v[2:3]
	v_lshl_add_u64 v[110:111], v[98:99], 2, v[2:3]
	v_lshl_add_u64 v[98:99], v[100:101], 2, v[2:3]
	v_mov_b32_e32 v97, v101
	global_load_dword v96, v[112:113], off nt
	global_load_dword v87, v[106:107], off nt
	global_load_dword v77, v[98:99], off nt
	global_load_dword v89, v[110:111], off nt
	s_add_i32 s35, s35, 8
	s_add_i32 s34, s34, 8
	s_add_i32 s58, s58, -8
	v_mad_u64_u32 v[100:101], s[64:65], v102, s41, v[4:5]
	s_cmp_lg_u32 s58, 0
	v_mad_u64_u32 v[112:113], s[64:65], v83, s41, v[4:5]
	v_mad_u64_u32 v[98:99], s[64:65], v64, s41, v[4:5]
	v_mad_u64_u32 v[106:107], s[64:65], v103, s41, v[4:5]
	v_mad_u64_u32 v[110:111], s[64:65], v66, s41, v[4:5]
	v_mad_u64_u32 v[108:109], s[64:65], v65, s41, v[4:5]
	v_mad_u64_u32 v[104:105], s[64:65], v69, s41, v[4:5]
	v_mad_u64_u32 v[102:103], s[64:65], v67, s41, v[4:5]
	s_waitcnt vmcnt(15)
	ds_write_b32 v94, v72
	s_waitcnt vmcnt(14)
	ds_write_b32 v92, v73
	s_waitcnt vmcnt(13)
	ds_write_b32 v76, v79
	s_waitcnt vmcnt(12)
	ds_write_b32 v84, v80
	s_waitcnt vmcnt(11)
	ds_write_b32 v88, v68
	s_waitcnt vmcnt(10)
	ds_write_b32 v86, v81
	s_waitcnt vmcnt(9)
	ds_write_b32 v82, v78
	s_waitcnt vmcnt(8)
	ds_write_b32 v74, v90
	s_waitcnt vmcnt(7)
	ds_write_b32 v100, v70
	s_waitcnt vmcnt(6)
	ds_write_b32 v112, v71
	s_waitcnt vmcnt(5)
	ds_write_b32 v98, v75
	s_waitcnt vmcnt(4)
	ds_write_b32 v106, v85
	s_waitcnt vmcnt(3)
	ds_write_b32 v110, v96
	s_waitcnt vmcnt(2)
	ds_write_b32 v108, v87
	s_waitcnt vmcnt(1)
	ds_write_b32 v104, v77
	s_waitcnt vmcnt(0)
	ds_write_b32 v102, v89
	v_mov_b32_e32 v0, v96
	v_mov_b32_e32 v1, v97
	v_mov_b32_e32 v8, v100
	v_mov_b32_e32 v9, v101
	v_mov_b32_e32 v10, v112
	v_mov_b32_e32 v11, v113
	v_mov_b32_e32 v12, v98
	v_mov_b32_e32 v13, v99
	v_mov_b32_e32 v17, v83
	v_mov_b32_e32 v18, v106
	v_mov_b32_e32 v19, v107
	v_mov_b32_e32 v20, v110
	v_mov_b32_e32 v21, v111
	v_mov_b32_e32 v22, v108
	v_mov_b32_e32 v23, v109
	v_mov_b32_e32 v24, v104
	v_mov_b32_e32 v25, v105
	v_mov_b32_e32 v26, v102
	v_mov_b32_e32 v27, v103
	v_mov_b32_e32 v28, v66
	v_mov_b32_e32 v29, v67
	v_mov_b32_e32 v30, v69
	v_mov_b32_e32 v31, v70
	v_mov_b32_e32 v32, v87
	v_mov_b32_e32 v33, v71
	v_mov_b32_e32 v34, v75
	v_mov_b32_e32 v35, v85
	v_mov_b32_e32 v36, v77
	v_mov_b32_e32 v37, v89
	v_lshlrev_b32_sdwa v0, v14, v7 dst_sel:DWORD dst_unused:UNUSED_PAD src0_sel:DWORD src1_sel:BYTE_0
	v_and_b32_e32 v0, 0x7e, v0
	v_lshrrev_b32_sdwa v3, v15, v7 dst_sel:DWORD dst_unused:UNUSED_PAD src0_sel:DWORD src1_sel:BYTE_0
	v_or_b32_e32 v2, s31, v3
	v_or_b32_e32 v8, s2, v0
	v_mul_u32_u24_e32 v0, 0x84, v0
	v_lshlrev_b32_e32 v3, 2, v3
	v_add3_u32 v17, s36, v0, v3
	s_waitcnt lgkmcnt(0)
	s_barrier
	ds_read2_b32 v[4:5], v17 offset0:33 offset1:37
	ds_read2_b32 v[6:7], v17 offset1:4
	v_lshlrev_b32_e32 v0, 1, v8
	v_ashrrev_i32_e32 v3, 31, v2
	v_lshl_add_u64 v[8:9], s[16:17], 0, v[0:1]
	ds_read2_b32 v[10:11], v17 offset0:8 offset1:12
	v_lshlrev_b64 v[12:13], 11, v[2:3]
	ds_read2_b32 v[18:19], v17 offset0:41 offset1:45
	s_waitcnt lgkmcnt(2)
	v_cvt_pk_bf16_f32 v0, v6, v4
	v_lshl_add_u64 v[12:13], v[8:9], 0, v[12:13]
	global_store_dword v[12:13], v0, off
	v_or_b32_e32 v12, 4, v2
	v_ashrrev_i32_e32 v13, 31, v12
	v_lshlrev_b64 v[12:13], 11, v[12:13]
	ds_read2_b32 v[20:21], v17 offset0:16 offset1:20
	ds_read2_b32 v[22:23], v17 offset0:49 offset1:53
	s_waitcnt lgkmcnt(2)
	v_cvt_pk_bf16_f32 v0, v10, v18
	v_lshl_add_u64 v[12:13], v[8:9], 0, v[12:13]
	global_store_dword v[12:13], v0, off
	v_or_b32_e32 v12, 8, v2
	v_ashrrev_i32_e32 v13, 31, v12
	v_lshlrev_b64 v[12:13], 11, v[12:13]
	ds_read2_b32 v[24:25], v17 offset0:24 offset1:28
	ds_read2_b32 v[26:27], v17 offset0:57 offset1:61
	s_waitcnt lgkmcnt(2)
	v_cvt_pk_bf16_f32 v0, v20, v22
	v_lshl_add_u64 v[12:13], v[8:9], 0, v[12:13]
	global_store_dword v[12:13], v0, off
	v_or_b32_e32 v12, 12, v2
	v_ashrrev_i32_e32 v13, 31, v12
	v_lshlrev_b64 v[12:13], 11, v[12:13]
	s_waitcnt lgkmcnt(0)
	v_cvt_pk_bf16_f32 v0, v24, v26
	v_lshl_add_u64 v[12:13], v[8:9], 0, v[12:13]
	global_store_dword v[12:13], v0, off
	v_or_b32_e32 v12, 16, v2
	v_ashrrev_i32_e32 v13, 31, v12
	v_cvt_pk_bf16_f32 v0, v7, v5
	v_lshlrev_b64 v[4:5], 11, v[12:13]
	v_lshl_add_u64 v[4:5], v[8:9], 0, v[4:5]
	global_store_dword v[4:5], v0, off
	v_or_b32_e32 v4, 20, v2
	v_ashrrev_i32_e32 v5, 31, v4
	v_lshlrev_b64 v[4:5], 11, v[4:5]
	v_cvt_pk_bf16_f32 v0, v11, v19
	v_lshl_add_u64 v[4:5], v[8:9], 0, v[4:5]
	global_store_dword v[4:5], v0, off
	v_or_b32_e32 v4, 24, v2
	v_ashrrev_i32_e32 v5, 31, v4
	v_or_b32_e32 v2, 28, v2
	v_lshlrev_b64 v[4:5], 11, v[4:5]
	v_ashrrev_i32_e32 v3, 31, v2
	v_cvt_pk_bf16_f32 v0, v21, v23
	v_lshl_add_u64 v[4:5], v[8:9], 0, v[4:5]
	v_lshlrev_b64 v[2:3], 11, v[2:3]
	global_store_dword v[4:5], v0, off
	v_cvt_pk_bf16_f32 v0, v25, v27
	v_lshl_add_u64 v[2:3], v[8:9], 0, v[2:3]
	s_mov_b64 s[2:3], 0
	global_store_dword v[2:3], v0, off
	s_barrier

.LBB0_101:
	s_lshl_b32 s35, s30, 3
	s_lshl_b32 s34, s20, 3
	v_mov_b32_e32 v65, v25
	v_or_b32_e32 v64, s35, v6
	s_add_i32 s59, s35, 16
	v_or_b32_e32 v66, s34, v5
	s_add_i32 s58, s34, 16
	s_add_i32 s61, s34, 32
	s_add_i32 s64, s35, 32
	s_add_i32 s34, s34, 48
	v_mov_b32_e32 v69, v1
	v_add_u32_e32 v68, s2, v64
	v_mov_b32_e32 v71, v27
	v_or_b32_e32 v70, s59, v6
	s_add_i32 s35, s35, 48
	v_mov_b32_e32 v73, v9
	v_add_u32_e32 v72, s3, v66
	v_mov_b32_e32 v74, v64
	v_or_b32_e32 v75, s58, v5
	v_mov_b32_e32 v64, v70
	v_or_b32_e32 v65, s61, v5
	v_or_b32_e32 v67, s64, v6
	v_or_b32_e32 v70, s34, v5
	v_mov_b32_e32 v77, v69
	v_mul_lo_u32 v76, v68, s56
	v_mov_b32_e32 v69, v13
	v_add_u32_e32 v68, s2, v64
	v_mov_b32_e32 v78, v72
	v_mov_b32_e32 v79, v77
	v_or_b32_e32 v71, s35, v6
	v_mov_b32_e32 v73, v79
	v_mul_lo_u32 v72, v78, s56
	v_mov_b32_e32 v79, v11
	v_add_u32_e32 v78, s3, v75
	v_add_u32_e32 v80, s2, v67
	v_mov_b32_e32 v83, v19
	v_add_u32_e32 v82, s3, v65
	v_mov_b32_e32 v85, v23
	v_add_u32_e32 v84, s3, v70
	v_lshl_add_u64 v[86:87], v[76:77], 2, v[2:3]
	v_mov_b32_e32 v89, v77
	v_mul_lo_u32 v88, v68, s56
	v_mov_b32_e32 v76, v78
	v_mov_b32_e32 v77, v89
	v_add_u32_e32 v78, s2, v71
	v_lshl_add_u64 v[90:91], v[72:73], 2, v[2:3]
	v_mov_b32_e32 v73, v77
	v_mul_lo_u32 v72, v76, s56
	v_mov_b32_e32 v77, v69
	v_mul_lo_u32 v76, v82, s56
	v_mov_b32_e32 v69, v83
	v_mul_lo_u32 v68, v84, s56
	v_lshl_add_u64 v[82:83], v[88:89], 2, v[2:3]
	v_mov_b32_e32 v85, v89
	v_mul_lo_u32 v84, v80, s56
	v_mov_b32_e32 v88, v76
	v_mov_b32_e32 v89, v85
	v_mov_b32_e32 v76, v68
	v_mov_b32_e32 v77, v85
	v_lshl_add_u64 v[68:69], v[72:73], 2, v[2:3]
	global_load_dword v72, v[86:87], off nt
	global_load_dword v73, v[90:91], off nt
	global_load_dword v79, v[82:83], off nt
	global_load_dword v80, v[68:69], off nt
	v_lshl_add_u64 v[92:93], v[84:85], 2, v[2:3]
	v_mov_b32_e32 v91, v85
	v_mul_lo_u32 v90, v78, s56
	v_lshl_add_u64 v[84:85], v[88:89], 2, v[2:3]
	v_lshl_add_u64 v[88:89], v[76:77], 2, v[2:3]
	v_lshl_add_u64 v[76:77], v[90:91], 2, v[2:3]
	v_mov_b32_e32 v69, v91
	global_load_dword v68, v[92:93], off nt
	global_load_dword v81, v[84:85], off nt
	global_load_dword v78, v[76:77], off nt
	global_load_dword v90, v[88:89], off nt
	s_add_i32 s30, s30, 8
	s_add_i32 s20, s20, 8
	s_add_i32 s31, s31, -8
	v_mad_u64_u32 v[94:95], s[34:35], v74, s41, v[4:5]
	s_cmp_lg_u32 s31, 0
	v_mad_u64_u32 v[92:93], s[34:35], v66, s41, v[4:5]
	v_mad_u64_u32 v[76:77], s[34:35], v64, s41, v[4:5]
	v_mad_u64_u32 v[84:85], s[34:35], v75, s41, v[4:5]
	v_mad_u64_u32 v[88:89], s[34:35], v67, s41, v[4:5]
	v_mad_u64_u32 v[86:87], s[34:35], v65, s41, v[4:5]
	v_mad_u64_u32 v[82:83], s[34:35], v71, s41, v[4:5]
	v_mad_u64_u32 v[74:75], s[34:35], v70, s41, v[4:5]
	s_lshl_b32 s35, s30, 3
	s_lshl_b32 s34, s20, 3
	v_mov_b32_e32 v65, v83
	v_or_b32_e32 v64, s35, v6
	s_add_i32 s59, s35, 16
	v_or_b32_e32 v83, s34, v5
	s_add_i32 s58, s34, 16
	s_add_i32 s61, s34, 32
	s_add_i32 s64, s35, 32
	s_add_i32 s34, s34, 48
	v_mov_b32_e32 v97, v69
	v_add_u32_e32 v96, s2, v64
	v_mov_b32_e32 v99, v75
	v_or_b32_e32 v98, s59, v6
	s_add_i32 s35, s35, 48
	v_mov_b32_e32 v101, v95
	v_add_u32_e32 v100, s3, v83
	v_mov_b32_e32 v102, v64
	v_or_b32_e32 v103, s58, v5
	v_mov_b32_e32 v64, v98
	v_or_b32_e32 v65, s61, v5
	v_or_b32_e32 v66, s64, v6
	v_or_b32_e32 v67, s34, v5
	v_mov_b32_e32 v99, v97
	v_mul_lo_u32 v98, v96, s56
	v_mov_b32_e32 v97, v77
	v_add_u32_e32 v96, s2, v64
	v_mov_b32_e32 v104, v100
	v_mov_b32_e32 v105, v99
	v_or_b32_e32 v69, s35, v6
	v_mov_b32_e32 v71, v105
	v_mul_lo_u32 v70, v104, s56
	v_mov_b32_e32 v101, v93
	v_add_u32_e32 v100, s3, v103
	v_add_u32_e32 v75, s2, v66
	v_mov_b32_e32 v105, v85
	v_add_u32_e32 v104, s3, v65
	v_mov_b32_e32 v107, v87
	v_add_u32_e32 v106, s3, v67
	v_lshl_add_u64 v[108:109], v[98:99], 2, v[2:3]
	v_mov_b32_e32 v111, v99
	v_mul_lo_u32 v110, v96, s56
	v_mov_b32_e32 v98, v100
	v_mov_b32_e32 v99, v111
	v_add_u32_e32 v77, s2, v69
	v_lshl_add_u64 v[100:101], v[70:71], 2, v[2:3]
	v_mov_b32_e32 v71, v99
	v_mul_lo_u32 v70, v98, s56
	v_mov_b32_e32 v99, v97
	v_mul_lo_u32 v98, v104, s56
	v_mov_b32_e32 v97, v105
	v_mul_lo_u32 v96, v106, s56
	v_lshl_add_u64 v[104:105], v[110:111], 2, v[2:3]
	v_mov_b32_e32 v107, v111
	v_mul_lo_u32 v106, v75, s56
	v_mov_b32_e32 v110, v98
	v_mov_b32_e32 v111, v107
	v_mov_b32_e32 v98, v96
	v_mov_b32_e32 v99, v107
	v_lshl_add_u64 v[96:97], v[70:71], 2, v[2:3]
	global_load_dword v70, v[108:109], off nt
	global_load_dword v71, v[100:101], off nt
	global_load_dword v75, v[104:105], off nt
	global_load_dword v85, v[96:97], off nt
	v_lshl_add_u64 v[112:113], v[106:107], 2, v[2:3]
	v_mov_b32_e32 v101, v107
	v_mul_lo_u32 v100, v77, s56
	v_lshl_add_u64 v[106:107], v[110:111], 2, v[2:3]
	v_lshl_add_u64 v[110:111], v[98:99], 2, v[2:3]
	v_lshl_add_u64 v[98:99], v[100:101], 2, v[2:3]
	v_mov_b32_e32 v97, v101
	global_load_dword v96, v[112:113], off nt
	global_load_dword v87, v[106:107], off nt
	global_load_dword v77, v[98:99], off nt
	global_load_dword v89, v[110:111], off nt
	s_add_i32 s30, s30, 8
	s_add_i32 s20, s20, 8
	s_add_i32 s31, s31, -8
	v_mad_u64_u32 v[100:101], s[34:35], v102, s41, v[4:5]
	s_cmp_lg_u32 s31, 0
	v_mad_u64_u32 v[112:113], s[34:35], v83, s41, v[4:5]
	v_mad_u64_u32 v[98:99], s[34:35], v64, s41, v[4:5]
	v_mad_u64_u32 v[106:107], s[34:35], v103, s41, v[4:5]
	v_mad_u64_u32 v[110:111], s[34:35], v66, s41, v[4:5]
	v_mad_u64_u32 v[108:109], s[34:35], v65, s41, v[4:5]
	v_mad_u64_u32 v[104:105], s[34:35], v69, s41, v[4:5]
	v_mad_u64_u32 v[102:103], s[34:35], v67, s41, v[4:5]
	s_waitcnt vmcnt(15)
	ds_write_b32 v94, v72
	s_waitcnt vmcnt(14)
	ds_write_b32 v92, v73
	s_waitcnt vmcnt(13)
	ds_write_b32 v76, v79
	s_waitcnt vmcnt(12)
	ds_write_b32 v84, v80
	s_waitcnt vmcnt(11)
	ds_write_b32 v88, v68
	s_waitcnt vmcnt(10)
	ds_write_b32 v86, v81
	s_waitcnt vmcnt(9)
	ds_write_b32 v82, v78
	s_waitcnt vmcnt(8)
	ds_write_b32 v74, v90
	s_waitcnt vmcnt(7)
	ds_write_b32 v100, v70
	s_waitcnt vmcnt(6)
	ds_write_b32 v112, v71
	s_waitcnt vmcnt(5)
	ds_write_b32 v98, v75
	s_waitcnt vmcnt(4)
	ds_write_b32 v106, v85
	s_waitcnt vmcnt(3)
	ds_write_b32 v110, v96
	s_waitcnt vmcnt(2)
	ds_write_b32 v108, v87
	s_waitcnt vmcnt(1)
	ds_write_b32 v104, v77
	s_waitcnt vmcnt(0)
	ds_write_b32 v102, v89
	v_mov_b32_e32 v0, v96
	v_mov_b32_e32 v1, v97
	v_mov_b32_e32 v8, v100
	v_mov_b32_e32 v9, v101
	v_mov_b32_e32 v10, v112
	v_mov_b32_e32 v11, v113
	v_mov_b32_e32 v12, v98
	v_mov_b32_e32 v13, v99
	v_mov_b32_e32 v17, v83
	v_mov_b32_e32 v18, v106
	v_mov_b32_e32 v19, v107
	v_mov_b32_e32 v20, v110
	v_mov_b32_e32 v21, v111
	v_mov_b32_e32 v22, v108
	v_mov_b32_e32 v23, v109
	v_mov_b32_e32 v24, v104
	v_mov_b32_e32 v25, v105
	v_mov_b32_e32 v26, v102
	v_mov_b32_e32 v27, v103
	v_mov_b32_e32 v28, v66
	v_mov_b32_e32 v29, v67
	v_mov_b32_e32 v30, v69
	v_mov_b32_e32 v31, v70
	v_mov_b32_e32 v32, v87
	v_mov_b32_e32 v33, v71
	v_mov_b32_e32 v34, v75
	v_mov_b32_e32 v35, v85
	v_mov_b32_e32 v36, v77
	v_mov_b32_e32 v37, v89
	v_lshlrev_b32_sdwa v0, v14, v7 dst_sel:DWORD dst_unused:UNUSED_PAD src0_sel:DWORD src1_sel:BYTE_0
	v_and_b32_e32 v0, 0x7e, v0
	v_lshrrev_b32_sdwa v10, v15, v7 dst_sel:DWORD dst_unused:UNUSED_PAD src0_sel:DWORD src1_sel:BYTE_0
	v_mul_u32_u24_e32 v2, 0x84, v0
	v_lshlrev_b32_e32 v3, 2, v10
	v_add3_u32 v12, s36, v2, v3
	s_waitcnt lgkmcnt(0)
	s_barrier
	ds_read2_b32 v[2:3], v12 offset0:33 offset1:37
	ds_read2_b32 v[4:5], v12 offset1:4
	v_or_b32_e32 v0, s2, v0
	v_lshlrev_b32_e32 v0, 1, v0
	v_lshl_add_u64 v[6:7], s[18:19], 0, v[0:1]
	v_lshlrev_b32_e32 v0, 11, v10
	s_waitcnt lgkmcnt(0)
	v_cvt_pk_bf16_f32 v2, v4, v2
	v_lshl_add_u64 v[10:11], v[6:7], 0, v[0:1]
	ds_read2_b32 v[8:9], v12 offset0:8 offset1:12
	global_store_dword v[10:11], v2, off
	v_cvt_pk_bf16_f32 v10, v5, v3
	ds_read2_b32 v[2:3], v12 offset0:41 offset1:45
	v_or_b32_e32 v4, 0x2000, v0
	v_mov_b32_e32 v5, v1
	v_lshl_add_u64 v[4:5], v[6:7], 0, v[4:5]
	global_store_dword v[4:5], v10, off
	v_or_b32_e32 v4, 0x4000, v0
	v_mov_b32_e32 v5, v1
	s_waitcnt lgkmcnt(0)
	v_cvt_pk_bf16_f32 v2, v8, v2
	v_lshl_add_u64 v[4:5], v[6:7], 0, v[4:5]
	global_store_dword v[4:5], v2, off
	v_cvt_pk_bf16_f32 v10, v9, v3
	ds_read2_b32 v[2:3], v12 offset0:16 offset1:20
	ds_read2_b32 v[4:5], v12 offset0:49 offset1:53
	v_or_b32_e32 v8, 0x6000, v0
	v_mov_b32_e32 v9, v1
	v_lshl_add_u64 v[8:9], v[6:7], 0, v[8:9]
	global_store_dword v[8:9], v10, off
	v_or_b32_e32 v8, 0x8000, v0
	v_mov_b32_e32 v9, v1
	s_waitcnt lgkmcnt(0)
	v_cvt_pk_bf16_f32 v2, v2, v4
	v_lshl_add_u64 v[8:9], v[6:7], 0, v[8:9]
	global_store_dword v[8:9], v2, off
	v_cvt_pk_bf16_f32 v10, v3, v5
	ds_read2_b32 v[2:3], v12 offset0:57 offset1:61
	ds_read2_b32 v[4:5], v12 offset0:24 offset1:28
	v_or_b32_e32 v8, 0xa000, v0
	v_mov_b32_e32 v9, v1
	v_lshl_add_u64 v[8:9], v[6:7], 0, v[8:9]
	global_store_dword v[8:9], v10, off
	v_or_b32_e32 v8, 0xc000, v0
	v_mov_b32_e32 v9, v1
	s_waitcnt lgkmcnt(0)
	v_cvt_pk_bf16_f32 v2, v4, v2
	v_lshl_add_u64 v[8:9], v[6:7], 0, v[8:9]
	v_or_b32_e32 v0, 0xe000, v0
	global_store_dword v[8:9], v2, off
	v_cvt_pk_bf16_f32 v4, v5, v3
	v_lshl_add_u64 v[2:3], v[6:7], 0, v[0:1]
	global_store_dword v[2:3], v4, off
	s_barrier
	s_branch .LBB0_32

.LBB0_805:
	s_lshl_b32 s71, s35, 3
	s_lshl_b32 s37, s34, 3
	v_or_b32_e32 v64, s71, v6
	v_or_b32_e32 v65, s37, v5
	v_mov_b32_e32 v67, v1
	v_add_lshl_u32 v66, v64, s2, 10
	v_mov_b32_e32 v69, v9
	v_add_lshl_u32 v68, v65, s3, 10
	v_lshl_add_u64 v[70:71], v[66:67], 2, v[2:3]
	v_mov_b32_e32 v72, v68
	v_mov_b32_e32 v73, v67
	v_lshl_add_u64 v[68:69], v[72:73], 2, v[2:3]
	v_mov_b32_e32 v73, v67
	global_load_dword v72, v[70:71], off nt
	global_load_dword v66, v[68:69], off nt
	v_mad_u64_u32 v[74:75], s[72:73], v64, s64, v[4:5]
	v_mad_u64_u32 v[68:69], s[72:73], v65, s64, v[4:5]
	s_add_i32 s73, s71, 16
	s_add_i32 s72, s37, 16
	v_or_b32_e32 v67, s73, v6
	v_or_b32_e32 v64, s72, v5
	v_mov_b32_e32 v70, v74
	v_mov_b32_e32 v71, v73
	s_add_i32 s35, s35, 8
	s_add_i32 s34, s34, 8
	s_add_i32 s36, s36, -8
	v_mov_b32_e32 v75, v73
	v_add_lshl_u32 v74, v67, s2, 10
	v_mov_b32_e32 v77, v71
	v_add_lshl_u32 v76, v64, s3, 10
	v_lshl_add_u64 v[78:79], v[74:75], 2, v[2:3]
	v_lshl_add_u64 v[80:81], v[76:77], 2, v[2:3]
	v_mov_b32_e32 v77, v75
	global_load_dword v76, v[78:79], off nt
	global_load_dword v65, v[80:81], off nt
	v_mad_u64_u32 v[74:75], s[72:73], v67, s64, v[4:5]
	v_mad_u64_u32 v[80:81], s[72:73], v64, s64, v[4:5]
	s_add_i32 s73, s71, 32
	s_add_i32 s72, s37, 32
	v_or_b32_e32 v69, s73, v6
	v_or_b32_e32 v67, s72, v5
	v_mov_b32_e32 v78, v74
	v_mov_b32_e32 v79, v77
	s_add_i32 s71, s71, 48
	s_add_i32 s37, s37, 48
	s_cmp_lg_u32 s36, 0
	v_mov_b32_e32 v75, v77
	v_add_lshl_u32 v74, v69, s2, 10
	v_mov_b32_e32 v83, v79
	v_add_lshl_u32 v82, v67, s3, 10
	v_lshl_add_u64 v[84:85], v[74:75], 2, v[2:3]
	v_lshl_add_u64 v[86:87], v[82:83], 2, v[2:3]
	v_mov_b32_e32 v83, v75
	global_load_dword v82, v[84:85], off nt
	global_load_dword v64, v[86:87], off nt
	v_mad_u64_u32 v[74:75], s[72:73], v69, s64, v[4:5]
	v_or_b32_e32 v71, s71, v6
	v_mad_u64_u32 v[86:87], s[72:73], v67, s64, v[4:5]
	v_or_b32_e32 v69, s37, v5
	v_mov_b32_e32 v84, v74
	v_mov_b32_e32 v85, v83
	v_mov_b32_e32 v75, v83
	v_add_lshl_u32 v74, v71, s2, 10
	v_mov_b32_e32 v89, v85
	v_add_lshl_u32 v88, v69, s3, 10
	v_lshl_add_u64 v[90:91], v[74:75], 2, v[2:3]
	v_lshl_add_u64 v[92:93], v[88:89], 2, v[2:3]
	v_mov_b32_e32 v89, v75
	global_load_dword v88, v[90:91], off nt
	global_load_dword v67, v[92:93], off nt
	v_mad_u64_u32 v[74:75], s[72:73], v71, s64, v[4:5]
	v_mad_u64_u32 v[92:93], s[72:73], v69, s64, v[4:5]
	s_lshl_b32 s71, s35, 3
	s_lshl_b32 s37, s34, 3
	v_or_b32_e32 v73, s71, v6
	v_or_b32_e32 v71, s37, v5
	v_mov_b32_e32 v91, v89
	v_add_lshl_u32 v90, v73, s2, 10
	v_mov_b32_e32 v95, v75
	v_add_lshl_u32 v94, v71, s3, 10
	v_lshl_add_u64 v[96:97], v[90:91], 2, v[2:3]
	v_mov_b32_e32 v98, v94
	v_mov_b32_e32 v99, v91
	v_lshl_add_u64 v[94:95], v[98:99], 2, v[2:3]
	v_mov_b32_e32 v99, v91
	global_load_dword v98, v[96:97], off nt
	global_load_dword v69, v[94:95], off nt
	v_mad_u64_u32 v[90:91], s[72:73], v73, s64, v[4:5]
	v_mad_u64_u32 v[94:95], s[72:73], v71, s64, v[4:5]
	s_add_i32 s73, s71, 16
	s_add_i32 s72, s37, 16
	v_or_b32_e32 v75, s73, v6
	v_or_b32_e32 v73, s72, v5
	v_mov_b32_e32 v96, v90
	v_mov_b32_e32 v97, v99
	s_add_i32 s35, s35, 8
	s_add_i32 s34, s34, 8
	s_add_i32 s36, s36, -8
	v_mov_b32_e32 v91, v99
	v_add_lshl_u32 v90, v75, s2, 10
	v_mov_b32_e32 v101, v97
	v_add_lshl_u32 v100, v73, s3, 10
	v_lshl_add_u64 v[102:103], v[90:91], 2, v[2:3]
	v_lshl_add_u64 v[104:105], v[100:101], 2, v[2:3]
	v_mov_b32_e32 v101, v91
	global_load_dword v100, v[102:103], off nt
	global_load_dword v71, v[104:105], off nt
	v_mad_u64_u32 v[90:91], s[72:73], v75, s64, v[4:5]
	v_mad_u64_u32 v[104:105], s[72:73], v73, s64, v[4:5]
	s_add_i32 s73, s71, 32
	s_add_i32 s72, s37, 32
	v_or_b32_e32 v77, s73, v6
	v_or_b32_e32 v75, s72, v5
	v_mov_b32_e32 v102, v90
	v_mov_b32_e32 v103, v101
	s_add_i32 s71, s71, 48
	s_add_i32 s37, s37, 48
	s_cmp_lg_u32 s36, 0
	v_mov_b32_e32 v91, v101
	v_add_lshl_u32 v90, v77, s2, 10
	v_mov_b32_e32 v107, v103
	v_add_lshl_u32 v106, v75, s3, 10
	v_lshl_add_u64 v[108:109], v[90:91], 2, v[2:3]
	v_lshl_add_u64 v[110:111], v[106:107], 2, v[2:3]
	v_mov_b32_e32 v107, v91
	global_load_dword v106, v[108:109], off nt
	global_load_dword v73, v[110:111], off nt
	v_mad_u64_u32 v[90:91], s[72:73], v77, s64, v[4:5]
	v_or_b32_e32 v79, s71, v6
	v_mad_u64_u32 v[110:111], s[72:73], v75, s64, v[4:5]
	v_or_b32_e32 v77, s37, v5
	v_mov_b32_e32 v108, v90
	v_mov_b32_e32 v109, v107
	v_mov_b32_e32 v91, v107
	v_add_lshl_u32 v90, v79, s2, 10
	v_mov_b32_e32 v113, v109
	v_add_lshl_u32 v112, v77, s3, 10
	v_lshl_add_u64 v[114:115], v[90:91], 2, v[2:3]
	v_lshl_add_u64 v[116:117], v[112:113], 2, v[2:3]
	v_mov_b32_e32 v113, v91
	global_load_dword v112, v[114:115], off nt
	global_load_dword v75, v[116:117], off nt
	v_mad_u64_u32 v[90:91], s[72:73], v79, s64, v[4:5]
	v_mad_u64_u32 v[116:117], s[72:73], v77, s64, v[4:5]
	s_waitcnt vmcnt(15)
	ds_write_b32 v70, v72
	s_waitcnt vmcnt(14)
	ds_write_b32 v68, v66
	s_waitcnt vmcnt(13)
	ds_write_b32 v78, v76
	s_waitcnt vmcnt(12)
	ds_write_b32 v80, v65
	s_waitcnt vmcnt(11)
	ds_write_b32 v84, v82
	s_waitcnt vmcnt(10)
	ds_write_b32 v86, v64
	s_waitcnt vmcnt(9)
	ds_write_b32 v74, v88
	s_waitcnt vmcnt(8)
	ds_write_b32 v92, v67
	s_waitcnt vmcnt(7)
	ds_write_b32 v96, v98
	s_waitcnt vmcnt(6)
	ds_write_b32 v94, v69
	s_waitcnt vmcnt(5)
	ds_write_b32 v102, v100
	s_waitcnt vmcnt(4)
	ds_write_b32 v104, v71
	s_waitcnt vmcnt(3)
	ds_write_b32 v108, v106
	s_waitcnt vmcnt(2)
	ds_write_b32 v110, v73
	s_waitcnt vmcnt(1)
	ds_write_b32 v90, v112
	s_waitcnt vmcnt(0)
	ds_write_b32 v116, v75
	v_mov_b32_e32 v0, v112
	v_mov_b32_e32 v1, v113
	v_mov_b32_e32 v8, v90
	v_mov_b32_e32 v9, v91
	v_mov_b32_e32 v10, v116
	v_mov_b32_e32 v11, v117
	v_mov_b32_e32 v12, v77
	v_mov_b32_e32 v13, v79
	v_mov_b32_e32 v18, v75
	v_lshlrev_b32_sdwa v0, v14, v7 dst_sel:DWORD dst_unused:UNUSED_PAD src0_sel:DWORD src1_sel:BYTE_0
	v_and_b32_e32 v0, 0x7e, v0
	v_lshrrev_b32_sdwa v8, v15, v7 dst_sel:DWORD dst_unused:UNUSED_PAD src0_sel:DWORD src1_sel:BYTE_0
	v_or_b32_e32 v6, s2, v0
	v_mul_u32_u24_e32 v0, 0x84, v0
	v_lshlrev_b32_e32 v2, 2, v8
	v_add3_u32 v12, s47, v0, v2
	s_waitcnt lgkmcnt(0)
	s_barrier
	ds_read2_b32 v[2:3], v12 offset0:33 offset1:37
	ds_read2_b32 v[4:5], v12 offset1:4
	v_lshlrev_b32_e32 v0, 1, v6
	v_lshl_add_u64 v[6:7], s[4:5], 0, v[0:1]
	v_or_b32_e32 v0, s20, v8
	v_lshlrev_b64 v[10:11], 11, v[0:1]
	s_waitcnt lgkmcnt(0)
	v_cvt_pk_bf16_f32 v2, v4, v2
	v_lshl_add_u64 v[10:11], v[6:7], 0, v[10:11]
	ds_read2_b32 v[8:9], v12 offset0:8 offset1:12
	global_store_dword v[10:11], v2, off
	v_or_b32_e32 v10, 4, v0
	v_mov_b32_e32 v11, v1
	v_cvt_pk_bf16_f32 v13, v5, v3
	ds_read2_b32 v[4:5], v12 offset0:41 offset1:45
	v_lshlrev_b64 v[2:3], 11, v[10:11]
	v_lshl_add_u64 v[2:3], v[6:7], 0, v[2:3]
	global_store_dword v[2:3], v13, off
	v_or_b32_e32 v2, 8, v0
	v_mov_b32_e32 v3, v1
	v_lshlrev_b64 v[2:3], 11, v[2:3]
	s_waitcnt lgkmcnt(0)
	v_cvt_pk_bf16_f32 v4, v8, v4
	v_lshl_add_u64 v[2:3], v[6:7], 0, v[2:3]
	global_store_dword v[2:3], v4, off
	v_or_b32_e32 v2, 12, v0
	v_mov_b32_e32 v3, v1
	v_cvt_pk_bf16_f32 v10, v9, v5
	ds_read2_b32 v[4:5], v12 offset0:16 offset1:20
	ds_read2_b32 v[8:9], v12 offset0:49 offset1:53
	v_lshlrev_b64 v[2:3], 11, v[2:3]
	v_lshl_add_u64 v[2:3], v[6:7], 0, v[2:3]
	global_store_dword v[2:3], v10, off
	v_or_b32_e32 v2, 16, v0
	v_mov_b32_e32 v3, v1
	v_lshlrev_b64 v[2:3], 11, v[2:3]
	s_waitcnt lgkmcnt(0)
	v_cvt_pk_bf16_f32 v4, v4, v8
	v_lshl_add_u64 v[2:3], v[6:7], 0, v[2:3]
	global_store_dword v[2:3], v4, off
	v_or_b32_e32 v2, 20, v0
	v_mov_b32_e32 v3, v1
	v_cvt_pk_bf16_f32 v10, v5, v9
	ds_read2_b32 v[4:5], v12 offset0:57 offset1:61
	ds_read2_b32 v[8:9], v12 offset0:24 offset1:28
	v_lshlrev_b64 v[2:3], 11, v[2:3]
	v_lshl_add_u64 v[2:3], v[6:7], 0, v[2:3]
	global_store_dword v[2:3], v10, off
	v_or_b32_e32 v2, 24, v0
	v_mov_b32_e32 v3, v1
	v_lshlrev_b64 v[2:3], 11, v[2:3]
	s_waitcnt lgkmcnt(0)
	v_cvt_pk_bf16_f32 v4, v8, v4
	v_lshl_add_u64 v[2:3], v[6:7], 0, v[2:3]
	v_or_b32_e32 v0, 28, v0
	global_store_dword v[2:3], v4, off
	v_lshlrev_b64 v[2:3], 11, v[0:1]
	v_cvt_pk_bf16_f32 v4, v9, v5
	v_lshl_add_u64 v[2:3], v[6:7], 0, v[2:3]
	global_store_dword v[2:3], v4, off
	s_barrier
	s_mov_b64 s[2:3], 0

.LBB0_809:
	s_lshl_b32 s74, s35, 3
	s_lshl_b32 s71, s34, 3
	v_or_b32_e32 v64, s74, v6
	v_or_b32_e32 v65, s71, v5
	v_mov_b32_e32 v67, v1
	v_add_lshl_u32 v66, v64, s3, 10
	v_mov_b32_e32 v69, v9
	v_add_lshl_u32 v68, v65, s36, 10
	v_lshl_add_u64 v[70:71], v[66:67], 2, v[2:3]
	v_mov_b32_e32 v72, v68
	v_mov_b32_e32 v73, v67
	v_lshl_add_u64 v[68:69], v[72:73], 2, v[2:3]
	v_mov_b32_e32 v73, v67
	global_load_dword v72, v[70:71], off nt
	global_load_dword v66, v[68:69], off nt
	v_mad_u64_u32 v[74:75], s[72:73], v64, s64, v[4:5]
	v_mad_u64_u32 v[68:69], s[72:73], v65, s64, v[4:5]
	s_add_i32 s73, s74, 16
	s_add_i32 s72, s71, 16
	v_or_b32_e32 v67, s73, v6
	v_or_b32_e32 v64, s72, v5
	v_mov_b32_e32 v70, v74
	v_mov_b32_e32 v71, v73
	s_add_i32 s35, s35, 8
	s_add_i32 s34, s34, 8
	s_add_i32 s37, s37, -8
	v_mov_b32_e32 v75, v73
	v_add_lshl_u32 v74, v67, s3, 10
	v_mov_b32_e32 v77, v71
	v_add_lshl_u32 v76, v64, s36, 10
	v_lshl_add_u64 v[78:79], v[74:75], 2, v[2:3]
	v_lshl_add_u64 v[80:81], v[76:77], 2, v[2:3]
	v_mov_b32_e32 v77, v75
	global_load_dword v76, v[78:79], off nt
	global_load_dword v65, v[80:81], off nt
	v_mad_u64_u32 v[74:75], s[72:73], v67, s64, v[4:5]
	v_mad_u64_u32 v[80:81], s[72:73], v64, s64, v[4:5]
	s_add_i32 s73, s74, 32
	s_add_i32 s72, s71, 32
	v_or_b32_e32 v69, s73, v6
	v_or_b32_e32 v67, s72, v5
	v_mov_b32_e32 v78, v74
	v_mov_b32_e32 v79, v77
	s_add_i32 s74, s74, 48
	s_add_i32 s71, s71, 48
	s_cmp_lg_u32 s37, 0
	v_mov_b32_e32 v75, v77
	v_add_lshl_u32 v74, v69, s3, 10
	v_mov_b32_e32 v83, v79
	v_add_lshl_u32 v82, v67, s36, 10
	v_lshl_add_u64 v[84:85], v[74:75], 2, v[2:3]
	v_lshl_add_u64 v[86:87], v[82:83], 2, v[2:3]
	v_mov_b32_e32 v83, v75
	global_load_dword v82, v[84:85], off nt
	global_load_dword v64, v[86:87], off nt
	v_mad_u64_u32 v[74:75], s[72:73], v69, s64, v[4:5]
	v_or_b32_e32 v71, s74, v6
	v_mad_u64_u32 v[86:87], s[72:73], v67, s64, v[4:5]
	v_or_b32_e32 v69, s71, v5
	v_mov_b32_e32 v84, v74
	v_mov_b32_e32 v85, v83
	v_mov_b32_e32 v75, v83
	v_add_lshl_u32 v74, v71, s3, 10
	v_mov_b32_e32 v89, v85
	v_add_lshl_u32 v88, v69, s36, 10
	v_lshl_add_u64 v[90:91], v[74:75], 2, v[2:3]
	v_lshl_add_u64 v[92:93], v[88:89], 2, v[2:3]
	v_mov_b32_e32 v89, v75
	global_load_dword v88, v[90:91], off nt
	global_load_dword v67, v[92:93], off nt
	v_mad_u64_u32 v[74:75], s[72:73], v71, s64, v[4:5]
	v_mad_u64_u32 v[92:93], s[72:73], v69, s64, v[4:5]
	s_lshl_b32 s74, s35, 3
	s_lshl_b32 s71, s34, 3
	v_or_b32_e32 v73, s74, v6
	v_or_b32_e32 v71, s71, v5
	v_mov_b32_e32 v91, v89
	v_add_lshl_u32 v90, v73, s3, 10
	v_mov_b32_e32 v95, v75
	v_add_lshl_u32 v94, v71, s36, 10
	v_lshl_add_u64 v[96:97], v[90:91], 2, v[2:3]
	v_mov_b32_e32 v98, v94
	v_mov_b32_e32 v99, v91
	v_lshl_add_u64 v[94:95], v[98:99], 2, v[2:3]
	v_mov_b32_e32 v99, v91
	global_load_dword v98, v[96:97], off nt
	global_load_dword v69, v[94:95], off nt
	v_mad_u64_u32 v[90:91], s[72:73], v73, s64, v[4:5]
	v_mad_u64_u32 v[94:95], s[72:73], v71, s64, v[4:5]
	s_add_i32 s73, s74, 16
	s_add_i32 s72, s71, 16
	v_or_b32_e32 v75, s73, v6
	v_or_b32_e32 v73, s72, v5
	v_mov_b32_e32 v96, v90
	v_mov_b32_e32 v97, v99
	s_add_i32 s35, s35, 8
	s_add_i32 s34, s34, 8
	s_add_i32 s37, s37, -8
	v_mov_b32_e32 v91, v99
	v_add_lshl_u32 v90, v75, s3, 10
	v_mov_b32_e32 v101, v97
	v_add_lshl_u32 v100, v73, s36, 10
	v_lshl_add_u64 v[102:103], v[90:91], 2, v[2:3]
	v_lshl_add_u64 v[104:105], v[100:101], 2, v[2:3]
	v_mov_b32_e32 v101, v91
	global_load_dword v100, v[102:103], off nt
	global_load_dword v71, v[104:105], off nt
	v_mad_u64_u32 v[90:91], s[72:73], v75, s64, v[4:5]
	v_mad_u64_u32 v[104:105], s[72:73], v73, s64, v[4:5]
	s_add_i32 s73, s74, 32
	s_add_i32 s72, s71, 32
	v_or_b32_e32 v77, s73, v6
	v_or_b32_e32 v75, s72, v5
	v_mov_b32_e32 v102, v90
	v_mov_b32_e32 v103, v101
	s_add_i32 s74, s74, 48
	s_add_i32 s71, s71, 48
	s_cmp_lg_u32 s37, 0
	v_mov_b32_e32 v91, v101
	v_add_lshl_u32 v90, v77, s3, 10
	v_mov_b32_e32 v107, v103
	v_add_lshl_u32 v106, v75, s36, 10
	v_lshl_add_u64 v[108:109], v[90:91], 2, v[2:3]
	v_lshl_add_u64 v[110:111], v[106:107], 2, v[2:3]
	v_mov_b32_e32 v107, v91
	global_load_dword v106, v[108:109], off nt
	global_load_dword v73, v[110:111], off nt
	v_mad_u64_u32 v[90:91], s[72:73], v77, s64, v[4:5]
	v_or_b32_e32 v79, s74, v6
	v_mad_u64_u32 v[110:111], s[72:73], v75, s64, v[4:5]
	v_or_b32_e32 v77, s71, v5
	v_mov_b32_e32 v108, v90
	v_mov_b32_e32 v109, v107
	v_mov_b32_e32 v91, v107
	v_add_lshl_u32 v90, v79, s3, 10
	v_mov_b32_e32 v113, v109
	v_add_lshl_u32 v112, v77, s36, 10
	v_lshl_add_u64 v[114:115], v[90:91], 2, v[2:3]
	v_lshl_add_u64 v[116:117], v[112:113], 2, v[2:3]
	v_mov_b32_e32 v113, v91
	global_load_dword v112, v[114:115], off nt
	global_load_dword v75, v[116:117], off nt
	v_mad_u64_u32 v[90:91], s[72:73], v79, s64, v[4:5]
	v_mad_u64_u32 v[116:117], s[72:73], v77, s64, v[4:5]
	s_waitcnt vmcnt(15)
	ds_write_b32 v70, v72
	s_waitcnt vmcnt(14)
	ds_write_b32 v68, v66
	s_waitcnt vmcnt(13)
	ds_write_b32 v78, v76
	s_waitcnt vmcnt(12)
	ds_write_b32 v80, v65
	s_waitcnt vmcnt(11)
	ds_write_b32 v84, v82
	s_waitcnt vmcnt(10)
	ds_write_b32 v86, v64
	s_waitcnt vmcnt(9)
	ds_write_b32 v74, v88
	s_waitcnt vmcnt(8)
	ds_write_b32 v92, v67
	s_waitcnt vmcnt(7)
	ds_write_b32 v96, v98
	s_waitcnt vmcnt(6)
	ds_write_b32 v94, v69
	s_waitcnt vmcnt(5)
	ds_write_b32 v102, v100
	s_waitcnt vmcnt(4)
	ds_write_b32 v104, v71
	s_waitcnt vmcnt(3)
	ds_write_b32 v108, v106
	s_waitcnt vmcnt(2)
	ds_write_b32 v110, v73
	s_waitcnt vmcnt(1)
	ds_write_b32 v90, v112
	s_waitcnt vmcnt(0)
	ds_write_b32 v116, v75
	v_mov_b32_e32 v0, v112
	v_mov_b32_e32 v1, v113
	v_mov_b32_e32 v8, v90
	v_mov_b32_e32 v9, v91
	v_mov_b32_e32 v10, v116
	v_mov_b32_e32 v11, v117
	v_mov_b32_e32 v12, v77
	v_mov_b32_e32 v13, v79
	v_mov_b32_e32 v18, v75
	v_lshlrev_b32_sdwa v0, v14, v7 dst_sel:DWORD dst_unused:UNUSED_PAD src0_sel:DWORD src1_sel:BYTE_0
	v_and_b32_e32 v0, 0x7e, v0
	v_lshrrev_b32_sdwa v2, v15, v7 dst_sel:DWORD dst_unused:UNUSED_PAD src0_sel:DWORD src1_sel:BYTE_0
	v_or_b32_e32 v12, s2, v2
	v_or_b32_e32 v6, s3, v0
	v_mul_u32_u24_e32 v0, 0x84, v0
	v_lshlrev_b32_e32 v2, 2, v2
	v_add3_u32 v22, s47, v0, v2
	s_waitcnt lgkmcnt(0)
	s_barrier
	ds_read2_b32 v[2:3], v22 offset0:33 offset1:37
	ds_read2_b32 v[4:5], v22 offset1:4
	s_lshl_b64 s[34:35], s[20:21], 20
	s_add_u32 s34, s41, s34
	s_addc_u32 s35, s42, s35
	v_lshlrev_b32_e32 v0, 1, v6
	v_lshl_add_u64 v[6:7], s[34:35], 0, v[0:1]
	ds_read2_b32 v[8:9], v22 offset0:8 offset1:12
	ds_read2_b32 v[10:11], v22 offset0:41 offset1:45
	v_lshlrev_b32_e32 v0, 10, v12
	s_waitcnt lgkmcnt(2)
	v_cvt_pk_bf16_f32 v2, v4, v2
	v_lshl_add_u64 v[6:7], v[6:7], 0, v[0:1]
	global_store_dword v[6:7], v2, off
	ds_read2_b32 v[12:13], v22 offset0:16 offset1:20
	ds_read2_b32 v[18:19], v22 offset0:49 offset1:53
	ds_read2_b32 v[20:21], v22 offset0:24 offset1:28
	ds_read2_b32 v[22:23], v22 offset0:57 offset1:61
	s_movk_i32 s2, 0x2000
	v_add_co_u32_e32 v24, vcc, s2, v6
	s_waitcnt lgkmcnt(4)
	v_cvt_pk_bf16_f32 v0, v8, v10
	v_addc_co_u32_e32 v25, vcc, 0, v7, vcc
	global_store_dword v[24:25], v0, off offset:-4096
	s_waitcnt lgkmcnt(2)
	v_cvt_pk_bf16_f32 v0, v12, v18
	s_movk_i32 s2, 0x4000
	global_store_dword v[24:25], v0, off
	v_add_co_u32_e32 v24, vcc, s2, v6
	s_waitcnt lgkmcnt(0)
	v_cvt_pk_bf16_f32 v0, v20, v22
	v_addc_co_u32_e32 v25, vcc, 0, v7, vcc
	s_movk_i32 s2, 0x5000
	global_store_dword v[24:25], v0, off offset:-4096
	v_cvt_pk_bf16_f32 v0, v5, v3
	v_add_co_u32_e32 v2, vcc, s2, v6
	global_store_dword v[24:25], v0, off
	v_cvt_pk_bf16_f32 v0, v9, v11
	v_addc_co_u32_e32 v3, vcc, 0, v7, vcc
	global_store_dword v[2:3], v0, off
	v_add_co_u32_e32 v2, vcc, 0x6000, v6
	v_cvt_pk_bf16_f32 v0, v13, v19
	s_nop 0
	v_addc_co_u32_e32 v3, vcc, 0, v7, vcc
	global_store_dword v[2:3], v0, off
	v_add_co_u32_e32 v2, vcc, 0x7000, v6
	v_cvt_pk_bf16_f32 v0, v21, v23
	s_nop 0
	v_addc_co_u32_e32 v3, vcc, 0, v7, vcc
	global_store_dword v[2:3], v0, off
	s_barrier

.LBB0_812:
	s_andn2_b64 vcc, exec, s[2:3]
	s_cbranch_vccnz .LBB0_824
	s_bfe_u32 s20, s51, 0x1a0005
	v_mov_b32_e32 v18, v198
	s_lshl_b64 s[2:3], s[20:21], 7
	s_bfe_u32 s20, s59, 0x10007
	v_mov_b32_e32 v5, v1
	v_bfe_u32 v10, v18, 5, 3
	v_lshlrev_b32_e32 v2, 2, v18
	v_lshl_or_b32 v8, s20, 7, v10
	v_mul_u32_u24_e32 v0, 0x84, v10
	v_and_b32_e32 v12, 0x7c, v2
	v_lshlrev_b32_e32 v6, 12, v8
	v_add3_u32 v19, v0, v12, s47
	v_or_b32_e32 v0, 0x18000, v6
	v_lshl_add_u64 v[2:3], s[2:3], 0, v[0:1]
	v_lshlrev_b32_e32 v0, 2, v10
	v_lshlrev_b32_e32 v10, 12, v10
	v_or_b32_e32 v4, 0x10000, v6
	v_or_b32_e32 v6, 0x8000, v6
	v_mov_b32_e32 v7, v1
	v_lshl_or_b32 v10, s20, 19, v10
	v_mov_b32_e32 v11, v1
	v_lshl_add_u64 v[4:5], s[2:3], 0, v[4:5]
	v_lshl_add_u64 v[6:7], s[2:3], 0, v[6:7]
	v_lshl_add_u64 v[10:11], s[2:3], 0, v[10:11]
	v_readlane_b32 s88, v240, 2
	v_or_b32_e32 v2, v2, v12
	v_or_b32_e32 v4, v4, v12
	v_or_b32_e32 v6, v6, v12
	v_or_b32_e32 v10, v10, v12
	v_readlane_b32 s92, v240, 6
	v_readlane_b32 s93, v240, 7
	v_lshl_add_u64 v[2:3], s[22:23], 0, v[2:3]
	v_lshl_or_b32 v0, s20, 9, v0
	v_lshl_add_u64 v[4:5], s[22:23], 0, v[4:5]
	v_lshl_add_u64 v[6:7], s[22:23], 0, v[6:7]
	v_lshl_or_b32 v8, v8, 2, v16
	v_mov_b32_e32 v9, v1
	v_lshl_add_u64 v[10:11], s[22:23], 0, v[10:11]
	s_mov_b64 s[34:35], 0
	s_mov_b64 s[36:37], s[92:93]
	v_readlane_b32 s89, v240, 3
	v_readlane_b32 s90, v240, 4
	v_readlane_b32 s91, v240, 5
	v_readlane_b32 s94, v240, 8
	v_readlane_b32 s95, v240, 9
	s_andn2_b64 vcc, exec, s[6:7]
	s_cbranch_vccnz .LBB0_815
	v_lshl_add_u64 v[64:65], v[10:11], 0, s[34:35]
	v_mov_b32_e32 v67, v65
	global_load_dword v66, v[64:65], off nt
	v_cndmask_b32_e64 v64, 0, 1, s[6:7]
	v_cmp_ne_u32_e64 s[2:3], 1, v64
	s_andn2_b64 vcc, exec, s[6:7]
	v_lshl_add_u64 v[68:69], s[36:37], 0, v[8:9]
	global_load_dword v65, v[68:69], off nt
	v_lshl_add_u64 v[70:71], v[6:7], 0, s[34:35]
	v_mov_b32_e32 v73, v69
	global_load_dword v72, v[70:71], off nt
	s_and_b64 vcc, exec, s[2:3]
	v_lshl_add_u64 v[68:69], s[36:37], 0, v[0:1]
	global_load_dword v64, v[68:69], off offset:1056 nt
	v_lshl_add_u64 v[70:71], v[4:5], 0, s[34:35]
	v_mov_b32_e32 v75, v71
	global_load_dword v74, v[70:71], off nt
	s_and_b64 vcc, exec, s[2:3]
	global_load_dword v67, v[68:69], off offset:1088 nt
	v_lshl_add_u64 v[70:71], v[2:3], 0, s[34:35]
	v_mov_b32_e32 v77, v71
	global_load_dword v76, v[70:71], off nt
	s_and_b64 vcc, exec, s[2:3]
	v_mov_b32_e32 v71, v69
	global_load_dword v70, v[68:69], off offset:1120 nt
	s_add_u32 s34, s34, 0x20000
	s_addc_u32 s35, s35, 0
	s_add_u32 s36, s36, 0x80
	s_addc_u32 s37, s37, 0
	s_cmp_lg_u32 s34, 0x80000
	v_add_u32_e32 v68, 0x1080, v19
	v_lshl_add_u64 v[78:79], v[10:11], 0, s[34:35]
	v_mov_b32_e32 v81, v79
	global_load_dword v80, v[78:79], off nt
	v_cndmask_b32_e64 v69, 0, 1, s[6:7]
	v_cmp_ne_u32_e64 s[2:3], 1, v69
	s_andn2_b64 vcc, exec, s[6:7]
	v_lshl_add_u64 v[78:79], s[36:37], 0, v[8:9]
	global_load_dword v71, v[78:79], off nt
	v_lshl_add_u64 v[82:83], v[6:7], 0, s[34:35]
	v_mov_b32_e32 v85, v79
	global_load_dword v84, v[82:83], off nt
	s_and_b64 vcc, exec, s[2:3]
	v_lshl_add_u64 v[78:79], s[36:37], 0, v[0:1]
	global_load_dword v69, v[78:79], off offset:1056 nt
	v_lshl_add_u64 v[82:83], v[4:5], 0, s[34:35]
	v_mov_b32_e32 v87, v83
	global_load_dword v86, v[82:83], off nt
	s_and_b64 vcc, exec, s[2:3]
	global_load_dword v73, v[78:79], off offset:1088 nt
	v_lshl_add_u64 v[82:83], v[2:3], 0, s[34:35]
	v_mov_b32_e32 v89, v83
	global_load_dword v88, v[82:83], off nt
	s_and_b64 vcc, exec, s[2:3]
	v_mov_b32_e32 v83, v79
	global_load_dword v82, v[78:79], off offset:1120 nt
	s_add_u32 s34, s34, 0x20000
	s_addc_u32 s35, s35, 0
	s_add_u32 s36, s36, 0x80
	s_addc_u32 s37, s37, 0
	s_cmp_lg_u32 s34, 0x80000
	v_add_u32_e32 v75, 0x1080, v68
	v_lshl_add_u64 v[78:79], v[10:11], 0, s[34:35]
	v_mov_b32_e32 v91, v79
	global_load_dword v90, v[78:79], off nt
	v_cndmask_b32_e64 v77, 0, 1, s[6:7]
	v_cmp_ne_u32_e64 s[2:3], 1, v77
	s_andn2_b64 vcc, exec, s[6:7]
	v_lshl_add_u64 v[78:79], s[36:37], 0, v[8:9]
	global_load_dword v81, v[78:79], off nt
	v_lshl_add_u64 v[92:93], v[6:7], 0, s[34:35]
	v_mov_b32_e32 v95, v79
	global_load_dword v94, v[92:93], off nt
	s_and_b64 vcc, exec, s[2:3]
	v_lshl_add_u64 v[78:79], s[36:37], 0, v[0:1]
	global_load_dword v77, v[78:79], off offset:1056 nt
	v_lshl_add_u64 v[92:93], v[4:5], 0, s[34:35]
	v_mov_b32_e32 v97, v93
	global_load_dword v96, v[92:93], off nt
	s_and_b64 vcc, exec, s[2:3]
	global_load_dword v83, v[78:79], off offset:1088 nt
	v_lshl_add_u64 v[92:93], v[2:3], 0, s[34:35]
	v_mov_b32_e32 v99, v93
	global_load_dword v98, v[92:93], off nt
	s_and_b64 vcc, exec, s[2:3]
	v_mov_b32_e32 v93, v79
	global_load_dword v92, v[78:79], off offset:1120 nt
	s_add_u32 s34, s34, 0x20000
	s_addc_u32 s35, s35, 0
	s_add_u32 s36, s36, 0x80
	s_addc_u32 s37, s37, 0
	s_cmp_lg_u32 s34, 0x80000
	v_add_u32_e32 v78, 0x1080, v75
	v_lshl_add_u64 v[100:101], v[10:11], 0, s[34:35]
	v_mov_b32_e32 v103, v101
	global_load_dword v102, v[100:101], off nt
	v_cndmask_b32_e64 v79, 0, 1, s[6:7]
	v_cmp_ne_u32_e64 s[2:3], 1, v79
	s_andn2_b64 vcc, exec, s[6:7]
	v_lshl_add_u64 v[100:101], s[36:37], 0, v[8:9]
	global_load_dword v85, v[100:101], off nt
	v_lshl_add_u64 v[104:105], v[6:7], 0, s[34:35]
	v_mov_b32_e32 v107, v101
	global_load_dword v106, v[104:105], off nt
	s_and_b64 vcc, exec, s[2:3]
	v_lshl_add_u64 v[100:101], s[36:37], 0, v[0:1]
	global_load_dword v79, v[100:101], off offset:1056 nt
	v_lshl_add_u64 v[104:105], v[4:5], 0, s[34:35]
	v_mov_b32_e32 v109, v105
	global_load_dword v108, v[104:105], off nt
	s_and_b64 vcc, exec, s[2:3]
	global_load_dword v87, v[100:101], off offset:1088 nt
	v_lshl_add_u64 v[104:105], v[2:3], 0, s[34:35]
	v_mov_b32_e32 v111, v105
	global_load_dword v110, v[104:105], off nt
	s_and_b64 vcc, exec, s[2:3]
	v_mov_b32_e32 v105, v101
	global_load_dword v104, v[100:101], off offset:1120 nt
	s_add_u32 s34, s34, 0x20000
	s_addc_u32 s35, s35, 0
	s_add_u32 s36, s36, 0x80
	s_addc_u32 s37, s37, 0
	s_cmp_lg_u32 s34, 0x80000
	v_add_u32_e32 v89, 0x1080, v78
	s_waitcnt vmcnt(30)
	v_mul_f32_e32 v66, v66, v65
	ds_write_b32 v19, v66
	s_waitcnt vmcnt(28)
	v_mul_f32_e32 v72, v72, v64
	ds_write_b32 v19, v72 offset:1056
	s_waitcnt vmcnt(26)
	v_mul_f32_e32 v74, v74, v67
	ds_write_b32 v19, v74 offset:2112
	s_waitcnt vmcnt(24)
	v_mul_f32_e32 v76, v76, v70
	ds_write_b32 v19, v76 offset:3168
	s_waitcnt vmcnt(22)
	v_mul_f32_e32 v80, v80, v71
	ds_write_b32 v68, v80
	s_waitcnt vmcnt(20)
	v_mul_f32_e32 v84, v84, v69
	ds_write_b32 v68, v84 offset:1056
	s_waitcnt vmcnt(18)
	v_mul_f32_e32 v86, v86, v73
	ds_write_b32 v68, v86 offset:2112
	s_waitcnt vmcnt(16)
	v_mul_f32_e32 v88, v88, v82
	ds_write_b32 v68, v88 offset:3168
	s_waitcnt vmcnt(14)
	v_mul_f32_e32 v90, v90, v81
	ds_write_b32 v75, v90
	s_waitcnt vmcnt(12)
	v_mul_f32_e32 v94, v94, v77
	ds_write_b32 v75, v94 offset:1056
	s_waitcnt vmcnt(10)
	v_mul_f32_e32 v96, v96, v83
	ds_write_b32 v75, v96 offset:2112
	s_waitcnt vmcnt(8)
	v_mul_f32_e32 v98, v98, v92
	ds_write_b32 v75, v98 offset:3168
	s_waitcnt vmcnt(6)
	v_mul_f32_e32 v102, v102, v85
	ds_write_b32 v78, v102
	s_waitcnt vmcnt(4)
	v_mul_f32_e32 v106, v106, v79
	ds_write_b32 v78, v106 offset:1056
	s_waitcnt vmcnt(2)
	v_mul_f32_e32 v108, v108, v87
	ds_write_b32 v78, v108 offset:2112
	s_waitcnt vmcnt(0)
	v_mul_f32_e32 v110, v110, v104
	ds_write_b32 v78, v110 offset:3168
	v_mov_b32_e32 v12, v104
	v_mov_b32_e32 v13, v105
	v_mov_b32_e32 v19, v89
	v_mov_b32_e32 v20, v110
	v_mov_b32_e32 v21, v111
	s_branch .LBB0_823

.LBB0_830:
	s_mul_i32 s2, s71, 6
	s_sub_i32 s2, s34, s2
	s_and_b32 s2, s2, 0xff
	s_lshl_b32 s36, s2, 7
	s_lshl_b64 s[2:3], s[20:21], 2
	s_add_u32 s34, s43, s2
	s_addc_u32 s35, s46, s3
	s_cmpk_gt_u32 s37, 0x59
	s_mov_b64 s[2:3], -1
	s_mul_i32 s20, s71, 48
	s_cbranch_scc0 .LBB0_842
	v_mov_b32_e32 v6, v198
	s_mul_hi_u32 s2, s37, 0x2aaaaaab
	v_bfe_u32 v4, v6, 5, 3
	v_lshlrev_b32_e32 v0, 2, v6
	v_and_b32_e32 v0, 0x7c, v0
	v_mul_u32_u24_e32 v5, 0x84, v4
	v_lshl_add_u64 v[2:3], s[34:35], 0, v[0:1]
	v_add3_u32 v7, v5, v0, s47
	v_lshl_or_b32 v0, s37, 7, v4
	s_mulk_i32 s2, 0x300
	v_subrev_u32_e32 v8, s2, v0
	v_add_lshl_u32 v0, v4, s36, 2
	v_lshl_add_u64 v[4:5], s[24:25], 0, v[0:1]
	s_mov_b32 s71, 0
	s_andn2_b64 vcc, exec, s[10:11]
	s_cbranch_vccnz .LBB0_833
	v_mov_b32_e32 v65, v1
	v_add_u32_e32 v64, s71, v8
	v_mad_u64_u32 v[66:67], s[2:3], v64, s66, v[2:3]
	global_load_dword v68, v[66:67], off nt
	v_mov_b32_e32 v71, v67
	v_cndmask_b32_e64 v70, 0, 1, s[10:11]
	v_cmp_ne_u32_e64 s[2:3], 1, v70
	s_andn2_b64 vcc, exec, s[10:11]
	v_readlane_b32 s88, v240, 2
	v_readlane_b32 s89, v240, 3
	v_readlane_b32 s90, v240, 4
	v_readlane_b32 s91, v240, 5
	v_lshl_add_u64 v[66:67], v[64:65], 2, s[88:89]
	v_mov_b32_e32 v71, v67
	global_load_dword v70, v[66:67], off offset:3072 nt
	v_readlane_b32 s92, v240, 6
	v_readlane_b32 s93, v240, 7
	v_readlane_b32 s94, v240, 8
	v_readlane_b32 s95, v240, 9
	v_add_u32_e32 v66, 8, v64
	v_mad_u64_u32 v[72:73], s[72:73], v66, s66, v[2:3]
	global_load_dword v67, v[72:73], off nt
	s_and_b64 vcc, exec, s[2:3]
	v_mov_b32_e32 v75, v73
	global_load_dword v74, v[4:5], off offset:-64 nt
	v_add_u32_e32 v66, 16, v64
	v_mad_u64_u32 v[72:73], s[72:73], v66, s66, v[2:3]
	global_load_dword v69, v[72:73], off nt
	s_and_b64 vcc, exec, s[2:3]
	v_mov_b32_e32 v77, v73
	global_load_dword v76, v[4:5], off offset:-32 nt
	v_mov_b32_e32 v73, v65
	v_add_u32_e32 v72, 24, v64
	v_mad_u64_u32 v[64:65], s[72:73], v72, s66, v[2:3]
	v_mov_b32_e32 v79, v73
	global_load_dword v78, v[64:65], off nt
	s_and_b64 vcc, exec, s[2:3]
	global_load_dword v66, v[4:5], off nt
	s_add_i32 s71, s71, 32
	v_add_u32_e32 v71, 0x1080, v7
	s_cmpk_lg_i32 s71, 0x80
	v_lshl_add_u64 v[72:73], v[4:5], 0, s[26:27]
	v_mov_b32_e32 v81, v79
	v_add_u32_e32 v80, s71, v8
	v_mad_u64_u32 v[82:83], s[2:3], v80, s66, v[2:3]
	global_load_dword v64, v[82:83], off nt
	v_mov_b32_e32 v85, v83
	v_cndmask_b32_e64 v84, 0, 1, s[10:11]
	v_cmp_ne_u32_e64 s[2:3], 1, v84
	s_andn2_b64 vcc, exec, s[10:11]
	v_readlane_b32 s88, v240, 2
	v_readlane_b32 s89, v240, 3
	v_readlane_b32 s90, v240, 4
	v_readlane_b32 s91, v240, 5
	v_lshl_add_u64 v[82:83], v[80:81], 2, s[88:89]
	v_mov_b32_e32 v85, v83
	global_load_dword v84, v[82:83], off offset:3072 nt
	v_readlane_b32 s92, v240, 6
	v_readlane_b32 s93, v240, 7
	v_readlane_b32 s94, v240, 8
	v_readlane_b32 s95, v240, 9
	v_add_u32_e32 v65, 8, v80
	v_mad_u64_u32 v[82:83], s[72:73], v65, s66, v[2:3]
	global_load_dword v75, v[82:83], off nt
	s_and_b64 vcc, exec, s[2:3]
	v_mov_b32_e32 v87, v83
	global_load_dword v86, v[72:73], off offset:-64 nt
	v_add_u32_e32 v65, 16, v80
	v_mad_u64_u32 v[82:83], s[72:73], v65, s66, v[2:3]
	global_load_dword v77, v[82:83], off nt
	s_and_b64 vcc, exec, s[2:3]
	v_mov_b32_e32 v89, v83
	global_load_dword v88, v[72:73], off offset:-32 nt
	v_mov_b32_e32 v83, v81
	v_add_u32_e32 v82, 24, v80
	v_mad_u64_u32 v[80:81], s[72:73], v82, s66, v[2:3]
	v_mov_b32_e32 v91, v83
	global_load_dword v90, v[80:81], off nt
	s_and_b64 vcc, exec, s[2:3]
	global_load_dword v65, v[72:73], off nt
	s_add_i32 s71, s71, 32
	v_add_u32_e32 v79, 0x1080, v71
	s_cmpk_lg_i32 s71, 0x80
	v_lshl_add_u64 v[82:83], v[72:73], 0, s[26:27]
	v_mov_b32_e32 v73, v91
	v_add_u32_e32 v72, s71, v8
	v_mad_u64_u32 v[92:93], s[2:3], v72, s66, v[2:3]
	global_load_dword v80, v[92:93], off nt
	v_mov_b32_e32 v95, v93
	v_cndmask_b32_e64 v94, 0, 1, s[10:11]
	v_cmp_ne_u32_e64 s[2:3], 1, v94
	s_andn2_b64 vcc, exec, s[10:11]
	v_readlane_b32 s88, v240, 2
	v_readlane_b32 s89, v240, 3
	v_readlane_b32 s90, v240, 4
	v_readlane_b32 s91, v240, 5
	v_lshl_add_u64 v[92:93], v[72:73], 2, s[88:89]
	v_mov_b32_e32 v95, v93
	global_load_dword v94, v[92:93], off offset:3072 nt
	v_readlane_b32 s92, v240, 6
	v_readlane_b32 s93, v240, 7
	v_readlane_b32 s94, v240, 8
	v_readlane_b32 s95, v240, 9
	v_add_u32_e32 v81, 8, v72
	v_mad_u64_u32 v[92:93], s[72:73], v81, s66, v[2:3]
	global_load_dword v85, v[92:93], off nt
	s_and_b64 vcc, exec, s[2:3]
	v_mov_b32_e32 v97, v93
	global_load_dword v96, v[82:83], off offset:-64 nt
	v_add_u32_e32 v81, 16, v72
	v_mad_u64_u32 v[92:93], s[72:73], v81, s66, v[2:3]
	global_load_dword v87, v[92:93], off nt
	s_and_b64 vcc, exec, s[2:3]
	v_mov_b32_e32 v99, v93
	global_load_dword v98, v[82:83], off offset:-32 nt
	v_mov_b32_e32 v93, v73
	v_add_u32_e32 v92, 24, v72
	v_mad_u64_u32 v[72:73], s[72:73], v92, s66, v[2:3]
	v_mov_b32_e32 v101, v93
	global_load_dword v100, v[72:73], off nt
	s_and_b64 vcc, exec, s[2:3]
	global_load_dword v81, v[82:83], off nt
	s_add_i32 s71, s71, 32
	v_add_u32_e32 v89, 0x1080, v79
	s_cmpk_lg_i32 s71, 0x80
	v_lshl_add_u64 v[92:93], v[82:83], 0, s[26:27]
	v_mov_b32_e32 v83, v101
	v_add_u32_e32 v82, s71, v8
	v_mad_u64_u32 v[102:103], s[2:3], v82, s66, v[2:3]
	global_load_dword v72, v[102:103], off nt
	v_mov_b32_e32 v105, v103
	v_cndmask_b32_e64 v104, 0, 1, s[10:11]
	v_cmp_ne_u32_e64 s[2:3], 1, v104
	s_andn2_b64 vcc, exec, s[10:11]
	v_readlane_b32 s88, v240, 2
	v_readlane_b32 s89, v240, 3
	v_readlane_b32 s90, v240, 4
	v_readlane_b32 s91, v240, 5
	v_lshl_add_u64 v[102:103], v[82:83], 2, s[88:89]
	v_mov_b32_e32 v105, v103
	global_load_dword v104, v[102:103], off offset:3072 nt
	v_readlane_b32 s92, v240, 6
	v_readlane_b32 s93, v240, 7
	v_readlane_b32 s94, v240, 8
	v_readlane_b32 s95, v240, 9
	v_add_u32_e32 v73, 8, v82
	v_mad_u64_u32 v[102:103], s[72:73], v73, s66, v[2:3]
	global_load_dword v91, v[102:103], off nt
	s_and_b64 vcc, exec, s[2:3]
	v_mov_b32_e32 v107, v103
	global_load_dword v106, v[92:93], off offset:-64 nt
	v_add_u32_e32 v73, 16, v82
	v_mad_u64_u32 v[102:103], s[72:73], v73, s66, v[2:3]
	global_load_dword v95, v[102:103], off nt
	s_and_b64 vcc, exec, s[2:3]
	v_mov_b32_e32 v109, v103
	global_load_dword v108, v[92:93], off offset:-32 nt
	v_mov_b32_e32 v103, v83
	v_add_u32_e32 v102, 24, v82
	v_mad_u64_u32 v[82:83], s[72:73], v102, s66, v[2:3]
	v_mov_b32_e32 v111, v103
	global_load_dword v110, v[82:83], off nt
	s_and_b64 vcc, exec, s[2:3]
	global_load_dword v73, v[92:93], off nt
	s_add_i32 s71, s71, 32
	v_add_u32_e32 v97, 0x1080, v89
	s_cmpk_lg_i32 s71, 0x80
	v_lshl_add_u64 v[102:103], v[92:93], 0, s[26:27]
	s_waitcnt vmcnt(30)
	v_mul_f32_e32 v68, v68, v70
	v_mul_f32_e32 v68, 0x3e16c740, v68
	ds_write_b32 v7, v68
	s_waitcnt vmcnt(28)
	v_mul_f32_e32 v67, v67, v74
	v_mul_f32_e32 v67, 0x3e16c740, v67
	ds_write_b32 v7, v67 offset:1056
	s_waitcnt vmcnt(26)
	v_mul_f32_e32 v69, v69, v76
	v_mul_f32_e32 v69, 0x3e16c740, v69
	ds_write_b32 v7, v69 offset:2112
	s_waitcnt vmcnt(24)
	v_mul_f32_e32 v78, v78, v66
	v_mul_f32_e32 v78, 0x3e16c740, v78
	ds_write_b32 v7, v78 offset:3168
	s_waitcnt vmcnt(22)
	v_mul_f32_e32 v64, v64, v84
	v_mul_f32_e32 v64, 0x3e16c740, v64
	ds_write_b32 v71, v64
	s_waitcnt vmcnt(20)
	v_mul_f32_e32 v75, v75, v86
	v_mul_f32_e32 v75, 0x3e16c740, v75
	ds_write_b32 v71, v75 offset:1056
	s_waitcnt vmcnt(18)
	v_mul_f32_e32 v77, v77, v88
	v_mul_f32_e32 v77, 0x3e16c740, v77
	ds_write_b32 v71, v77 offset:2112
	s_waitcnt vmcnt(16)
	v_mul_f32_e32 v90, v90, v65
	v_mul_f32_e32 v90, 0x3e16c740, v90
	ds_write_b32 v71, v90 offset:3168
	s_waitcnt vmcnt(14)
	v_mul_f32_e32 v80, v80, v94
	v_mul_f32_e32 v80, 0x3e16c740, v80
	ds_write_b32 v79, v80
	s_waitcnt vmcnt(12)
	v_mul_f32_e32 v85, v85, v96
	v_mul_f32_e32 v85, 0x3e16c740, v85
	ds_write_b32 v79, v85 offset:1056
	s_waitcnt vmcnt(10)
	v_mul_f32_e32 v87, v87, v98
	v_mul_f32_e32 v87, 0x3e16c740, v87
	ds_write_b32 v79, v87 offset:2112
	s_waitcnt vmcnt(8)
	v_mul_f32_e32 v100, v100, v81
	v_mul_f32_e32 v100, 0x3e16c740, v100
	ds_write_b32 v79, v100 offset:3168
	s_waitcnt vmcnt(6)
	v_mul_f32_e32 v72, v72, v104
	v_mul_f32_e32 v72, 0x3e16c740, v72
	ds_write_b32 v89, v72
	s_waitcnt vmcnt(4)
	v_mul_f32_e32 v91, v91, v106
	v_mul_f32_e32 v91, 0x3e16c740, v91
	ds_write_b32 v89, v91 offset:1056
	s_waitcnt vmcnt(2)
	v_mul_f32_e32 v95, v95, v108
	v_mul_f32_e32 v95, 0x3e16c740, v95
	ds_write_b32 v89, v95 offset:2112
	s_waitcnt vmcnt(0)
	v_mul_f32_e32 v110, v110, v73
	v_mul_f32_e32 v110, 0x3e16c740, v110
	ds_write_b32 v89, v110 offset:3168
	v_mov_b32_e32 v0, v110
	v_mov_b32_e32 v1, v111
	v_mov_b32_e32 v4, v102
	v_mov_b32_e32 v5, v103
	v_mov_b32_e32 v7, v97
	v_mov_b32_e32 v9, v73
	v_mov_b32_e32 v10, v82
	v_mov_b32_e32 v11, v83
	s_branch .LBB0_841

.LBB0_842:
	s_and_b64 vcc, exec, s[2:3]
	s_cbranch_vccz .LBB0_854
	v_mov_b32_e32 v6, v198
	s_mul_hi_u32 s2, s37, 0x2aaaaaab
	v_bfe_u32 v4, v6, 5, 3
	v_lshlrev_b32_e32 v0, 2, v6
	v_and_b32_e32 v0, 0x7c, v0
	v_mul_u32_u24_e32 v5, 0x84, v4
	v_lshl_add_u64 v[2:3], s[34:35], 0, v[0:1]
	v_add3_u32 v7, v5, v0, s47
	v_lshl_or_b32 v0, s37, 7, v4
	s_mulk_i32 s2, 0x300
	v_subrev_u32_e32 v8, s2, v0
	v_add_lshl_u32 v0, v4, s36, 2
	v_lshl_add_u64 v[4:5], s[24:25], 0, v[0:1]
	s_mov_b32 s34, 0
	s_andn2_b64 vcc, exec, s[10:11]
	s_cbranch_vccnz .LBB0_845
	v_mov_b32_e32 v65, v1
	v_add_u32_e32 v64, s34, v8
	v_mad_u64_u32 v[66:67], s[2:3], v64, s66, v[2:3]
	global_load_dword v68, v[66:67], off nt
	v_mov_b32_e32 v71, v67
	v_cndmask_b32_e64 v70, 0, 1, s[10:11]
	v_cmp_ne_u32_e64 s[2:3], 1, v70
	s_andn2_b64 vcc, exec, s[10:11]
	v_readlane_b32 s88, v240, 2
	v_readlane_b32 s89, v240, 3
	v_readlane_b32 s90, v240, 4
	v_readlane_b32 s91, v240, 5
	v_lshl_add_u64 v[66:67], v[64:65], 2, s[88:89]
	v_mov_b32_e32 v71, v67
	global_load_dword v70, v[66:67], off offset:3072 nt
	v_readlane_b32 s92, v240, 6
	v_readlane_b32 s93, v240, 7
	v_readlane_b32 s94, v240, 8
	v_readlane_b32 s95, v240, 9
	v_add_u32_e32 v66, 8, v64
	v_mad_u64_u32 v[72:73], s[72:73], v66, s66, v[2:3]
	global_load_dword v67, v[72:73], off nt
	s_and_b64 vcc, exec, s[2:3]
	v_mov_b32_e32 v75, v73
	global_load_dword v74, v[4:5], off offset:-64 nt
	v_add_u32_e32 v66, 16, v64
	v_mad_u64_u32 v[72:73], s[72:73], v66, s66, v[2:3]
	global_load_dword v69, v[72:73], off nt
	s_and_b64 vcc, exec, s[2:3]
	v_mov_b32_e32 v77, v73
	global_load_dword v76, v[4:5], off offset:-32 nt
	v_mov_b32_e32 v73, v65
	v_add_u32_e32 v72, 24, v64
	v_mad_u64_u32 v[64:65], s[72:73], v72, s66, v[2:3]
	v_mov_b32_e32 v79, v73
	global_load_dword v78, v[64:65], off nt
	s_and_b64 vcc, exec, s[2:3]
	global_load_dword v66, v[4:5], off nt
	s_add_i32 s34, s34, 32
	v_add_u32_e32 v71, 0x1080, v7
	s_cmpk_lg_i32 s34, 0x80
	v_lshl_add_u64 v[72:73], v[4:5], 0, s[26:27]
	v_mov_b32_e32 v81, v79
	v_add_u32_e32 v80, s34, v8
	v_mad_u64_u32 v[82:83], s[2:3], v80, s66, v[2:3]
	global_load_dword v64, v[82:83], off nt
	v_mov_b32_e32 v85, v83
	v_cndmask_b32_e64 v84, 0, 1, s[10:11]
	v_cmp_ne_u32_e64 s[2:3], 1, v84
	s_andn2_b64 vcc, exec, s[10:11]
	v_readlane_b32 s88, v240, 2
	v_readlane_b32 s89, v240, 3
	v_readlane_b32 s90, v240, 4
	v_readlane_b32 s91, v240, 5
	v_lshl_add_u64 v[82:83], v[80:81], 2, s[88:89]
	v_mov_b32_e32 v85, v83
	global_load_dword v84, v[82:83], off offset:3072 nt
	v_readlane_b32 s92, v240, 6
	v_readlane_b32 s93, v240, 7
	v_readlane_b32 s94, v240, 8
	v_readlane_b32 s95, v240, 9
	v_add_u32_e32 v65, 8, v80
	v_mad_u64_u32 v[82:83], s[72:73], v65, s66, v[2:3]
	global_load_dword v75, v[82:83], off nt
	s_and_b64 vcc, exec, s[2:3]
	v_mov_b32_e32 v87, v83
	global_load_dword v86, v[72:73], off offset:-64 nt
	v_add_u32_e32 v65, 16, v80
	v_mad_u64_u32 v[82:83], s[72:73], v65, s66, v[2:3]
	global_load_dword v77, v[82:83], off nt
	s_and_b64 vcc, exec, s[2:3]
	v_mov_b32_e32 v89, v83
	global_load_dword v88, v[72:73], off offset:-32 nt
	v_mov_b32_e32 v83, v81
	v_add_u32_e32 v82, 24, v80
	v_mad_u64_u32 v[80:81], s[72:73], v82, s66, v[2:3]
	v_mov_b32_e32 v91, v83
	global_load_dword v90, v[80:81], off nt
	s_and_b64 vcc, exec, s[2:3]
	global_load_dword v65, v[72:73], off nt
	s_add_i32 s34, s34, 32
	v_add_u32_e32 v79, 0x1080, v71
	s_cmpk_lg_i32 s34, 0x80
	v_lshl_add_u64 v[82:83], v[72:73], 0, s[26:27]
	v_mov_b32_e32 v73, v91
	v_add_u32_e32 v72, s34, v8
	v_mad_u64_u32 v[92:93], s[2:3], v72, s66, v[2:3]
	global_load_dword v80, v[92:93], off nt
	v_mov_b32_e32 v95, v93
	v_cndmask_b32_e64 v94, 0, 1, s[10:11]
	v_cmp_ne_u32_e64 s[2:3], 1, v94
	s_andn2_b64 vcc, exec, s[10:11]
	v_readlane_b32 s88, v240, 2
	v_readlane_b32 s89, v240, 3
	v_readlane_b32 s90, v240, 4
	v_readlane_b32 s91, v240, 5
	v_lshl_add_u64 v[92:93], v[72:73], 2, s[88:89]
	v_mov_b32_e32 v95, v93
	global_load_dword v94, v[92:93], off offset:3072 nt
	v_readlane_b32 s92, v240, 6
	v_readlane_b32 s93, v240, 7
	v_readlane_b32 s94, v240, 8
	v_readlane_b32 s95, v240, 9
	v_add_u32_e32 v81, 8, v72
	v_mad_u64_u32 v[92:93], s[72:73], v81, s66, v[2:3]
	global_load_dword v85, v[92:93], off nt
	s_and_b64 vcc, exec, s[2:3]
	v_mov_b32_e32 v97, v93
	global_load_dword v96, v[82:83], off offset:-64 nt
	v_add_u32_e32 v81, 16, v72
	v_mad_u64_u32 v[92:93], s[72:73], v81, s66, v[2:3]
	global_load_dword v87, v[92:93], off nt
	s_and_b64 vcc, exec, s[2:3]
	v_mov_b32_e32 v99, v93
	global_load_dword v98, v[82:83], off offset:-32 nt
	v_mov_b32_e32 v93, v73
	v_add_u32_e32 v92, 24, v72
	v_mad_u64_u32 v[72:73], s[72:73], v92, s66, v[2:3]
	v_mov_b32_e32 v101, v93
	global_load_dword v100, v[72:73], off nt
	s_and_b64 vcc, exec, s[2:3]
	global_load_dword v81, v[82:83], off nt
	s_add_i32 s34, s34, 32
	v_add_u32_e32 v89, 0x1080, v79
	s_cmpk_lg_i32 s34, 0x80
	v_lshl_add_u64 v[92:93], v[82:83], 0, s[26:27]
	v_mov_b32_e32 v83, v101
	v_add_u32_e32 v82, s34, v8
	v_mad_u64_u32 v[102:103], s[2:3], v82, s66, v[2:3]
	global_load_dword v72, v[102:103], off nt
	v_mov_b32_e32 v105, v103
	v_cndmask_b32_e64 v104, 0, 1, s[10:11]
	v_cmp_ne_u32_e64 s[2:3], 1, v104
	s_andn2_b64 vcc, exec, s[10:11]
	v_readlane_b32 s88, v240, 2
	v_readlane_b32 s89, v240, 3
	v_readlane_b32 s90, v240, 4
	v_readlane_b32 s91, v240, 5
	v_lshl_add_u64 v[102:103], v[82:83], 2, s[88:89]
	v_mov_b32_e32 v105, v103
	global_load_dword v104, v[102:103], off offset:3072 nt
	v_readlane_b32 s92, v240, 6
	v_readlane_b32 s93, v240, 7
	v_readlane_b32 s94, v240, 8
	v_readlane_b32 s95, v240, 9
	v_add_u32_e32 v73, 8, v82
	v_mad_u64_u32 v[102:103], s[72:73], v73, s66, v[2:3]
	global_load_dword v91, v[102:103], off nt
	s_and_b64 vcc, exec, s[2:3]
	v_mov_b32_e32 v107, v103
	global_load_dword v106, v[92:93], off offset:-64 nt
	v_add_u32_e32 v73, 16, v82
	v_mad_u64_u32 v[102:103], s[72:73], v73, s66, v[2:3]
	global_load_dword v95, v[102:103], off nt
	s_and_b64 vcc, exec, s[2:3]
	v_mov_b32_e32 v109, v103
	global_load_dword v108, v[92:93], off offset:-32 nt
	v_mov_b32_e32 v103, v83
	v_add_u32_e32 v102, 24, v82
	v_mad_u64_u32 v[82:83], s[72:73], v102, s66, v[2:3]
	v_mov_b32_e32 v111, v103
	global_load_dword v110, v[82:83], off nt
	s_and_b64 vcc, exec, s[2:3]
	global_load_dword v73, v[92:93], off nt
	s_add_i32 s34, s34, 32
	v_add_u32_e32 v97, 0x1080, v89
	s_cmpk_lg_i32 s34, 0x80
	v_lshl_add_u64 v[102:103], v[92:93], 0, s[26:27]
	s_waitcnt vmcnt(30)
	v_mul_f32_e32 v68, v68, v70
	v_mul_f32_e32 v68, 0x3e16c740, v68
	ds_write_b32 v7, v68
	s_waitcnt vmcnt(28)
	v_mul_f32_e32 v67, v67, v74
	v_mul_f32_e32 v67, 0x3e16c740, v67
	ds_write_b32 v7, v67 offset:1056
	s_waitcnt vmcnt(26)
	v_mul_f32_e32 v69, v69, v76
	v_mul_f32_e32 v69, 0x3e16c740, v69
	ds_write_b32 v7, v69 offset:2112
	s_waitcnt vmcnt(24)
	v_mul_f32_e32 v78, v78, v66
	v_mul_f32_e32 v78, 0x3e16c740, v78
	ds_write_b32 v7, v78 offset:3168
	s_waitcnt vmcnt(22)
	v_mul_f32_e32 v64, v64, v84
	v_mul_f32_e32 v64, 0x3e16c740, v64
	ds_write_b32 v71, v64
	s_waitcnt vmcnt(20)
	v_mul_f32_e32 v75, v75, v86
	v_mul_f32_e32 v75, 0x3e16c740, v75
	ds_write_b32 v71, v75 offset:1056
	s_waitcnt vmcnt(18)
	v_mul_f32_e32 v77, v77, v88
	v_mul_f32_e32 v77, 0x3e16c740, v77
	ds_write_b32 v71, v77 offset:2112
	s_waitcnt vmcnt(16)
	v_mul_f32_e32 v90, v90, v65
	v_mul_f32_e32 v90, 0x3e16c740, v90
	ds_write_b32 v71, v90 offset:3168
	s_waitcnt vmcnt(14)
	v_mul_f32_e32 v80, v80, v94
	v_mul_f32_e32 v80, 0x3e16c740, v80
	ds_write_b32 v79, v80
	s_waitcnt vmcnt(12)
	v_mul_f32_e32 v85, v85, v96
	v_mul_f32_e32 v85, 0x3e16c740, v85
	ds_write_b32 v79, v85 offset:1056
	s_waitcnt vmcnt(10)
	v_mul_f32_e32 v87, v87, v98
	v_mul_f32_e32 v87, 0x3e16c740, v87
	ds_write_b32 v79, v87 offset:2112
	s_waitcnt vmcnt(8)
	v_mul_f32_e32 v100, v100, v81
	v_mul_f32_e32 v100, 0x3e16c740, v100
	ds_write_b32 v79, v100 offset:3168
	s_waitcnt vmcnt(6)
	v_mul_f32_e32 v72, v72, v104
	v_mul_f32_e32 v72, 0x3e16c740, v72
	ds_write_b32 v89, v72
	s_waitcnt vmcnt(4)
	v_mul_f32_e32 v91, v91, v106
	v_mul_f32_e32 v91, 0x3e16c740, v91
	ds_write_b32 v89, v91 offset:1056
	s_waitcnt vmcnt(2)
	v_mul_f32_e32 v95, v95, v108
	v_mul_f32_e32 v95, 0x3e16c740, v95
	ds_write_b32 v89, v95 offset:2112
	s_waitcnt vmcnt(0)
	v_mul_f32_e32 v110, v110, v73
	v_mul_f32_e32 v110, 0x3e16c740, v110
	ds_write_b32 v89, v110 offset:3168
	v_mov_b32_e32 v0, v110
	v_mov_b32_e32 v1, v111
	v_mov_b32_e32 v4, v102
	v_mov_b32_e32 v5, v103
	v_mov_b32_e32 v7, v97
	v_mov_b32_e32 v9, v73
	v_mov_b32_e32 v10, v82
	v_mov_b32_e32 v11, v83
	s_branch .LBB0_853

.LBB0_857:
	s_lshl_b32 s71, s35, 3
	s_lshl_b32 s37, s34, 3
	v_or_b32_e32 v64, s71, v6
	v_or_b32_e32 v65, s37, v5
	v_mov_b32_e32 v67, v1
	v_add_u32_e32 v66, s2, v64
	v_mov_b32_e32 v69, v9
	v_add_u32_e32 v68, s3, v65
	v_mov_b32_e32 v71, v67
	v_mul_lo_u32 v70, v66, s67
	v_mov_b32_e32 v67, v69
	v_mul_lo_u32 v66, v68, s67
	v_lshl_add_u64 v[68:69], v[70:71], 2, v[2:3]
	v_mov_b32_e32 v72, v66
	v_mov_b32_e32 v73, v71
	v_lshl_add_u64 v[66:67], v[72:73], 2, v[2:3]
	v_mov_b32_e32 v73, v71
	global_load_dword v72, v[68:69], off nt
	global_load_dword v70, v[66:67], off nt
	v_mad_u64_u32 v[74:75], s[72:73], v64, s64, v[4:5]
	v_mad_u64_u32 v[66:67], s[72:73], v65, s64, v[4:5]
	s_add_i32 s73, s71, 16
	s_add_i32 s72, s37, 16
	v_or_b32_e32 v68, s73, v6
	v_or_b32_e32 v64, s72, v5
	v_mov_b32_e32 v76, v74
	v_mov_b32_e32 v77, v73
	s_add_i32 s35, s35, 8
	s_add_i32 s34, s34, 8
	s_add_i32 s36, s36, -8
	v_mov_b32_e32 v75, v73
	v_add_u32_e32 v74, s2, v68
	v_mov_b32_e32 v79, v77
	v_add_u32_e32 v78, s3, v64
	v_mov_b32_e32 v81, v75
	v_mul_lo_u32 v80, v74, s67
	v_mov_b32_e32 v75, v79
	v_mul_lo_u32 v74, v78, s67
	v_lshl_add_u64 v[78:79], v[80:81], 2, v[2:3]
	v_lshl_add_u64 v[82:83], v[74:75], 2, v[2:3]
	v_mov_b32_e32 v75, v81
	global_load_dword v74, v[78:79], off nt
	global_load_dword v65, v[82:83], off nt
	v_mad_u64_u32 v[80:81], s[72:73], v68, s64, v[4:5]
	v_mad_u64_u32 v[82:83], s[72:73], v64, s64, v[4:5]
	s_add_i32 s73, s71, 32
	s_add_i32 s72, s37, 32
	v_or_b32_e32 v67, s73, v6
	v_or_b32_e32 v68, s72, v5
	v_mov_b32_e32 v78, v80
	v_mov_b32_e32 v79, v75
	s_add_i32 s71, s71, 48
	s_add_i32 s37, s37, 48
	s_cmp_lg_u32 s36, 0
	v_mov_b32_e32 v81, v75
	v_add_u32_e32 v80, s2, v67
	v_mov_b32_e32 v85, v79
	v_add_u32_e32 v84, s3, v68
	v_mov_b32_e32 v87, v81
	v_mul_lo_u32 v86, v80, s67
	v_mov_b32_e32 v81, v85
	v_mul_lo_u32 v80, v84, s67
	v_lshl_add_u64 v[84:85], v[86:87], 2, v[2:3]
	v_lshl_add_u64 v[88:89], v[80:81], 2, v[2:3]
	v_mov_b32_e32 v81, v87
	global_load_dword v80, v[84:85], off nt
	global_load_dword v64, v[88:89], off nt
	v_mad_u64_u32 v[86:87], s[72:73], v67, s64, v[4:5]
	v_or_b32_e32 v69, s71, v6
	v_mad_u64_u32 v[88:89], s[72:73], v68, s64, v[4:5]
	v_or_b32_e32 v67, s37, v5
	v_mov_b32_e32 v84, v86
	v_mov_b32_e32 v85, v81
	v_mov_b32_e32 v87, v81
	v_add_u32_e32 v86, s2, v69
	v_mov_b32_e32 v91, v85
	v_add_u32_e32 v90, s3, v67
	v_mov_b32_e32 v93, v87
	v_mul_lo_u32 v92, v86, s67
	v_mov_b32_e32 v87, v91
	v_mul_lo_u32 v86, v90, s67
	v_lshl_add_u64 v[90:91], v[92:93], 2, v[2:3]
	v_lshl_add_u64 v[94:95], v[86:87], 2, v[2:3]
	v_mov_b32_e32 v87, v93
	global_load_dword v86, v[90:91], off nt
	global_load_dword v68, v[94:95], off nt
	v_mad_u64_u32 v[92:93], s[72:73], v69, s64, v[4:5]
	v_mad_u64_u32 v[94:95], s[72:73], v67, s64, v[4:5]
	s_lshl_b32 s71, s35, 3
	s_lshl_b32 s37, s34, 3
	v_or_b32_e32 v71, s71, v6
	v_or_b32_e32 v69, s37, v5
	v_mov_b32_e32 v91, v87
	v_add_u32_e32 v90, s2, v71
	v_mov_b32_e32 v97, v93
	v_add_u32_e32 v96, s3, v69
	v_mov_b32_e32 v99, v91
	v_mul_lo_u32 v98, v90, s67
	v_mov_b32_e32 v91, v97
	v_mul_lo_u32 v90, v96, s67
	v_lshl_add_u64 v[96:97], v[98:99], 2, v[2:3]
	v_mov_b32_e32 v100, v90
	v_mov_b32_e32 v101, v99
	v_lshl_add_u64 v[90:91], v[100:101], 2, v[2:3]
	v_mov_b32_e32 v101, v99
	global_load_dword v100, v[96:97], off nt
	global_load_dword v67, v[90:91], off nt
	v_mad_u64_u32 v[98:99], s[72:73], v71, s64, v[4:5]
	v_mad_u64_u32 v[90:91], s[72:73], v69, s64, v[4:5]
	s_add_i32 s73, s71, 16
	s_add_i32 s72, s37, 16
	v_or_b32_e32 v73, s73, v6
	v_or_b32_e32 v71, s72, v5
	v_mov_b32_e32 v96, v98
	v_mov_b32_e32 v97, v101
	s_add_i32 s35, s35, 8
	s_add_i32 s34, s34, 8
	s_add_i32 s36, s36, -8
	v_mov_b32_e32 v99, v101
	v_add_u32_e32 v98, s2, v73
	v_mov_b32_e32 v103, v97
	v_add_u32_e32 v102, s3, v71
	v_mov_b32_e32 v105, v99
	v_mul_lo_u32 v104, v98, s67
	v_mov_b32_e32 v99, v103
	v_mul_lo_u32 v98, v102, s67
	v_lshl_add_u64 v[102:103], v[104:105], 2, v[2:3]
	v_lshl_add_u64 v[106:107], v[98:99], 2, v[2:3]
	v_mov_b32_e32 v99, v105
	global_load_dword v98, v[102:103], off nt
	global_load_dword v69, v[106:107], off nt
	v_mad_u64_u32 v[104:105], s[72:73], v73, s64, v[4:5]
	v_mad_u64_u32 v[106:107], s[72:73], v71, s64, v[4:5]
	s_add_i32 s73, s71, 32
	s_add_i32 s72, s37, 32
	v_or_b32_e32 v75, s73, v6
	v_or_b32_e32 v73, s72, v5
	v_mov_b32_e32 v102, v104
	v_mov_b32_e32 v103, v99
	s_add_i32 s71, s71, 48
	s_add_i32 s37, s37, 48
	s_cmp_lg_u32 s36, 0
	v_mov_b32_e32 v105, v99
	v_add_u32_e32 v104, s2, v75
	v_mov_b32_e32 v109, v103
	v_add_u32_e32 v108, s3, v73
	v_mov_b32_e32 v111, v105
	v_mul_lo_u32 v110, v104, s67
	v_mov_b32_e32 v105, v109
	v_mul_lo_u32 v104, v108, s67
	v_lshl_add_u64 v[108:109], v[110:111], 2, v[2:3]
	v_lshl_add_u64 v[112:113], v[104:105], 2, v[2:3]
	v_mov_b32_e32 v105, v111
	global_load_dword v104, v[108:109], off nt
	global_load_dword v71, v[112:113], off nt
	v_mad_u64_u32 v[110:111], s[72:73], v75, s64, v[4:5]
	v_or_b32_e32 v77, s71, v6
	v_mad_u64_u32 v[112:113], s[72:73], v73, s64, v[4:5]
	v_or_b32_e32 v75, s37, v5
	v_mov_b32_e32 v108, v110
	v_mov_b32_e32 v109, v105
	v_mov_b32_e32 v111, v105
	v_add_u32_e32 v110, s2, v77
	v_mov_b32_e32 v115, v109
	v_add_u32_e32 v114, s3, v75
	v_mov_b32_e32 v117, v111
	v_mul_lo_u32 v116, v110, s67
	v_mov_b32_e32 v111, v115
	v_mul_lo_u32 v110, v114, s67
	v_lshl_add_u64 v[114:115], v[116:117], 2, v[2:3]
	v_lshl_add_u64 v[118:119], v[110:111], 2, v[2:3]
	v_mov_b32_e32 v111, v117
	global_load_dword v110, v[114:115], off nt
	global_load_dword v73, v[118:119], off nt
	v_mad_u64_u32 v[116:117], s[72:73], v77, s64, v[4:5]
	v_mad_u64_u32 v[118:119], s[72:73], v75, s64, v[4:5]
	s_waitcnt vmcnt(15)
	ds_write_b32 v76, v72
	s_waitcnt vmcnt(14)
	ds_write_b32 v66, v70
	s_waitcnt vmcnt(13)
	ds_write_b32 v78, v74
	s_waitcnt vmcnt(12)
	ds_write_b32 v82, v65
	s_waitcnt vmcnt(11)
	ds_write_b32 v84, v80
	s_waitcnt vmcnt(10)
	ds_write_b32 v88, v64
	s_waitcnt vmcnt(9)
	ds_write_b32 v92, v86
	s_waitcnt vmcnt(8)
	ds_write_b32 v94, v68
	s_waitcnt vmcnt(7)
	ds_write_b32 v96, v100
	s_waitcnt vmcnt(6)
	ds_write_b32 v90, v67
	s_waitcnt vmcnt(5)
	ds_write_b32 v102, v98
	s_waitcnt vmcnt(4)
	ds_write_b32 v106, v69
	s_waitcnt vmcnt(3)
	ds_write_b32 v108, v104
	s_waitcnt vmcnt(2)
	ds_write_b32 v112, v71
	s_waitcnt vmcnt(1)
	ds_write_b32 v116, v110
	s_waitcnt vmcnt(0)
	ds_write_b32 v118, v73
	v_mov_b32_e32 v0, v110
	v_mov_b32_e32 v1, v111
	v_mov_b32_e32 v8, v116
	v_mov_b32_e32 v9, v117
	v_mov_b32_e32 v10, v118
	v_mov_b32_e32 v11, v119
	v_mov_b32_e32 v12, v75
	v_mov_b32_e32 v13, v77
	v_mov_b32_e32 v18, v73
	v_lshlrev_b32_sdwa v0, v14, v7 dst_sel:DWORD dst_unused:UNUSED_PAD src0_sel:DWORD src1_sel:BYTE_0
	v_and_b32_e32 v0, 0x7e, v0
	v_lshrrev_b32_sdwa v3, v15, v7 dst_sel:DWORD dst_unused:UNUSED_PAD src0_sel:DWORD src1_sel:BYTE_0
	v_or_b32_e32 v2, s20, v3
	v_or_b32_e32 v8, s2, v0
	v_mul_u32_u24_e32 v0, 0x84, v0
	v_lshlrev_b32_e32 v3, 2, v3
	v_add3_u32 v24, s47, v0, v3
	s_waitcnt lgkmcnt(0)
	s_barrier
	ds_read2_b32 v[4:5], v24 offset0:33 offset1:37
	ds_read2_b32 v[6:7], v24 offset1:4
	v_lshlrev_b32_e32 v0, 1, v8
	v_mov_b32_e32 v3, v1
	ds_read2_b32 v[10:11], v24 offset0:8 offset1:12
	ds_read2_b32 v[12:13], v24 offset0:41 offset1:45
	v_lshl_add_u64 v[8:9], s[14:15], 0, v[0:1]
	v_lshlrev_b64 v[18:19], 11, v[2:3]
	s_waitcnt lgkmcnt(2)
	v_cvt_pk_bf16_f32 v0, v6, v4
	v_lshl_add_u64 v[18:19], v[8:9], 0, v[18:19]
	global_store_dword v[18:19], v0, off
	v_or_b32_e32 v0, 4, v2
	v_lshlrev_b64 v[22:23], 11, v[0:1]
	s_waitcnt lgkmcnt(0)
	v_cvt_pk_bf16_f32 v3, v10, v12
	ds_read2_b32 v[18:19], v24 offset0:16 offset1:20
	ds_read2_b32 v[20:21], v24 offset0:49 offset1:53
	v_lshl_add_u64 v[22:23], v[8:9], 0, v[22:23]
	global_store_dword v[22:23], v3, off
	ds_read2_b32 v[22:23], v24 offset0:24 offset1:28
	ds_read2_b32 v[24:25], v24 offset0:57 offset1:61
	v_or_b32_e32 v0, 8, v2
	v_lshlrev_b64 v[26:27], 11, v[0:1]
	s_waitcnt lgkmcnt(2)
	v_cvt_pk_bf16_f32 v3, v18, v20
	v_lshl_add_u64 v[26:27], v[8:9], 0, v[26:27]
	v_or_b32_e32 v0, 12, v2
	global_store_dword v[26:27], v3, off
	v_lshlrev_b64 v[26:27], 11, v[0:1]
	s_waitcnt lgkmcnt(0)
	v_cvt_pk_bf16_f32 v3, v22, v24
	v_lshl_add_u64 v[26:27], v[8:9], 0, v[26:27]
	v_or_b32_e32 v0, 16, v2
	global_store_dword v[26:27], v3, off
	v_cvt_pk_bf16_f32 v3, v7, v5
	v_lshlrev_b64 v[4:5], 11, v[0:1]
	v_lshl_add_u64 v[4:5], v[8:9], 0, v[4:5]
	v_or_b32_e32 v0, 20, v2
	global_store_dword v[4:5], v3, off
	v_lshlrev_b64 v[4:5], 11, v[0:1]
	v_cvt_pk_bf16_f32 v3, v11, v13
	v_lshl_add_u64 v[4:5], v[8:9], 0, v[4:5]
	v_or_b32_e32 v0, 24, v2
	global_store_dword v[4:5], v3, off
	v_lshlrev_b64 v[4:5], 11, v[0:1]
	v_cvt_pk_bf16_f32 v3, v19, v21
	v_lshl_add_u64 v[4:5], v[8:9], 0, v[4:5]
	v_or_b32_e32 v0, 28, v2
	global_store_dword v[4:5], v3, off
	v_lshlrev_b64 v[2:3], 11, v[0:1]
	v_cvt_pk_bf16_f32 v4, v23, v25
	v_lshl_add_u64 v[2:3], v[8:9], 0, v[2:3]
	global_store_dword v[2:3], v4, off
	s_barrier

.LBB0_863:
	s_lshl_b32 s72, s37, 3
	s_lshl_b32 s71, s36, 3
	v_or_b32_e32 v64, s72, v6
	v_or_b32_e32 v65, s71, v5
	v_mov_b32_e32 v67, v1
	v_add_u32_e32 v66, s2, v64
	v_mov_b32_e32 v69, v9
	v_add_u32_e32 v68, s3, v65
	v_mov_b32_e32 v71, v67
	v_mul_lo_u32 v70, v66, s67
	v_mov_b32_e32 v67, v69
	v_mul_lo_u32 v66, v68, s67
	v_lshl_add_u64 v[68:69], v[70:71], 2, v[2:3]
	v_mov_b32_e32 v72, v66
	v_mov_b32_e32 v73, v71
	v_lshl_add_u64 v[66:67], v[72:73], 2, v[2:3]
	v_mov_b32_e32 v73, v71
	global_load_dword v72, v[68:69], off nt
	global_load_dword v70, v[66:67], off nt
	v_mad_u64_u32 v[74:75], s[74:75], v64, s64, v[4:5]
	v_mad_u64_u32 v[66:67], s[74:75], v65, s64, v[4:5]
	s_add_i32 s74, s72, 16
	s_add_i32 s73, s71, 16
	v_or_b32_e32 v68, s74, v6
	v_or_b32_e32 v64, s73, v5
	v_mov_b32_e32 v76, v74
	v_mov_b32_e32 v77, v73
	s_add_i32 s73, s71, 32
	s_add_i32 s71, s71, 48
	s_add_i32 s37, s37, 8
	s_add_i32 s36, s36, 8
	s_add_i32 s70, s70, -8
	v_mov_b32_e32 v75, v73
	v_add_u32_e32 v74, s2, v68
	v_mov_b32_e32 v79, v77
	v_add_u32_e32 v78, s3, v64
	v_mov_b32_e32 v81, v75
	v_mul_lo_u32 v80, v74, s67
	v_mov_b32_e32 v75, v79
	v_mul_lo_u32 v74, v78, s67
	v_lshl_add_u64 v[78:79], v[80:81], 2, v[2:3]
	v_lshl_add_u64 v[82:83], v[74:75], 2, v[2:3]
	v_mov_b32_e32 v75, v81
	global_load_dword v74, v[78:79], off nt
	global_load_dword v65, v[82:83], off nt
	v_mad_u64_u32 v[80:81], s[74:75], v68, s64, v[4:5]
	v_mad_u64_u32 v[82:83], s[74:75], v64, s64, v[4:5]
	s_add_i32 s74, s72, 32
	s_nop 0
	v_or_b32_e32 v67, s74, v6
	v_or_b32_e32 v68, s73, v5
	v_mov_b32_e32 v78, v80
	v_mov_b32_e32 v79, v75
	s_add_i32 s72, s72, 48
	s_cmp_lg_u32 s70, 0
	v_mov_b32_e32 v81, v75
	v_add_u32_e32 v80, s2, v67
	v_mov_b32_e32 v85, v79
	v_add_u32_e32 v84, s3, v68
	v_mov_b32_e32 v87, v81
	v_mul_lo_u32 v86, v80, s67
	v_mov_b32_e32 v81, v85
	v_mul_lo_u32 v80, v84, s67
	v_lshl_add_u64 v[84:85], v[86:87], 2, v[2:3]
	v_lshl_add_u64 v[88:89], v[80:81], 2, v[2:3]
	v_mov_b32_e32 v81, v87
	global_load_dword v80, v[84:85], off nt
	global_load_dword v64, v[88:89], off nt
	v_mad_u64_u32 v[86:87], s[74:75], v67, s64, v[4:5]
	v_or_b32_e32 v69, s72, v6
	v_mad_u64_u32 v[88:89], s[74:75], v68, s64, v[4:5]
	v_or_b32_e32 v67, s71, v5
	v_mov_b32_e32 v84, v86
	v_mov_b32_e32 v85, v81
	v_mov_b32_e32 v87, v81
	v_add_u32_e32 v86, s2, v69
	v_mov_b32_e32 v91, v85
	v_add_u32_e32 v90, s3, v67
	v_mov_b32_e32 v93, v87
	v_mul_lo_u32 v92, v86, s67
	v_mov_b32_e32 v87, v91
	v_mul_lo_u32 v86, v90, s67
	v_lshl_add_u64 v[90:91], v[92:93], 2, v[2:3]
	v_lshl_add_u64 v[94:95], v[86:87], 2, v[2:3]
	v_mov_b32_e32 v87, v93
	global_load_dword v86, v[90:91], off nt
	global_load_dword v68, v[94:95], off nt
	v_mad_u64_u32 v[92:93], s[72:73], v69, s64, v[4:5]
	v_mad_u64_u32 v[94:95], s[72:73], v67, s64, v[4:5]
	s_lshl_b32 s72, s37, 3
	s_lshl_b32 s71, s36, 3
	v_or_b32_e32 v71, s72, v6
	v_or_b32_e32 v69, s71, v5
	v_mov_b32_e32 v91, v87
	v_add_u32_e32 v90, s2, v71
	v_mov_b32_e32 v97, v93
	v_add_u32_e32 v96, s3, v69
	v_mov_b32_e32 v99, v91
	v_mul_lo_u32 v98, v90, s67
	v_mov_b32_e32 v91, v97
	v_mul_lo_u32 v90, v96, s67
	v_lshl_add_u64 v[96:97], v[98:99], 2, v[2:3]
	v_mov_b32_e32 v100, v90
	v_mov_b32_e32 v101, v99
	v_lshl_add_u64 v[90:91], v[100:101], 2, v[2:3]
	v_mov_b32_e32 v101, v99
	global_load_dword v100, v[96:97], off nt
	global_load_dword v67, v[90:91], off nt
	v_mad_u64_u32 v[98:99], s[74:75], v71, s64, v[4:5]
	v_mad_u64_u32 v[90:91], s[74:75], v69, s64, v[4:5]
	s_add_i32 s74, s72, 16
	s_add_i32 s73, s71, 16
	v_or_b32_e32 v73, s74, v6
	v_or_b32_e32 v71, s73, v5
	v_mov_b32_e32 v96, v98
	v_mov_b32_e32 v97, v101
	s_add_i32 s73, s71, 32
	s_add_i32 s71, s71, 48
	s_add_i32 s37, s37, 8
	s_add_i32 s36, s36, 8
	s_add_i32 s70, s70, -8
	v_mov_b32_e32 v99, v101
	v_add_u32_e32 v98, s2, v73
	v_mov_b32_e32 v103, v97
	v_add_u32_e32 v102, s3, v71
	v_mov_b32_e32 v105, v99
	v_mul_lo_u32 v104, v98, s67
	v_mov_b32_e32 v99, v103
	v_mul_lo_u32 v98, v102, s67
	v_lshl_add_u64 v[102:103], v[104:105], 2, v[2:3]
	v_lshl_add_u64 v[106:107], v[98:99], 2, v[2:3]
	v_mov_b32_e32 v99, v105
	global_load_dword v98, v[102:103], off nt
	global_load_dword v69, v[106:107], off nt
	v_mad_u64_u32 v[104:105], s[74:75], v73, s64, v[4:5]
	v_mad_u64_u32 v[106:107], s[74:75], v71, s64, v[4:5]
	s_add_i32 s74, s72, 32
	s_nop 0
	v_or_b32_e32 v75, s74, v6
	v_or_b32_e32 v73, s73, v5
	v_mov_b32_e32 v102, v104
	v_mov_b32_e32 v103, v99
	s_add_i32 s72, s72, 48
	s_cmp_lg_u32 s70, 0
	v_mov_b32_e32 v105, v99
	v_add_u32_e32 v104, s2, v75
	v_mov_b32_e32 v109, v103
	v_add_u32_e32 v108, s3, v73
	v_mov_b32_e32 v111, v105
	v_mul_lo_u32 v110, v104, s67
	v_mov_b32_e32 v105, v109
	v_mul_lo_u32 v104, v108, s67
	v_lshl_add_u64 v[108:109], v[110:111], 2, v[2:3]
	v_lshl_add_u64 v[112:113], v[104:105], 2, v[2:3]
	v_mov_b32_e32 v105, v111
	global_load_dword v104, v[108:109], off nt
	global_load_dword v71, v[112:113], off nt
	v_mad_u64_u32 v[110:111], s[74:75], v75, s64, v[4:5]
	v_or_b32_e32 v77, s72, v6
	v_mad_u64_u32 v[112:113], s[74:75], v73, s64, v[4:5]
	v_or_b32_e32 v75, s71, v5
	v_mov_b32_e32 v108, v110
	v_mov_b32_e32 v109, v105
	v_mov_b32_e32 v111, v105
	v_add_u32_e32 v110, s2, v77
	v_mov_b32_e32 v115, v109
	v_add_u32_e32 v114, s3, v75
	v_mov_b32_e32 v117, v111
	v_mul_lo_u32 v116, v110, s67
	v_mov_b32_e32 v111, v115
	v_mul_lo_u32 v110, v114, s67
	v_lshl_add_u64 v[114:115], v[116:117], 2, v[2:3]
	v_lshl_add_u64 v[118:119], v[110:111], 2, v[2:3]
	v_mov_b32_e32 v111, v117
	global_load_dword v110, v[114:115], off nt
	global_load_dword v73, v[118:119], off nt
	v_mad_u64_u32 v[116:117], s[72:73], v77, s64, v[4:5]
	v_mad_u64_u32 v[118:119], s[72:73], v75, s64, v[4:5]
	s_waitcnt vmcnt(15)
	ds_write_b32 v76, v72
	s_waitcnt vmcnt(14)
	ds_write_b32 v66, v70
	s_waitcnt vmcnt(13)
	ds_write_b32 v78, v74
	s_waitcnt vmcnt(12)
	ds_write_b32 v82, v65
	s_waitcnt vmcnt(11)
	ds_write_b32 v84, v80
	s_waitcnt vmcnt(10)
	ds_write_b32 v88, v64
	s_waitcnt vmcnt(9)
	ds_write_b32 v92, v86
	s_waitcnt vmcnt(8)
	ds_write_b32 v94, v68
	s_waitcnt vmcnt(7)
	ds_write_b32 v96, v100
	s_waitcnt vmcnt(6)
	ds_write_b32 v90, v67
	s_waitcnt vmcnt(5)
	ds_write_b32 v102, v98
	s_waitcnt vmcnt(4)
	ds_write_b32 v106, v69
	s_waitcnt vmcnt(3)
	ds_write_b32 v108, v104
	s_waitcnt vmcnt(2)
	ds_write_b32 v112, v71
	s_waitcnt vmcnt(1)
	ds_write_b32 v116, v110
	s_waitcnt vmcnt(0)
	ds_write_b32 v118, v73
	v_mov_b32_e32 v0, v110
	v_mov_b32_e32 v1, v111
	v_mov_b32_e32 v8, v116
	v_mov_b32_e32 v9, v117
	v_mov_b32_e32 v10, v118
	v_mov_b32_e32 v11, v119
	v_mov_b32_e32 v12, v75
	v_mov_b32_e32 v13, v77
	v_mov_b32_e32 v18, v73
	v_lshlrev_b32_sdwa v0, v14, v7 dst_sel:DWORD dst_unused:UNUSED_PAD src0_sel:DWORD src1_sel:BYTE_0
	v_and_b32_e32 v0, 0x7e, v0
	v_lshrrev_b32_sdwa v3, v15, v7 dst_sel:DWORD dst_unused:UNUSED_PAD src0_sel:DWORD src1_sel:BYTE_0
	v_or_b32_e32 v2, s35, v3
	v_or_b32_e32 v8, s2, v0
	v_mul_u32_u24_e32 v0, 0x84, v0
	v_lshlrev_b32_e32 v3, 2, v3
	v_add3_u32 v26, s47, v0, v3
	s_waitcnt lgkmcnt(0)
	s_barrier
	ds_read2_b32 v[4:5], v26 offset0:33 offset1:37
	ds_read2_b32 v[6:7], v26 offset1:4
	v_lshlrev_b32_e32 v0, 1, v8
	v_ashrrev_i32_e32 v3, 31, v2
	v_lshl_add_u64 v[8:9], s[16:17], 0, v[0:1]
	ds_read2_b32 v[10:11], v26 offset0:8 offset1:12
	v_lshlrev_b64 v[12:13], 11, v[2:3]
	ds_read2_b32 v[18:19], v26 offset0:41 offset1:45
	s_waitcnt lgkmcnt(2)
	v_cvt_pk_bf16_f32 v0, v6, v4
	v_lshl_add_u64 v[12:13], v[8:9], 0, v[12:13]
	global_store_dword v[12:13], v0, off
	v_or_b32_e32 v12, 4, v2
	v_ashrrev_i32_e32 v13, 31, v12
	v_lshlrev_b64 v[12:13], 11, v[12:13]
	ds_read2_b32 v[20:21], v26 offset0:16 offset1:20
	ds_read2_b32 v[22:23], v26 offset0:49 offset1:53
	s_waitcnt lgkmcnt(2)
	v_cvt_pk_bf16_f32 v0, v10, v18
	v_lshl_add_u64 v[12:13], v[8:9], 0, v[12:13]
	global_store_dword v[12:13], v0, off
	v_or_b32_e32 v12, 8, v2
	v_ashrrev_i32_e32 v13, 31, v12
	v_lshlrev_b64 v[12:13], 11, v[12:13]
	ds_read2_b32 v[24:25], v26 offset0:24 offset1:28
	ds_read2_b32 v[26:27], v26 offset0:57 offset1:61
	s_waitcnt lgkmcnt(2)
	v_cvt_pk_bf16_f32 v0, v20, v22
	v_lshl_add_u64 v[12:13], v[8:9], 0, v[12:13]
	global_store_dword v[12:13], v0, off
	v_or_b32_e32 v12, 12, v2
	v_ashrrev_i32_e32 v13, 31, v12
	v_lshlrev_b64 v[12:13], 11, v[12:13]
	s_waitcnt lgkmcnt(0)
	v_cvt_pk_bf16_f32 v0, v24, v26
	v_lshl_add_u64 v[12:13], v[8:9], 0, v[12:13]
	global_store_dword v[12:13], v0, off
	v_or_b32_e32 v12, 16, v2
	v_ashrrev_i32_e32 v13, 31, v12
	v_cvt_pk_bf16_f32 v0, v7, v5
	v_lshlrev_b64 v[4:5], 11, v[12:13]
	v_lshl_add_u64 v[4:5], v[8:9], 0, v[4:5]
	global_store_dword v[4:5], v0, off
	v_or_b32_e32 v4, 20, v2
	v_ashrrev_i32_e32 v5, 31, v4
	v_lshlrev_b64 v[4:5], 11, v[4:5]
	v_cvt_pk_bf16_f32 v0, v11, v19
	v_lshl_add_u64 v[4:5], v[8:9], 0, v[4:5]
	global_store_dword v[4:5], v0, off
	v_or_b32_e32 v4, 24, v2
	v_ashrrev_i32_e32 v5, 31, v4
	v_or_b32_e32 v2, 28, v2
	v_lshlrev_b64 v[4:5], 11, v[4:5]
	v_ashrrev_i32_e32 v3, 31, v2
	v_cvt_pk_bf16_f32 v0, v21, v23
	v_lshl_add_u64 v[4:5], v[8:9], 0, v[4:5]
	v_lshlrev_b64 v[2:3], 11, v[2:3]
	global_store_dword v[4:5], v0, off
	v_cvt_pk_bf16_f32 v0, v25, v27
	v_lshl_add_u64 v[2:3], v[8:9], 0, v[2:3]
	s_mov_b64 s[2:3], 0
	global_store_dword v[2:3], v0, off
	s_barrier

.LBB0_867:
	s_lshl_b32 s37, s34, 3
	s_lshl_b32 s36, s20, 3
	v_or_b32_e32 v64, s37, v6
	v_or_b32_e32 v65, s36, v5
	v_mov_b32_e32 v67, v1
	v_add_u32_e32 v66, s2, v64
	v_mov_b32_e32 v69, v9
	v_add_u32_e32 v68, s3, v65
	v_mov_b32_e32 v71, v67
	v_mul_lo_u32 v70, v66, s67
	v_mov_b32_e32 v67, v69
	v_mul_lo_u32 v66, v68, s67
	v_lshl_add_u64 v[68:69], v[70:71], 2, v[2:3]
	v_mov_b32_e32 v72, v66
	v_mov_b32_e32 v73, v71
	v_lshl_add_u64 v[66:67], v[72:73], 2, v[2:3]
	v_mov_b32_e32 v73, v71
	global_load_dword v72, v[68:69], off nt
	global_load_dword v70, v[66:67], off nt
	v_mad_u64_u32 v[74:75], s[70:71], v64, s64, v[4:5]
	v_mad_u64_u32 v[66:67], s[70:71], v65, s64, v[4:5]
	s_add_i32 s71, s37, 16
	s_add_i32 s70, s36, 16
	v_or_b32_e32 v68, s71, v6
	v_or_b32_e32 v64, s70, v5
	v_mov_b32_e32 v76, v74
	v_mov_b32_e32 v77, v73
	s_add_i32 s34, s34, 8
	s_add_i32 s20, s20, 8
	s_add_i32 s35, s35, -8
	v_mov_b32_e32 v75, v73
	v_add_u32_e32 v74, s2, v68
	v_mov_b32_e32 v79, v77
	v_add_u32_e32 v78, s3, v64
	v_mov_b32_e32 v81, v75
	v_mul_lo_u32 v80, v74, s67
	v_mov_b32_e32 v75, v79
	v_mul_lo_u32 v74, v78, s67
	v_lshl_add_u64 v[78:79], v[80:81], 2, v[2:3]
	v_lshl_add_u64 v[82:83], v[74:75], 2, v[2:3]
	v_mov_b32_e32 v75, v81
	global_load_dword v74, v[78:79], off nt
	global_load_dword v65, v[82:83], off nt
	v_mad_u64_u32 v[80:81], s[70:71], v68, s64, v[4:5]
	v_mad_u64_u32 v[82:83], s[70:71], v64, s64, v[4:5]
	s_add_i32 s71, s37, 32
	s_add_i32 s70, s36, 32
	v_or_b32_e32 v67, s71, v6
	v_or_b32_e32 v68, s70, v5
	v_mov_b32_e32 v78, v80
	v_mov_b32_e32 v79, v75
	s_add_i32 s37, s37, 48
	s_add_i32 s36, s36, 48
	s_cmp_lg_u32 s35, 0
	v_mov_b32_e32 v81, v75
	v_add_u32_e32 v80, s2, v67
	v_mov_b32_e32 v85, v79
	v_add_u32_e32 v84, s3, v68
	v_mov_b32_e32 v87, v81
	v_mul_lo_u32 v86, v80, s67
	v_mov_b32_e32 v81, v85
	v_mul_lo_u32 v80, v84, s67
	v_lshl_add_u64 v[84:85], v[86:87], 2, v[2:3]
	v_lshl_add_u64 v[88:89], v[80:81], 2, v[2:3]
	v_mov_b32_e32 v81, v87
	global_load_dword v80, v[84:85], off nt
	global_load_dword v64, v[88:89], off nt
	v_mad_u64_u32 v[86:87], s[70:71], v67, s64, v[4:5]
	v_or_b32_e32 v69, s37, v6
	v_mad_u64_u32 v[88:89], s[70:71], v68, s64, v[4:5]
	v_or_b32_e32 v67, s36, v5
	v_mov_b32_e32 v84, v86
	v_mov_b32_e32 v85, v81
	v_mov_b32_e32 v87, v81
	v_add_u32_e32 v86, s2, v69
	v_mov_b32_e32 v91, v85
	v_add_u32_e32 v90, s3, v67
	v_mov_b32_e32 v93, v87
	v_mul_lo_u32 v92, v86, s67
	v_mov_b32_e32 v87, v91
	v_mul_lo_u32 v86, v90, s67
	v_lshl_add_u64 v[90:91], v[92:93], 2, v[2:3]
	v_lshl_add_u64 v[94:95], v[86:87], 2, v[2:3]
	v_mov_b32_e32 v87, v93
	global_load_dword v86, v[90:91], off nt
	global_load_dword v68, v[94:95], off nt
	v_mad_u64_u32 v[92:93], s[36:37], v69, s64, v[4:5]
	v_mad_u64_u32 v[94:95], s[36:37], v67, s64, v[4:5]
	s_lshl_b32 s37, s34, 3
	s_lshl_b32 s36, s20, 3
	v_or_b32_e32 v71, s37, v6
	v_or_b32_e32 v69, s36, v5
	v_mov_b32_e32 v91, v87
	v_add_u32_e32 v90, s2, v71
	v_mov_b32_e32 v97, v93
	v_add_u32_e32 v96, s3, v69
	v_mov_b32_e32 v99, v91
	v_mul_lo_u32 v98, v90, s67
	v_mov_b32_e32 v91, v97
	v_mul_lo_u32 v90, v96, s67
	v_lshl_add_u64 v[96:97], v[98:99], 2, v[2:3]
	v_mov_b32_e32 v100, v90
	v_mov_b32_e32 v101, v99
	v_lshl_add_u64 v[90:91], v[100:101], 2, v[2:3]
	v_mov_b32_e32 v101, v99
	global_load_dword v100, v[96:97], off nt
	global_load_dword v67, v[90:91], off nt
	v_mad_u64_u32 v[98:99], s[70:71], v71, s64, v[4:5]
	v_mad_u64_u32 v[90:91], s[70:71], v69, s64, v[4:5]
	s_add_i32 s71, s37, 16
	s_add_i32 s70, s36, 16
	v_or_b32_e32 v73, s71, v6
	v_or_b32_e32 v71, s70, v5
	v_mov_b32_e32 v96, v98
	v_mov_b32_e32 v97, v101
	s_add_i32 s34, s34, 8
	s_add_i32 s20, s20, 8
	s_add_i32 s35, s35, -8
	v_mov_b32_e32 v99, v101
	v_add_u32_e32 v98, s2, v73
	v_mov_b32_e32 v103, v97
	v_add_u32_e32 v102, s3, v71
	v_mov_b32_e32 v105, v99
	v_mul_lo_u32 v104, v98, s67
	v_mov_b32_e32 v99, v103
	v_mul_lo_u32 v98, v102, s67
	v_lshl_add_u64 v[102:103], v[104:105], 2, v[2:3]
	v_lshl_add_u64 v[106:107], v[98:99], 2, v[2:3]
	v_mov_b32_e32 v99, v105
	global_load_dword v98, v[102:103], off nt
	global_load_dword v69, v[106:107], off nt
	v_mad_u64_u32 v[104:105], s[70:71], v73, s64, v[4:5]
	v_mad_u64_u32 v[106:107], s[70:71], v71, s64, v[4:5]
	s_add_i32 s71, s37, 32
	s_add_i32 s70, s36, 32
	v_or_b32_e32 v75, s71, v6
	v_or_b32_e32 v73, s70, v5
	v_mov_b32_e32 v102, v104
	v_mov_b32_e32 v103, v99
	s_add_i32 s37, s37, 48
	s_add_i32 s36, s36, 48
	s_cmp_lg_u32 s35, 0
	v_mov_b32_e32 v105, v99
	v_add_u32_e32 v104, s2, v75
	v_mov_b32_e32 v109, v103
	v_add_u32_e32 v108, s3, v73
	v_mov_b32_e32 v111, v105
	v_mul_lo_u32 v110, v104, s67
	v_mov_b32_e32 v105, v109
	v_mul_lo_u32 v104, v108, s67
	v_lshl_add_u64 v[108:109], v[110:111], 2, v[2:3]
	v_lshl_add_u64 v[112:113], v[104:105], 2, v[2:3]
	v_mov_b32_e32 v105, v111
	global_load_dword v104, v[108:109], off nt
	global_load_dword v71, v[112:113], off nt
	v_mad_u64_u32 v[110:111], s[70:71], v75, s64, v[4:5]
	v_or_b32_e32 v77, s37, v6
	v_mad_u64_u32 v[112:113], s[70:71], v73, s64, v[4:5]
	v_or_b32_e32 v75, s36, v5
	v_mov_b32_e32 v108, v110
	v_mov_b32_e32 v109, v105
	v_mov_b32_e32 v111, v105
	v_add_u32_e32 v110, s2, v77
	v_mov_b32_e32 v115, v109
	v_add_u32_e32 v114, s3, v75
	v_mov_b32_e32 v117, v111
	v_mul_lo_u32 v116, v110, s67
	v_mov_b32_e32 v111, v115
	v_mul_lo_u32 v110, v114, s67
	v_lshl_add_u64 v[114:115], v[116:117], 2, v[2:3]
	v_lshl_add_u64 v[118:119], v[110:111], 2, v[2:3]
	v_mov_b32_e32 v111, v117
	global_load_dword v110, v[114:115], off nt
	global_load_dword v73, v[118:119], off nt
	v_mad_u64_u32 v[116:117], s[36:37], v77, s64, v[4:5]
	v_mad_u64_u32 v[118:119], s[36:37], v75, s64, v[4:5]
	s_waitcnt vmcnt(15)
	ds_write_b32 v76, v72
	s_waitcnt vmcnt(14)
	ds_write_b32 v66, v70
	s_waitcnt vmcnt(13)
	ds_write_b32 v78, v74
	s_waitcnt vmcnt(12)
	ds_write_b32 v82, v65
	s_waitcnt vmcnt(11)
	ds_write_b32 v84, v80
	s_waitcnt vmcnt(10)
	ds_write_b32 v88, v64
	s_waitcnt vmcnt(9)
	ds_write_b32 v92, v86
	s_waitcnt vmcnt(8)
	ds_write_b32 v94, v68
	s_waitcnt vmcnt(7)
	ds_write_b32 v96, v100
	s_waitcnt vmcnt(6)
	ds_write_b32 v90, v67
	s_waitcnt vmcnt(5)
	ds_write_b32 v102, v98
	s_waitcnt vmcnt(4)
	ds_write_b32 v106, v69
	s_waitcnt vmcnt(3)
	ds_write_b32 v108, v104
	s_waitcnt vmcnt(2)
	ds_write_b32 v112, v71
	s_waitcnt vmcnt(1)
	ds_write_b32 v116, v110
	s_waitcnt vmcnt(0)
	ds_write_b32 v118, v73
	v_mov_b32_e32 v0, v110
	v_mov_b32_e32 v1, v111
	v_mov_b32_e32 v8, v116
	v_mov_b32_e32 v9, v117
	v_mov_b32_e32 v10, v118
	v_mov_b32_e32 v11, v119
	v_mov_b32_e32 v12, v75
	v_mov_b32_e32 v13, v77
	v_mov_b32_e32 v18, v73
	v_lshlrev_b32_sdwa v0, v14, v7 dst_sel:DWORD dst_unused:UNUSED_PAD src0_sel:DWORD src1_sel:BYTE_0
	v_and_b32_e32 v0, 0x7e, v0
	v_lshrrev_b32_sdwa v10, v15, v7 dst_sel:DWORD dst_unused:UNUSED_PAD src0_sel:DWORD src1_sel:BYTE_0
	v_mul_u32_u24_e32 v2, 0x84, v0
	v_lshlrev_b32_e32 v3, 2, v10
	v_add3_u32 v12, s47, v2, v3
	s_waitcnt lgkmcnt(0)
	s_barrier
	ds_read2_b32 v[2:3], v12 offset0:33 offset1:37
	ds_read2_b32 v[4:5], v12 offset1:4
	v_or_b32_e32 v0, s2, v0
	v_lshlrev_b32_e32 v0, 1, v0
	v_lshl_add_u64 v[6:7], s[18:19], 0, v[0:1]
	v_lshlrev_b32_e32 v0, 11, v10
	s_waitcnt lgkmcnt(0)
	v_cvt_pk_bf16_f32 v2, v4, v2
	v_lshl_add_u64 v[10:11], v[6:7], 0, v[0:1]
	ds_read2_b32 v[8:9], v12 offset0:8 offset1:12
	global_store_dword v[10:11], v2, off
	v_cvt_pk_bf16_f32 v10, v5, v3
	ds_read2_b32 v[2:3], v12 offset0:41 offset1:45
	v_or_b32_e32 v4, 0x2000, v0
	v_mov_b32_e32 v5, v1
	v_lshl_add_u64 v[4:5], v[6:7], 0, v[4:5]
	global_store_dword v[4:5], v10, off
	v_or_b32_e32 v4, 0x4000, v0
	v_mov_b32_e32 v5, v1
	s_waitcnt lgkmcnt(0)
	v_cvt_pk_bf16_f32 v2, v8, v2
	v_lshl_add_u64 v[4:5], v[6:7], 0, v[4:5]
	global_store_dword v[4:5], v2, off
	v_cvt_pk_bf16_f32 v10, v9, v3
	ds_read2_b32 v[2:3], v12 offset0:16 offset1:20
	ds_read2_b32 v[4:5], v12 offset0:49 offset1:53
	v_or_b32_e32 v8, 0x6000, v0
	v_mov_b32_e32 v9, v1
	v_lshl_add_u64 v[8:9], v[6:7], 0, v[8:9]
	global_store_dword v[8:9], v10, off
	v_or_b32_e32 v8, 0x8000, v0
	v_mov_b32_e32 v9, v1
	s_waitcnt lgkmcnt(0)
	v_cvt_pk_bf16_f32 v2, v2, v4
	v_lshl_add_u64 v[8:9], v[6:7], 0, v[8:9]
	global_store_dword v[8:9], v2, off
	v_cvt_pk_bf16_f32 v10, v3, v5
	ds_read2_b32 v[2:3], v12 offset0:57 offset1:61
	ds_read2_b32 v[4:5], v12 offset0:24 offset1:28
	v_or_b32_e32 v8, 0xa000, v0
	v_mov_b32_e32 v9, v1
	v_lshl_add_u64 v[8:9], v[6:7], 0, v[8:9]
	global_store_dword v[8:9], v10, off
	v_or_b32_e32 v8, 0xc000, v0
	v_mov_b32_e32 v9, v1
	s_waitcnt lgkmcnt(0)
	v_cvt_pk_bf16_f32 v2, v4, v2
	v_lshl_add_u64 v[8:9], v[6:7], 0, v[8:9]
	v_or_b32_e32 v0, 0xe000, v0
	global_store_dword v[8:9], v2, off
	v_cvt_pk_bf16_f32 v4, v5, v3
	v_lshl_add_u64 v[2:3], v[6:7], 0, v[0:1]
	global_store_dword v[2:3], v4, off
	s_barrier
	s_branch .LBB0_798
